# LDS-DMA stage loads switched to SGPR-base plus 32-bit VGPR offset form (no 64-bit VALU address adds in the K-loop)
# speedup vs baseline: 1.0155x; 1.0022x over previous
; #define PG8_STAGE(bufoff, gbase, voff) do { _Pragma("unroll") for (int _i = 0; _i < 2; ++_i) \
;         __builtin_amdgcn_global_load_lds((const unsigned*)((const char*)(gbase) + (voff)[_i]), (LAS unsigned*)(lds + (bufoff) + ldsw + _i * 8192), 16, 0, 0); } while (0)
; #define PG8_LDA(dst, b, h) do { _Pragma("unroll") for (int m = 0; m < 4; ++m) _Pragma("unroll") for (int k = 0; k < 2; ++k) dst[m][k] = *(const LAS bf16x8*)(lds + PG8_SA(b, h) + aoff + m * 2048 + k * 1024); } while (0)
; #define PG8_WAIT_V(n) asm volatile("s_waitcnt vmcnt(" #n ")" ::: "memory")
; template <class Epi, class Sched>
; __device__ __forceinline__ void gemm_phase(LAS unsigned char* lds, const Gemm g, const Sched& S, const Epi& E) {
;     ...
;         for (int t = 0; t < ntu; t += 2) {
;             const bool last = (t == ntu - 2);
;             const char* a1 = cA + (size_t)(t + 1) * kstep;
;             const char* a2 = last ? nA : cA + (size_t)(t + 2) * kstep; const char* b2 = last ? nB : cB + (size_t)(t + 2) * kstep;
;             const char* a3 = a2 + kstep; const char* b3 = b2 + kstep;
;             if (last && has_next) S.a_ready(nxt);
;             PG8_LDB(B0, 0, 0); PG8_SCHED; PG8_LDA(At, 0, 0); PG8_STAGE(PG8_SA(1, 1), a1 + hstepA, voffA);
;             PG8_WAIT_L(8); PG8_BAR; PG8_WAIT_L(0); PG8_MMA(0, 0, At, B0); PG8_BAR; PG8_SCHED;
;             PG8_LDB(B1, 0, 1); PG8_STAGE(PG8_SB(0, 0), b2, voffB);
;             PG8_BAR; PG8_WAIT_L(0); PG8_MMA(0, 1, At, B1); PG8_BAR;
;             PG8_LDA(At, 0, 1); PG8_STAGE(PG8_SA(0, 0), a2, voffA);
;             PG8_BAR; PG8_WAIT_L(0); PG8_MMA(1, 0, At, B0); PG8_BAR; PG8_SCHED;
;             PG8_STAGE(PG8_SB(0, 1), b2 + hstepB, voffB);
;             PG8_WAIT_V(6); PG8_BAR; PG8_MMA(1, 1, At, B1); PG8_BAR;
;             PG8_LDB(B0, 1, 0); PG8_SCHED; PG8_LDA(At, 1, 0); PG8_STAGE(PG8_SA(0, 1), a2 + hstepA, voffA);
;             PG8_WAIT_L(8); PG8_BAR; PG8_WAIT_L(0); PG8_MMA(0, 0, At, B0); PG8_BAR; PG8_SCHED;
;             PG8_LDB(B1, 1, 1); PG8_STAGE(PG8_SB(1, 0), b3, voffB);
;             PG8_BAR; PG8_WAIT_L(0); PG8_MMA(0, 1, At, B1); PG8_BAR;
;             PG8_LDA(At, 1, 1); PG8_STAGE(PG8_SA(1, 0), a3, voffA);
;             PG8_BAR; PG8_WAIT_L(0); PG8_MMA(1, 0, At, B0); PG8_BAR; PG8_SCHED;
;             PG8_STAGE(PG8_SB(1, 1), b3 + hstepB, voffB);
;             PG8_WAIT_V(6); PG8_BAR; PG8_MMA(1, 1, At, B1); PG8_BAR;
.LBB0_381:
	s_add_u32 s37, s12, 0xfff80080
	s_addc_u32 s38, s13, -1
	s_add_i32 s46, 0, 0x10000
	v_add_u32_e32 v162, s46, v170
	ds_read_b128 v[150:153], v162
	ds_read_b128 v[154:157], v162 offset:1024
	ds_read_b128 v[158:161], v162 offset:2048
	ds_read_b128 v[162:165], v162 offset:3072
	s_cmp_eq_u32 s36, 28
	s_cselect_b32 s55, s1, s38
	s_cselect_b32 s54, s25, s37
	s_cselect_b32 s53, s23, s30
	s_cselect_b32 s52, s28, s29
	ds_read_b128 v[186:189], v176
	ds_read_b128 v[190:193], v176 offset:1024
	ds_read_b128 v[194:197], v176 offset:2048
	ds_read_b128 v[198:201], v176 offset:3072
	ds_read_b128 v[202:205], v176 offset:4096
	ds_read_b128 v[206:209], v176 offset:5120
	ds_read_b128 v[210:213], v176 offset:6144
	ds_read_b128 v[214:217], v176 offset:7168
	s_add_u32 s98, s12, 0xfff80000
	s_addc_u32 s99, s13, -1
	s_mov_b32 m0, s70
	s_nop 0
	global_load_lds_dwordx4 v146, s[98:99]
	s_mov_b32 m0, s71
	s_nop 0
	global_load_lds_dwordx4 v148, s[98:99]
	s_add_i32 m0, s63, 0xc000
	s_nop 0
	global_load_lds_dwordx4 v146, s[12:13]
	s_add_i32 m0, s63, 0xe000
	s_nop 0
	global_load_lds_dwordx4 v148, s[12:13]
	s_add_i32 s37, 0, 0x14000
	v_add_u32_e32 v166, s37, v170
	ds_read_b128 v[218:221], v166
	ds_read_b128 v[222:225], v166 offset:1024
	ds_read_b128 v[226:229], v166 offset:2048
	ds_read_b128 v[244:247], v166 offset:3072
	s_waitcnt lgkmcnt(0)
	s_barrier
	v_mfma_f32_16x16x32_bf16 v[126:129], v[150:153], v[186:189], v[126:129]
	v_mfma_f32_16x16x32_bf16 v[126:129], v[154:157], v[190:193], v[126:129]
	v_mfma_f32_16x16x32_bf16 v[110:113], v[150:153], v[194:197], v[110:113]
	v_mfma_f32_16x16x32_bf16 v[110:113], v[154:157], v[198:201], v[110:113]
	v_mfma_f32_16x16x32_bf16 v[94:97], v[150:153], v[202:205], v[94:97]
	v_mfma_f32_16x16x32_bf16 v[94:97], v[154:157], v[206:209], v[94:97]
	v_mfma_f32_16x16x32_bf16 v[78:81], v[150:153], v[210:213], v[78:81]
	v_mfma_f32_16x16x32_bf16 v[78:81], v[154:157], v[214:217], v[78:81]
	v_mfma_f32_16x16x32_bf16 v[122:125], v[158:161], v[186:189], v[122:125]
	v_mfma_f32_16x16x32_bf16 v[122:125], v[162:165], v[190:193], v[122:125]
	v_mfma_f32_16x16x32_bf16 v[106:109], v[158:161], v[194:197], v[106:109]
	v_mfma_f32_16x16x32_bf16 v[106:109], v[162:165], v[198:201], v[106:109]
	v_mfma_f32_16x16x32_bf16 v[90:93], v[158:161], v[202:205], v[90:93]
	v_mfma_f32_16x16x32_bf16 v[90:93], v[162:165], v[206:209], v[90:93]
	v_mfma_f32_16x16x32_bf16 v[74:77], v[158:161], v[210:213], v[74:77]
	v_mfma_f32_16x16x32_bf16 v[74:77], v[162:165], v[214:217], v[74:77]
	v_mfma_f32_16x16x32_bf16 v[118:121], v[218:221], v[186:189], v[118:121]
	v_mfma_f32_16x16x32_bf16 v[118:121], v[222:225], v[190:193], v[118:121]
	v_mfma_f32_16x16x32_bf16 v[102:105], v[218:221], v[194:197], v[102:105]
	v_mfma_f32_16x16x32_bf16 v[102:105], v[222:225], v[198:201], v[102:105]
	v_mfma_f32_16x16x32_bf16 v[86:89], v[218:221], v[202:205], v[86:89]
	v_mfma_f32_16x16x32_bf16 v[86:89], v[222:225], v[206:209], v[86:89]
	v_mfma_f32_16x16x32_bf16 v[70:73], v[218:221], v[210:213], v[70:73]
	v_mfma_f32_16x16x32_bf16 v[70:73], v[222:225], v[214:217], v[70:73]
	v_mfma_f32_16x16x32_bf16 v[114:117], v[226:229], v[186:189], v[114:117]
	v_mfma_f32_16x16x32_bf16 v[114:117], v[244:247], v[190:193], v[114:117]
	v_mfma_f32_16x16x32_bf16 v[98:101], v[226:229], v[194:197], v[98:101]
	v_mfma_f32_16x16x32_bf16 v[98:101], v[244:247], v[198:201], v[98:101]
	v_mfma_f32_16x16x32_bf16 v[82:85], v[226:229], v[202:205], v[82:85]
	v_mfma_f32_16x16x32_bf16 v[82:85], v[244:247], v[206:209], v[82:85]
	v_mfma_f32_16x16x32_bf16 v[66:69], v[226:229], v[210:213], v[66:69]
	v_mfma_f32_16x16x32_bf16 v[66:69], v[244:247], v[214:217], v[66:69]
	s_barrier
	ds_read_b128 v[186:189], v176 offset:16384
	ds_read_b128 v[190:193], v176 offset:17408
	ds_read_b128 v[194:197], v176 offset:18432
	ds_read_b128 v[198:201], v176 offset:19456
	ds_read_b128 v[202:205], v176 offset:20480
	ds_read_b128 v[206:209], v176 offset:21504
	ds_read_b128 v[210:213], v176 offset:22528
	ds_read_b128 v[214:217], v176 offset:23552
	s_add_i32 s38, s46, s62
	s_mov_b32 m0, s38
	s_nop 0
	global_load_lds_dwordx4 v134, s[52:53]
	s_add_i32 m0, s38, 0x2000
	s_nop 0
	global_load_lds_dwordx4 v130, s[52:53]
	s_add_u32 s76, s52, 0x80000
	s_addc_u32 s77, s53, 0
	s_add_i32 s37, s37, s62
	s_mov_b32 m0, s37
	s_nop 0
	global_load_lds_dwordx4 v134, s[76:77]
	s_add_i32 m0, s37, 0x2000
	s_nop 0
	global_load_lds_dwordx4 v130, s[76:77]
	s_waitcnt vmcnt(4)
	s_waitcnt lgkmcnt(0)
	s_barrier
	v_mfma_f32_16x16x32_bf16 v[62:65], v[150:153], v[186:189], v[62:65]
	v_mfma_f32_16x16x32_bf16 v[62:65], v[154:157], v[190:193], v[62:65]
	v_mfma_f32_16x16x32_bf16 v[46:49], v[150:153], v[194:197], v[46:49]
	v_mfma_f32_16x16x32_bf16 v[46:49], v[154:157], v[198:201], v[46:49]
	v_mfma_f32_16x16x32_bf16 v[30:33], v[150:153], v[202:205], v[30:33]
	v_mfma_f32_16x16x32_bf16 v[30:33], v[154:157], v[206:209], v[30:33]
	v_mfma_f32_16x16x32_bf16 v[14:17], v[150:153], v[210:213], v[14:17]
	v_mfma_f32_16x16x32_bf16 v[14:17], v[154:157], v[214:217], v[14:17]
	v_mfma_f32_16x16x32_bf16 v[58:61], v[158:161], v[186:189], v[58:61]
	v_mfma_f32_16x16x32_bf16 v[58:61], v[162:165], v[190:193], v[58:61]
	v_mfma_f32_16x16x32_bf16 v[42:45], v[158:161], v[194:197], v[42:45]
	v_mfma_f32_16x16x32_bf16 v[42:45], v[162:165], v[198:201], v[42:45]
	v_mfma_f32_16x16x32_bf16 v[26:29], v[158:161], v[202:205], v[26:29]
	v_mfma_f32_16x16x32_bf16 v[26:29], v[162:165], v[206:209], v[26:29]
	v_mfma_f32_16x16x32_bf16 v[10:13], v[158:161], v[210:213], v[10:13]
	v_mfma_f32_16x16x32_bf16 v[10:13], v[162:165], v[214:217], v[10:13]
	v_mfma_f32_16x16x32_bf16 v[54:57], v[218:221], v[186:189], v[54:57]
	v_mfma_f32_16x16x32_bf16 v[54:57], v[222:225], v[190:193], v[54:57]
	v_mfma_f32_16x16x32_bf16 v[38:41], v[218:221], v[194:197], v[38:41]
	v_mfma_f32_16x16x32_bf16 v[38:41], v[222:225], v[198:201], v[38:41]
	v_mfma_f32_16x16x32_bf16 v[22:25], v[218:221], v[202:205], v[22:25]
	v_mfma_f32_16x16x32_bf16 v[22:25], v[222:225], v[206:209], v[22:25]
	v_mfma_f32_16x16x32_bf16 v[6:9], v[218:221], v[210:213], v[6:9]
	v_mfma_f32_16x16x32_bf16 v[6:9], v[222:225], v[214:217], v[6:9]
	v_mfma_f32_16x16x32_bf16 v[50:53], v[226:229], v[186:189], v[50:53]
	v_mfma_f32_16x16x32_bf16 v[50:53], v[244:247], v[190:193], v[50:53]
	v_mfma_f32_16x16x32_bf16 v[34:37], v[226:229], v[194:197], v[34:37]
	v_mfma_f32_16x16x32_bf16 v[34:37], v[244:247], v[198:201], v[34:37]
	v_mfma_f32_16x16x32_bf16 v[18:21], v[226:229], v[202:205], v[18:21]
	v_mfma_f32_16x16x32_bf16 v[18:21], v[244:247], v[206:209], v[18:21]
	v_mfma_f32_16x16x32_bf16 v[2:5], v[226:229], v[210:213], v[2:5]
	v_mfma_f32_16x16x32_bf16 v[2:5], v[244:247], v[214:217], v[2:5]
	s_add_i32 s37, 0, 0x18000
	v_add_u32_e32 v162, s37, v170
	s_barrier
; #define PG8_STAGE(bufoff, gbase, voff) do { _Pragma("unroll") for (int _i = 0; _i < 2; ++_i) \
;         __builtin_amdgcn_global_load_lds((const unsigned*)((const char*)(gbase) + (voff)[_i]), (LAS unsigned*)(lds + (bufoff) + ldsw + _i * 8192), 16, 0, 0); } while (0)
; #define PG8_LDA(dst, b, h) do { _Pragma("unroll") for (int m = 0; m < 4; ++m) _Pragma("unroll") for (int k = 0; k < 2; ++k) dst[m][k] = *(const LAS bf16x8*)(lds + PG8_SA(b, h) + aoff + m * 2048 + k * 1024); } while (0)
; #define PG8_LDB(dst, b, h) do { _Pragma("unroll") for (int n = 0; n < 2; ++n) _Pragma("unroll") for (int k = 0; k < 2; ++k) dst[n][k] = *(const LAS bf16x8*)(lds + PG8_SB(b, h) + boff + n * 2048 + k * 1024); } while (0)
; #define PG8_WAIT_V(n) asm volatile("s_waitcnt vmcnt(" #n ")" ::: "memory")
; #define PG8_WAIT_L(n) asm volatile("s_waitcnt lgkmcnt(" #n ")" ::: "memory")
; #define PG8_BAR __builtin_amdgcn_s_barrier()
; #define PG8_SCHED __builtin_amdgcn_sched_barrier(0)
; template <class Epi, class Sched>
; __device__ __forceinline__ void gemm_phase(LAS unsigned char* lds, const Gemm g, const Sched& S, const Epi& E) {
;     ...
;             PG8_LDB(B0, 0, 0); PG8_SCHED; PG8_LDA(At, 0, 0); PG8_STAGE(PG8_SA(1, 1), a1 + hstepA, voffA);
;             PG8_WAIT_L(8); PG8_BAR; PG8_WAIT_L(0); PG8_MMA(0, 0, At, B0); PG8_BAR; PG8_SCHED;
;             PG8_LDB(B1, 0, 1); PG8_STAGE(PG8_SB(0, 0), b2, voffB);
;             PG8_BAR; PG8_WAIT_L(0); PG8_MMA(0, 1, At, B1); PG8_BAR;
;             PG8_LDA(At, 0, 1); PG8_STAGE(PG8_SA(0, 0), a2, voffA);
;             PG8_BAR; PG8_WAIT_L(0); PG8_MMA(1, 0, At, B0); PG8_BAR; PG8_SCHED;
;             PG8_STAGE(PG8_SB(0, 1), b2 + hstepB, voffB);
;             PG8_WAIT_V(6); PG8_BAR; PG8_MMA(1, 1, At, B1); PG8_BAR;
;             PG8_LDB(B0, 1, 0); PG8_SCHED; PG8_LDA(At, 1, 0); PG8_STAGE(PG8_SA(0, 1), a2 + hstepA, voffA);
;             PG8_WAIT_L(8); PG8_BAR; PG8_WAIT_L(0); PG8_MMA(0, 0, At, B0); PG8_BAR; PG8_SCHED;
;             PG8_LDB(B1, 1, 1); PG8_STAGE(PG8_SB(1, 0), b3, voffB);
;             PG8_BAR; PG8_WAIT_L(0); PG8_MMA(0, 1, At, B1); PG8_BAR;
;             PG8_LDA(At, 1, 1); PG8_STAGE(PG8_SA(1, 0), a3, voffA);
;             PG8_BAR; PG8_WAIT_L(0); PG8_MMA(1, 0, At, B0); PG8_BAR; PG8_SCHED;
;             PG8_STAGE(PG8_SB(1, 1), b3 + hstepB, voffB);
;             PG8_WAIT_V(6); PG8_BAR; PG8_MMA(1, 1, At, B1); PG8_BAR;
	ds_read_b128 v[150:153], v162
	ds_read_b128 v[154:157], v162 offset:1024
	ds_read_b128 v[158:161], v162 offset:2048
	ds_read_b128 v[162:165], v162 offset:3072
	ds_read_b128 v[186:189], v176 offset:32768
	ds_read_b128 v[190:193], v176 offset:33792
	ds_read_b128 v[194:197], v176 offset:34816
	ds_read_b128 v[198:201], v176 offset:35840
	ds_read_b128 v[202:205], v176 offset:36864
	ds_read_b128 v[206:209], v176 offset:37888
	ds_read_b128 v[210:213], v176 offset:38912
	ds_read_b128 v[214:217], v176 offset:39936
	s_mov_b32 m0, s63
	s_nop 0
	global_load_lds_dwordx4 v136, s[54:55]
	s_mov_b32 m0, s66
	s_nop 0
	global_load_lds_dwordx4 v132, s[54:55]
	s_add_u32 s54, s54, 0x80000
	s_addc_u32 s55, s55, 0
	s_mov_b32 m0, s67
	s_nop 0
	global_load_lds_dwordx4 v136, s[54:55]
	s_mov_b32 m0, s68
	s_nop 0
	global_load_lds_dwordx4 v132, s[54:55]
	s_add_i32 s38, 0, 0x1c000
	v_add_u32_e32 v177, s38, v170
	ds_read_b128 v[218:221], v177
	ds_read_b128 v[222:225], v177 offset:1024
	ds_read_b128 v[226:229], v177 offset:2048
	ds_read_b128 v[244:247], v177 offset:3072
	s_waitcnt lgkmcnt(0)
	s_barrier
	v_mfma_f32_16x16x32_bf16 v[126:129], v[150:153], v[186:189], v[126:129]
	v_mfma_f32_16x16x32_bf16 v[126:129], v[154:157], v[190:193], v[126:129]
	v_mfma_f32_16x16x32_bf16 v[110:113], v[150:153], v[194:197], v[110:113]
	v_mfma_f32_16x16x32_bf16 v[110:113], v[154:157], v[198:201], v[110:113]
	v_mfma_f32_16x16x32_bf16 v[94:97], v[150:153], v[202:205], v[94:97]
	v_mfma_f32_16x16x32_bf16 v[94:97], v[154:157], v[206:209], v[94:97]
	v_mfma_f32_16x16x32_bf16 v[78:81], v[150:153], v[210:213], v[78:81]
	v_mfma_f32_16x16x32_bf16 v[78:81], v[154:157], v[214:217], v[78:81]
	v_mfma_f32_16x16x32_bf16 v[122:125], v[158:161], v[186:189], v[122:125]
	v_mfma_f32_16x16x32_bf16 v[122:125], v[162:165], v[190:193], v[122:125]
	v_mfma_f32_16x16x32_bf16 v[106:109], v[158:161], v[194:197], v[106:109]
	v_mfma_f32_16x16x32_bf16 v[106:109], v[162:165], v[198:201], v[106:109]
	v_mfma_f32_16x16x32_bf16 v[90:93], v[158:161], v[202:205], v[90:93]
	v_mfma_f32_16x16x32_bf16 v[90:93], v[162:165], v[206:209], v[90:93]
	v_mfma_f32_16x16x32_bf16 v[74:77], v[158:161], v[210:213], v[74:77]
	v_mfma_f32_16x16x32_bf16 v[74:77], v[162:165], v[214:217], v[74:77]
	v_mfma_f32_16x16x32_bf16 v[118:121], v[218:221], v[186:189], v[118:121]
	v_mfma_f32_16x16x32_bf16 v[118:121], v[222:225], v[190:193], v[118:121]
	v_mfma_f32_16x16x32_bf16 v[102:105], v[218:221], v[194:197], v[102:105]
	v_mfma_f32_16x16x32_bf16 v[102:105], v[222:225], v[198:201], v[102:105]
	v_mfma_f32_16x16x32_bf16 v[86:89], v[218:221], v[202:205], v[86:89]
	v_mfma_f32_16x16x32_bf16 v[86:89], v[222:225], v[206:209], v[86:89]
	v_mfma_f32_16x16x32_bf16 v[70:73], v[218:221], v[210:213], v[70:73]
	v_mfma_f32_16x16x32_bf16 v[70:73], v[222:225], v[214:217], v[70:73]
	v_mfma_f32_16x16x32_bf16 v[114:117], v[226:229], v[186:189], v[114:117]
	v_mfma_f32_16x16x32_bf16 v[114:117], v[244:247], v[190:193], v[114:117]
	v_mfma_f32_16x16x32_bf16 v[98:101], v[226:229], v[194:197], v[98:101]
	v_mfma_f32_16x16x32_bf16 v[98:101], v[244:247], v[198:201], v[98:101]
	v_mfma_f32_16x16x32_bf16 v[82:85], v[226:229], v[202:205], v[82:85]
	v_mfma_f32_16x16x32_bf16 v[82:85], v[244:247], v[206:209], v[82:85]
	v_mfma_f32_16x16x32_bf16 v[66:69], v[226:229], v[210:213], v[66:69]
	v_mfma_f32_16x16x32_bf16 v[66:69], v[244:247], v[214:217], v[66:69]
	s_barrier
	ds_read_b128 v[186:189], v176 offset:49152
	ds_read_b128 v[190:193], v176 offset:50176
	ds_read_b128 v[194:197], v176 offset:51200
	ds_read_b128 v[198:201], v176 offset:52224
	ds_read_b128 v[202:205], v176 offset:53248
	ds_read_b128 v[206:209], v176 offset:54272
	ds_read_b128 v[210:213], v176 offset:55296
	ds_read_b128 v[214:217], v176 offset:56320
	s_add_u32 s98, s52, 0x80
	s_addc_u32 s99, s53, 0
	s_add_i32 s37, s37, s62
	s_mov_b32 m0, s37
	s_nop 0
	global_load_lds_dwordx4 v134, s[98:99]
	s_add_i32 m0, s37, 0x2000
	s_nop 0
	global_load_lds_dwordx4 v130, s[98:99]
	s_add_u32 s52, s52, 0x80080
	s_addc_u32 s53, s53, 0
	s_add_i32 s37, s38, s62
	s_mov_b32 m0, s37
	s_nop 0
	global_load_lds_dwordx4 v134, s[52:53]
	s_add_i32 m0, s37, 0x2000
	s_nop 0
	global_load_lds_dwordx4 v130, s[52:53]
	s_waitcnt vmcnt(4)
	s_waitcnt lgkmcnt(0)
	s_barrier
; #define PG8_WAIT_V(n) asm volatile("s_waitcnt vmcnt(" #n ")" ::: "memory")
;     __device__ __forceinline__ void operator()(f32x4 (&acc)[2][2][4][2], const Unit& u, int wr, int wc, int fr, int fq) const {
;         const int pn = u.pn, lane = fq * 16 + fr, pmb = u.pm % 17; const bool lat = pmb != 0;
;         const int row0 = u.pm * BM + wr * 64 + fr, colq = wc * 32 + 8 * fq;
;         bf16_t* zp = Z + (size_t)row0 * ZS + pn * BM + colq;
;     ...
;         if (pn < 4) {
; #pragma unroll
;             EW_ROWS { float ss = 0.f;
; #pragma unroll
;                 for (int bj = 0; bj < 2; ++bj) { float v[8];
; #pragma unroll
;                     for (int e = 0; e < 8; ++e) { v[e] = EW_V(bj, e); ss += v[e] * v[e]; }
;                     st8(EW_ZP(bj), v); }
;                 ss += shflx(ss, 16, lane); ss += shflx(ss, 32, lane);
;                 if (fq == 0) SSQ[(size_t)(row0 + ai * HALF + m * 16) * 16 + pn * 4 + wc] = ss; }
;         } else if (pn < 8) {
; #pragma unroll
;             EW_ROWS {
; #pragma unroll
;                 for (int bj = 0; bj < 2; ++bj) { float v[8];
; #pragma unroll
;                     for (int e = 0; e < 8; ++e) v[e] = gelu_tanh(EW_V(bj, e));
;                     st8(EW_ZP(bj), v); } }
;         } else if (pn < 12) {
; #pragma unroll
;             EW_ROWS { float s = 0.f, ss = 0.f;
; #pragma unroll
;                 for (int bj = 0; bj < 2; ++bj) { float v[8];
; #pragma unroll
;                     for (int e = 0; e < 8; ++e) { const float g = gelu_tanh(EW_V(bj, e)); v[e] = g; s += g; ss += g * g; }
;                     st8(EW_ZP(bj), v); }
;                 s += shflx(s, 16, lane); s += shflx(s, 32, lane); ss += shflx(ss, 16, lane); ss += shflx(ss, 32, lane);
;                 if (fq == 0) SVS[(size_t)(row0 + ai * HALF + m * 16) * 16 + (pn - 8) * 4 + wc] = make_float2(s, ss); }
;         } else if (pn < 20 && lat) {
; #pragma unroll
;             for (int ai = 0; ai < 2; ++ai) { f32x4 c01[4], c23[4];
; #pragma unroll
; template <class Epi, class Sched>
; __device__ __forceinline__ void gemm_phase(LAS unsigned char* lds, const Gemm g, const Sched& S, const Epi& E) {
;     ...
;             PG8_BAR; PG8_WAIT_L(0); PG8_MMA(1, 0, At, B0); PG8_BAR; PG8_SCHED;
;             PG8_STAGE(PG8_SB(1, 1), b3 + hstepB, voffB);
;             PG8_WAIT_V(6); PG8_BAR; PG8_MMA(1, 1, At, B1); PG8_BAR;
;         }
;         E(acc, cur, wr, wc, fr, fq); S.done(cur);
	v_mfma_f32_16x16x32_bf16 v[62:65], v[150:153], v[186:189], v[62:65]
	v_mfma_f32_16x16x32_bf16 v[62:65], v[154:157], v[190:193], v[62:65]
	v_mfma_f32_16x16x32_bf16 v[46:49], v[150:153], v[194:197], v[46:49]
	v_mfma_f32_16x16x32_bf16 v[46:49], v[154:157], v[198:201], v[46:49]
	v_mfma_f32_16x16x32_bf16 v[30:33], v[150:153], v[202:205], v[30:33]
	v_mfma_f32_16x16x32_bf16 v[30:33], v[154:157], v[206:209], v[30:33]
	v_mfma_f32_16x16x32_bf16 v[14:17], v[150:153], v[210:213], v[14:17]
	v_mfma_f32_16x16x32_bf16 v[14:17], v[154:157], v[214:217], v[14:17]
	v_mfma_f32_16x16x32_bf16 v[58:61], v[158:161], v[186:189], v[58:61]
	v_mfma_f32_16x16x32_bf16 v[58:61], v[162:165], v[190:193], v[58:61]
	v_mfma_f32_16x16x32_bf16 v[42:45], v[158:161], v[194:197], v[42:45]
	v_mfma_f32_16x16x32_bf16 v[42:45], v[162:165], v[198:201], v[42:45]
	v_mfma_f32_16x16x32_bf16 v[26:29], v[158:161], v[202:205], v[26:29]
	v_mfma_f32_16x16x32_bf16 v[26:29], v[162:165], v[206:209], v[26:29]
	v_mfma_f32_16x16x32_bf16 v[10:13], v[158:161], v[210:213], v[10:13]
	v_mfma_f32_16x16x32_bf16 v[10:13], v[162:165], v[214:217], v[10:13]
	v_mfma_f32_16x16x32_bf16 v[54:57], v[218:221], v[186:189], v[54:57]
	v_mfma_f32_16x16x32_bf16 v[54:57], v[222:225], v[190:193], v[54:57]
	v_mfma_f32_16x16x32_bf16 v[38:41], v[218:221], v[194:197], v[38:41]
	v_mfma_f32_16x16x32_bf16 v[38:41], v[222:225], v[198:201], v[38:41]
	v_mfma_f32_16x16x32_bf16 v[22:25], v[218:221], v[202:205], v[22:25]
	v_mfma_f32_16x16x32_bf16 v[22:25], v[222:225], v[206:209], v[22:25]
	v_mfma_f32_16x16x32_bf16 v[6:9], v[218:221], v[210:213], v[6:9]
	v_mfma_f32_16x16x32_bf16 v[6:9], v[222:225], v[214:217], v[6:9]
	v_mfma_f32_16x16x32_bf16 v[50:53], v[226:229], v[186:189], v[50:53]
	v_mfma_f32_16x16x32_bf16 v[50:53], v[244:247], v[190:193], v[50:53]
	v_mfma_f32_16x16x32_bf16 v[34:37], v[226:229], v[194:197], v[34:37]
	v_mfma_f32_16x16x32_bf16 v[34:37], v[244:247], v[198:201], v[34:37]
	v_mfma_f32_16x16x32_bf16 v[18:21], v[226:229], v[202:205], v[18:21]
	v_mfma_f32_16x16x32_bf16 v[18:21], v[244:247], v[206:209], v[18:21]
	v_mfma_f32_16x16x32_bf16 v[2:5], v[226:229], v[210:213], v[2:5]
	v_mfma_f32_16x16x32_bf16 v[2:5], v[244:247], v[214:217], v[2:5]
	s_add_i32 s36, s36, 2
	s_add_u32 s12, s12, 0x100
	s_addc_u32 s13, s13, 0
	s_add_u32 s29, s29, 0x100
	s_addc_u32 s30, s30, 0
	s_cmp_gt_u32 s36, 29
	s_barrier
	s_cbranch_scc0 .LBB0_381
	v_lshl_add_u32 v152, s0, 8, v169
	v_mov_b64_e32 v[150:151], s[16:17]
	v_mad_i64_i32 v[150:151], s[12:13], v152, s84, v[150:151]
	s_lshl_b32 s12, s33, 8
	s_ashr_i32 s13, s12, 31
	v_lshl_add_u64 v[150:151], s[12:13], 1, v[150:151]
	v_readlane_b32 s76, v255, 26
	v_ashrrev_i32_e32 v153, 31, v152
	v_lshl_add_u64 v[150:151], v[150:151], 0, v[178:179]
	s_cmp_gt_i32 s33, 3
	s_mov_b64 s[12:13], -1
	v_readlane_b32 s77, v255, 27
	s_mov_b64 s[36:37], s[74:75]
	v_mov_b32_e32 v230, 0x3727c5ac
	s_cbranch_scc0 .LBB0_446
	s_cmp_gt_u32 s33, 7
	s_cbranch_scc0 .LBB0_443
	s_cmp_gt_u32 s33, 11
	s_cbranch_scc0 .LBB0_424
	s_mul_hi_i32 s1, s0, 0x78787879
	s_lshr_b32 s12, s1, 31
	s_ashr_i32 s1, s1, 3
	s_add_i32 s1, s1, s12
	s_mul_i32 s1, s1, 17
	s_sub_i32 s1, s0, s1
	s_cmp_lg_u32 s1, 0
	s_cselect_b64 s[28:29], -1, 0
	s_cmp_lt_u32 s33, 20
	s_cselect_b64 s[12:13], -1, 0
	s_and_b64 s[12:13], s[12:13], s[28:29]
	s_andn2_b64 vcc, exec, s[12:13]
	s_mov_b64 s[12:13], -1
	s_cbranch_vccz .LBB0_421
	s_cmp_gt_u32 s33, 23
	s_cbranch_scc0 .LBB0_418
	s_cmp_gt_u32 s33, 47
	s_cbranch_scc0 .LBB0_415
	s_andn2_b64 vcc, exec, s[4:5]
	s_cbranch_vccnz .LBB0_414
	s_lshl_b32 s23, s1, 2
	v_cndmask_b32_e64 v154, 0, 1, s[28:29]
	v_cmp_ne_u32_e64 s[12:13], 1, v154
	s_andn2_b64 vcc, exec, s[28:29]
	s_add_i32 s23, s23, s79
	s_cbranch_vccnz .LBB0_391
	v_mov_b32_e32 v154, s23
	v_cndmask_b32_e64 v154, v168, v154, s[6:7]
	v_lshlrev_b32_e32 v154, 4, v154
	v_ashrrev_i32_e32 v155, 31, v154
	v_lshl_add_u64 v[154:155], v[154:155], 3, v[138:139]
	global_load_dwordx4 v[164:167], v[154:155], off offset:16
	global_load_dwordx4 v[156:159], v[154:155], off
	s_waitcnt vmcnt(0)
	v_pk_mul_f32 v[162:163], v[122:123], v[164:165] op_sel:[1,1] op_sel_hi:[0,1]
	v_pk_mul_f32 v[184:185], v[126:127], v[156:157] op_sel:[1,1] op_sel_hi:[0,1]
	v_pk_fma_f32 v[154:155], v[126:127], v[156:157], v[184:185] op_sel_hi:[1,0,1]
	v_pk_mul_f32 v[182:183], v[126:127], v[156:157]
	v_mov_b32_e32 v154, v159
	v_pk_mul_f32 v[160:161], v[128:129], v[154:155] op_sel:[1,0] op_sel_hi:[0,0]
	v_mul_f32_e32 v154, v125, v167
	v_pk_fma_f32 v[156:157], v[128:129], v[158:159], v[160:161] op_sel_hi:[1,0,1] neg_lo:[0,0,1] neg_hi:[0,0,1]
	v_pk_fma_f32 v[158:159], v[128:129], v[158:159], v[160:161] op_sel_hi:[1,0,1]
	v_pk_fma_f32 v[160:161], v[122:123], v[164:165], v[162:163] op_sel_hi:[1,0,1] neg_lo:[0,0,1] neg_hi:[0,0,1]
	v_pk_fma_f32 v[162:163], v[122:123], v[164:165], v[162:163] op_sel_hi:[1,0,1]
	v_pk_fma_f32 v[164:165], v[124:125], v[166:167], v[154:155] op_sel_hi:[1,1,0] neg_lo:[0,0,1] neg_hi:[0,0,1]
	v_mul_f32_e32 v154, v124, v167
	v_pk_fma_f32 v[166:167], v[124:125], v[166:167], v[154:155] op_sel:[1,0,0] op_sel_hi:[0,1,0]
	v_sub_f32_e32 v154, v182, v184
	s_branch .LBB0_392

; #define PG8_STAGE(bufoff, gbase, voff) do { _Pragma("unroll") for (int _i = 0; _i < 2; ++_i) \
;         __builtin_amdgcn_global_load_lds((const unsigned*)((const char*)(gbase) + (voff)[_i]), (LAS unsigned*)(lds + (bufoff) + ldsw + _i * 8192), 16, 0, 0); } while (0)
; #define PG8_LDA(dst, b, h) do { _Pragma("unroll") for (int m = 0; m < 4; ++m) _Pragma("unroll") for (int k = 0; k < 2; ++k) dst[m][k] = *(const LAS bf16x8*)(lds + PG8_SA(b, h) + aoff + m * 2048 + k * 1024); } while (0)
; #define PG8_WAIT_V(n) asm volatile("s_waitcnt vmcnt(" #n ")" ::: "memory")
; template <class Epi, class Sched>
; __device__ __forceinline__ void gemm_phase(LAS unsigned char* lds, const Gemm g, const Sched& S, const Epi& E) {
;     ...
;         for (int t = 0; t < ntu; t += 2) {
;             const bool last = (t == ntu - 2);
;             const char* a1 = cA + (size_t)(t + 1) * kstep;
;             const char* a2 = last ? nA : cA + (size_t)(t + 2) * kstep; const char* b2 = last ? nB : cB + (size_t)(t + 2) * kstep;
;             const char* a3 = a2 + kstep; const char* b3 = b2 + kstep;
;             if (last && has_next) S.a_ready(nxt);
;             PG8_LDB(B0, 0, 0); PG8_SCHED; PG8_LDA(At, 0, 0); PG8_STAGE(PG8_SA(1, 1), a1 + hstepA, voffA);
;             PG8_WAIT_L(8); PG8_BAR; PG8_WAIT_L(0); PG8_MMA(0, 0, At, B0); PG8_BAR; PG8_SCHED;
;             PG8_LDB(B1, 0, 1); PG8_STAGE(PG8_SB(0, 0), b2, voffB);
;             PG8_BAR; PG8_WAIT_L(0); PG8_MMA(0, 1, At, B1); PG8_BAR;
;             PG8_LDA(At, 0, 1); PG8_STAGE(PG8_SA(0, 0), a2, voffA);
;             PG8_BAR; PG8_WAIT_L(0); PG8_MMA(1, 0, At, B0); PG8_BAR; PG8_SCHED;
;             PG8_STAGE(PG8_SB(0, 1), b2 + hstepB, voffB);
;             PG8_WAIT_V(6); PG8_BAR; PG8_MMA(1, 1, At, B1); PG8_BAR;
;             PG8_LDB(B0, 1, 0); PG8_SCHED; PG8_LDA(At, 1, 0); PG8_STAGE(PG8_SA(0, 1), a2 + hstepA, voffA);
;             PG8_WAIT_L(8); PG8_BAR; PG8_WAIT_L(0); PG8_MMA(0, 0, At, B0); PG8_BAR; PG8_SCHED;
;             PG8_LDB(B1, 1, 1); PG8_STAGE(PG8_SB(1, 0), b3, voffB);
;             PG8_BAR; PG8_WAIT_L(0); PG8_MMA(0, 1, At, B1); PG8_BAR;
;             PG8_LDA(At, 1, 1); PG8_STAGE(PG8_SA(1, 0), a3, voffA);
;             PG8_BAR; PG8_WAIT_L(0); PG8_MMA(1, 0, At, B0); PG8_BAR; PG8_SCHED;
;             PG8_STAGE(PG8_SB(1, 1), b3 + hstepB, voffB);
;             PG8_WAIT_V(6); PG8_BAR; PG8_MMA(1, 1, At, B1); PG8_BAR;
.LBB0_571:
	s_add_u32 s6, s56, 0x100
	s_addc_u32 s7, s57, 0
	s_add_i32 s77, 0, 0x10000
	v_add_u32_e32 v142, s77, v197
	ds_read_b128 v[130:133], v142
	ds_read_b128 v[134:137], v142 offset:1024
	ds_read_b128 v[138:141], v142 offset:2048
	ds_read_b128 v[142:145], v142 offset:3072
	s_cmp_eq_u32 s76, 4
	s_cselect_b32 s63, s53, s7
	s_cselect_b32 s62, s52, s6
	s_cselect_b32 s59, s28, s51
	s_cselect_b32 s58, s29, s30
	ds_read_b128 v[164:167], v201
	ds_read_b128 v[168:171], v201 offset:1024
	ds_read_b128 v[172:175], v201 offset:2048
	ds_read_b128 v[186:189], v201 offset:3072
	ds_read_b128 v[202:205], v201 offset:4096
	ds_read_b128 v[206:209], v201 offset:5120
	ds_read_b128 v[210:213], v201 offset:6144
	ds_read_b128 v[214:217], v201 offset:7168
	s_add_u32 s98, s56, 0xffe7c000
	s_addc_u32 s99, s57, -1
	s_mov_b32 m0, s66
	s_nop 0
	global_load_lds_dwordx4 v160, s[98:99]
	s_mov_b32 m0, s67
	s_nop 0
	global_load_lds_dwordx4 v162, s[98:99]
	s_add_i32 m0, s38, 0xc000
	s_nop 0
	global_load_lds_dwordx4 v160, s[56:57]
	s_add_i32 m0, s38, 0xe000
	s_nop 0
	global_load_lds_dwordx4 v162, s[56:57]
	s_add_i32 s79, 0, 0x14000
	v_add_u32_e32 v176, s79, v197
	ds_read_b128 v[218:221], v176
	ds_read_b128 v[222:225], v176 offset:1024
	ds_read_b128 v[226:229], v176 offset:2048
	ds_read_b128 v[244:247], v176 offset:3072
	s_waitcnt lgkmcnt(0)
	s_barrier
	v_mfma_f32_16x16x32_bf16 v[126:129], v[130:133], v[164:167], v[126:129]
	v_mfma_f32_16x16x32_bf16 v[126:129], v[134:137], v[168:171], v[126:129]
	v_mfma_f32_16x16x32_bf16 v[118:121], v[130:133], v[172:175], v[118:121]
	v_mfma_f32_16x16x32_bf16 v[118:121], v[134:137], v[186:189], v[118:121]
	v_mfma_f32_16x16x32_bf16 v[110:113], v[130:133], v[202:205], v[110:113]
	v_mfma_f32_16x16x32_bf16 v[110:113], v[134:137], v[206:209], v[110:113]
	v_mfma_f32_16x16x32_bf16 v[102:105], v[130:133], v[210:213], v[102:105]
	v_mfma_f32_16x16x32_bf16 v[102:105], v[134:137], v[214:217], v[102:105]
	v_mfma_f32_16x16x32_bf16 v[122:125], v[138:141], v[164:167], v[122:125]
	v_mfma_f32_16x16x32_bf16 v[122:125], v[142:145], v[168:171], v[122:125]
	v_mfma_f32_16x16x32_bf16 v[114:117], v[138:141], v[172:175], v[114:117]
	v_mfma_f32_16x16x32_bf16 v[114:117], v[142:145], v[186:189], v[114:117]
	v_mfma_f32_16x16x32_bf16 v[106:109], v[138:141], v[202:205], v[106:109]
	v_mfma_f32_16x16x32_bf16 v[106:109], v[142:145], v[206:209], v[106:109]
	v_mfma_f32_16x16x32_bf16 v[98:101], v[138:141], v[210:213], v[98:101]
	v_mfma_f32_16x16x32_bf16 v[98:101], v[142:145], v[214:217], v[98:101]
	v_mfma_f32_16x16x32_bf16 v[94:97], v[218:221], v[164:167], v[94:97]
	v_mfma_f32_16x16x32_bf16 v[94:97], v[222:225], v[168:171], v[94:97]
	v_mfma_f32_16x16x32_bf16 v[86:89], v[218:221], v[172:175], v[86:89]
	v_mfma_f32_16x16x32_bf16 v[86:89], v[222:225], v[186:189], v[86:89]
	v_mfma_f32_16x16x32_bf16 v[78:81], v[218:221], v[202:205], v[78:81]
	v_mfma_f32_16x16x32_bf16 v[78:81], v[222:225], v[206:209], v[78:81]
	v_mfma_f32_16x16x32_bf16 v[70:73], v[218:221], v[210:213], v[70:73]
	v_mfma_f32_16x16x32_bf16 v[70:73], v[222:225], v[214:217], v[70:73]
	v_mfma_f32_16x16x32_bf16 v[90:93], v[226:229], v[164:167], v[90:93]
	v_mfma_f32_16x16x32_bf16 v[90:93], v[244:247], v[168:171], v[90:93]
	v_mfma_f32_16x16x32_bf16 v[82:85], v[226:229], v[172:175], v[82:85]
	v_mfma_f32_16x16x32_bf16 v[82:85], v[244:247], v[186:189], v[82:85]
	v_mfma_f32_16x16x32_bf16 v[74:77], v[226:229], v[202:205], v[74:77]
	v_mfma_f32_16x16x32_bf16 v[74:77], v[244:247], v[206:209], v[74:77]
	v_mfma_f32_16x16x32_bf16 v[66:69], v[226:229], v[210:213], v[66:69]
	v_mfma_f32_16x16x32_bf16 v[66:69], v[244:247], v[214:217], v[66:69]
	s_barrier
	ds_read_b128 v[164:167], v201 offset:16384
	ds_read_b128 v[168:171], v201 offset:17408
	ds_read_b128 v[172:175], v201 offset:18432
	ds_read_b128 v[186:189], v201 offset:19456
	ds_read_b128 v[202:205], v201 offset:20480
	ds_read_b128 v[206:209], v201 offset:21504
	ds_read_b128 v[210:213], v201 offset:22528
	ds_read_b128 v[214:217], v201 offset:23552
	s_add_i32 s56, s77, s33
	s_mov_b32 m0, s56
	s_nop 0
	global_load_lds_dwordx4 v152, s[58:59]
	s_add_i32 m0, s56, 0x2000
	s_nop 0
	global_load_lds_dwordx4 v148, s[58:59]
	s_add_u32 s56, s58, 0x20000
	s_addc_u32 s57, s59, 0
	s_add_i32 s77, s79, s33
	s_mov_b32 m0, s77
	s_nop 0
	global_load_lds_dwordx4 v152, s[56:57]
	s_add_i32 m0, s77, 0x2000
	s_nop 0
	global_load_lds_dwordx4 v148, s[56:57]
	s_waitcnt vmcnt(4)
	s_waitcnt lgkmcnt(0)
	s_barrier
	v_mfma_f32_16x16x32_bf16 v[62:65], v[130:133], v[164:167], v[62:65]
	v_mfma_f32_16x16x32_bf16 v[62:65], v[134:137], v[168:171], v[62:65]
	v_mfma_f32_16x16x32_bf16 v[54:57], v[130:133], v[172:175], v[54:57]
	v_mfma_f32_16x16x32_bf16 v[54:57], v[134:137], v[186:189], v[54:57]
	v_mfma_f32_16x16x32_bf16 v[46:49], v[130:133], v[202:205], v[46:49]
	v_mfma_f32_16x16x32_bf16 v[46:49], v[134:137], v[206:209], v[46:49]
	v_mfma_f32_16x16x32_bf16 v[38:41], v[130:133], v[210:213], v[38:41]
	v_mfma_f32_16x16x32_bf16 v[38:41], v[134:137], v[214:217], v[38:41]
	v_mfma_f32_16x16x32_bf16 v[58:61], v[138:141], v[164:167], v[58:61]
	v_mfma_f32_16x16x32_bf16 v[58:61], v[142:145], v[168:171], v[58:61]
	v_mfma_f32_16x16x32_bf16 v[50:53], v[138:141], v[172:175], v[50:53]
	v_mfma_f32_16x16x32_bf16 v[50:53], v[142:145], v[186:189], v[50:53]
	v_mfma_f32_16x16x32_bf16 v[42:45], v[138:141], v[202:205], v[42:45]
	v_mfma_f32_16x16x32_bf16 v[42:45], v[142:145], v[206:209], v[42:45]
	v_mfma_f32_16x16x32_bf16 v[34:37], v[138:141], v[210:213], v[34:37]
	v_mfma_f32_16x16x32_bf16 v[34:37], v[142:145], v[214:217], v[34:37]
	v_mfma_f32_16x16x32_bf16 v[30:33], v[218:221], v[164:167], v[30:33]
	v_mfma_f32_16x16x32_bf16 v[30:33], v[222:225], v[168:171], v[30:33]
	v_mfma_f32_16x16x32_bf16 v[22:25], v[218:221], v[172:175], v[22:25]
	v_mfma_f32_16x16x32_bf16 v[22:25], v[222:225], v[186:189], v[22:25]
	v_mfma_f32_16x16x32_bf16 v[14:17], v[218:221], v[202:205], v[14:17]
	v_mfma_f32_16x16x32_bf16 v[14:17], v[222:225], v[206:209], v[14:17]
	v_mfma_f32_16x16x32_bf16 v[6:9], v[218:221], v[210:213], v[6:9]
	v_mfma_f32_16x16x32_bf16 v[6:9], v[222:225], v[214:217], v[6:9]
	v_mfma_f32_16x16x32_bf16 v[26:29], v[226:229], v[164:167], v[26:29]
	v_mfma_f32_16x16x32_bf16 v[26:29], v[244:247], v[168:171], v[26:29]
	v_mfma_f32_16x16x32_bf16 v[18:21], v[226:229], v[172:175], v[18:21]
	v_mfma_f32_16x16x32_bf16 v[18:21], v[244:247], v[186:189], v[18:21]
	v_mfma_f32_16x16x32_bf16 v[10:13], v[226:229], v[202:205], v[10:13]
	v_mfma_f32_16x16x32_bf16 v[10:13], v[244:247], v[206:209], v[10:13]
	v_mfma_f32_16x16x32_bf16 v[2:5], v[226:229], v[210:213], v[2:5]
	v_mfma_f32_16x16x32_bf16 v[2:5], v[244:247], v[214:217], v[2:5]
	s_add_i32 s77, 0, 0x18000
	v_add_u32_e32 v142, s77, v197
	s_barrier
; #define PG8_STAGE(bufoff, gbase, voff) do { _Pragma("unroll") for (int _i = 0; _i < 2; ++_i) \
;         __builtin_amdgcn_global_load_lds((const unsigned*)((const char*)(gbase) + (voff)[_i]), (LAS unsigned*)(lds + (bufoff) + ldsw + _i * 8192), 16, 0, 0); } while (0)
; #define PG8_LDA(dst, b, h) do { _Pragma("unroll") for (int m = 0; m < 4; ++m) _Pragma("unroll") for (int k = 0; k < 2; ++k) dst[m][k] = *(const LAS bf16x8*)(lds + PG8_SA(b, h) + aoff + m * 2048 + k * 1024); } while (0)
; #define PG8_LDB(dst, b, h) do { _Pragma("unroll") for (int n = 0; n < 2; ++n) _Pragma("unroll") for (int k = 0; k < 2; ++k) dst[n][k] = *(const LAS bf16x8*)(lds + PG8_SB(b, h) + boff + n * 2048 + k * 1024); } while (0)
; #define PG8_WAIT_V(n) asm volatile("s_waitcnt vmcnt(" #n ")" ::: "memory")
; #define PG8_WAIT_L(n) asm volatile("s_waitcnt lgkmcnt(" #n ")" ::: "memory")
; #define PG8_BAR __builtin_amdgcn_s_barrier()
; #define PG8_SCHED __builtin_amdgcn_sched_barrier(0)
; template <class Epi, class Sched>
; __device__ __forceinline__ void gemm_phase(LAS unsigned char* lds, const Gemm g, const Sched& S, const Epi& E) {
;     ...
;             PG8_LDB(B0, 0, 0); PG8_SCHED; PG8_LDA(At, 0, 0); PG8_STAGE(PG8_SA(1, 1), a1 + hstepA, voffA);
;             PG8_WAIT_L(8); PG8_BAR; PG8_WAIT_L(0); PG8_MMA(0, 0, At, B0); PG8_BAR; PG8_SCHED;
;             PG8_LDB(B1, 0, 1); PG8_STAGE(PG8_SB(0, 0), b2, voffB);
;             PG8_BAR; PG8_WAIT_L(0); PG8_MMA(0, 1, At, B1); PG8_BAR;
;             PG8_LDA(At, 0, 1); PG8_STAGE(PG8_SA(0, 0), a2, voffA);
;             PG8_BAR; PG8_WAIT_L(0); PG8_MMA(1, 0, At, B0); PG8_BAR; PG8_SCHED;
;             PG8_STAGE(PG8_SB(0, 1), b2 + hstepB, voffB);
;             PG8_WAIT_V(6); PG8_BAR; PG8_MMA(1, 1, At, B1); PG8_BAR;
;             PG8_LDB(B0, 1, 0); PG8_SCHED; PG8_LDA(At, 1, 0); PG8_STAGE(PG8_SA(0, 1), a2 + hstepA, voffA);
;             PG8_WAIT_L(8); PG8_BAR; PG8_WAIT_L(0); PG8_MMA(0, 0, At, B0); PG8_BAR; PG8_SCHED;
;             PG8_LDB(B1, 1, 1); PG8_STAGE(PG8_SB(1, 0), b3, voffB);
;             PG8_BAR; PG8_WAIT_L(0); PG8_MMA(0, 1, At, B1); PG8_BAR;
;             PG8_LDA(At, 1, 1); PG8_STAGE(PG8_SA(1, 0), a3, voffA);
;             PG8_BAR; PG8_WAIT_L(0); PG8_MMA(1, 0, At, B0); PG8_BAR; PG8_SCHED;
;             PG8_STAGE(PG8_SB(1, 1), b3 + hstepB, voffB);
;             PG8_WAIT_V(6); PG8_BAR; PG8_MMA(1, 1, At, B1); PG8_BAR;
;         }
	ds_read_b128 v[130:133], v142
	ds_read_b128 v[134:137], v142 offset:1024
	ds_read_b128 v[138:141], v142 offset:2048
	ds_read_b128 v[142:145], v142 offset:3072
	ds_read_b128 v[164:167], v201 offset:32768
	ds_read_b128 v[168:171], v201 offset:33792
	ds_read_b128 v[172:175], v201 offset:34816
	ds_read_b128 v[186:189], v201 offset:35840
	ds_read_b128 v[202:205], v201 offset:36864
	ds_read_b128 v[206:209], v201 offset:37888
	ds_read_b128 v[210:213], v201 offset:38912
	ds_read_b128 v[214:217], v201 offset:39936
	s_mov_b32 m0, s38
	s_nop 0
	global_load_lds_dwordx4 v154, s[62:63]
	s_mov_b32 m0, s39
	s_nop 0
	global_load_lds_dwordx4 v150, s[62:63]
	s_add_u32 s56, s62, 0x184000
	s_addc_u32 s57, s63, 0
	s_mov_b32 m0, s46
	s_nop 0
	global_load_lds_dwordx4 v154, s[56:57]
	s_mov_b32 m0, s64
	s_nop 0
	global_load_lds_dwordx4 v150, s[56:57]
	s_add_i32 s62, 0, 0x1c000
	v_add_u32_e32 v178, s62, v197
	ds_read_b128 v[218:221], v178
	ds_read_b128 v[222:225], v178 offset:1024
	ds_read_b128 v[226:229], v178 offset:2048
	ds_read_b128 v[244:247], v178 offset:3072
	s_waitcnt lgkmcnt(0)
	s_barrier
	v_mfma_f32_16x16x32_bf16 v[126:129], v[130:133], v[164:167], v[126:129]
	v_mfma_f32_16x16x32_bf16 v[126:129], v[134:137], v[168:171], v[126:129]
	v_mfma_f32_16x16x32_bf16 v[118:121], v[130:133], v[172:175], v[118:121]
	v_mfma_f32_16x16x32_bf16 v[118:121], v[134:137], v[186:189], v[118:121]
	v_mfma_f32_16x16x32_bf16 v[110:113], v[130:133], v[202:205], v[110:113]
	v_mfma_f32_16x16x32_bf16 v[110:113], v[134:137], v[206:209], v[110:113]
	v_mfma_f32_16x16x32_bf16 v[102:105], v[130:133], v[210:213], v[102:105]
	v_mfma_f32_16x16x32_bf16 v[102:105], v[134:137], v[214:217], v[102:105]
	v_mfma_f32_16x16x32_bf16 v[122:125], v[138:141], v[164:167], v[122:125]
	v_mfma_f32_16x16x32_bf16 v[122:125], v[142:145], v[168:171], v[122:125]
	v_mfma_f32_16x16x32_bf16 v[114:117], v[138:141], v[172:175], v[114:117]
	v_mfma_f32_16x16x32_bf16 v[114:117], v[142:145], v[186:189], v[114:117]
	v_mfma_f32_16x16x32_bf16 v[106:109], v[138:141], v[202:205], v[106:109]
	v_mfma_f32_16x16x32_bf16 v[106:109], v[142:145], v[206:209], v[106:109]
	v_mfma_f32_16x16x32_bf16 v[98:101], v[138:141], v[210:213], v[98:101]
	v_mfma_f32_16x16x32_bf16 v[98:101], v[142:145], v[214:217], v[98:101]
	v_mfma_f32_16x16x32_bf16 v[94:97], v[218:221], v[164:167], v[94:97]
	v_mfma_f32_16x16x32_bf16 v[94:97], v[222:225], v[168:171], v[94:97]
	v_mfma_f32_16x16x32_bf16 v[86:89], v[218:221], v[172:175], v[86:89]
	v_mfma_f32_16x16x32_bf16 v[86:89], v[222:225], v[186:189], v[86:89]
	v_mfma_f32_16x16x32_bf16 v[78:81], v[218:221], v[202:205], v[78:81]
	v_mfma_f32_16x16x32_bf16 v[78:81], v[222:225], v[206:209], v[78:81]
	v_mfma_f32_16x16x32_bf16 v[70:73], v[218:221], v[210:213], v[70:73]
	v_mfma_f32_16x16x32_bf16 v[70:73], v[222:225], v[214:217], v[70:73]
	v_mfma_f32_16x16x32_bf16 v[90:93], v[226:229], v[164:167], v[90:93]
	v_mfma_f32_16x16x32_bf16 v[90:93], v[244:247], v[168:171], v[90:93]
	v_mfma_f32_16x16x32_bf16 v[82:85], v[226:229], v[172:175], v[82:85]
	v_mfma_f32_16x16x32_bf16 v[82:85], v[244:247], v[186:189], v[82:85]
	v_mfma_f32_16x16x32_bf16 v[74:77], v[226:229], v[202:205], v[74:77]
	v_mfma_f32_16x16x32_bf16 v[74:77], v[244:247], v[206:209], v[74:77]
	v_mfma_f32_16x16x32_bf16 v[66:69], v[226:229], v[210:213], v[66:69]
	v_mfma_f32_16x16x32_bf16 v[66:69], v[244:247], v[214:217], v[66:69]
	s_barrier
	ds_read_b128 v[164:167], v201 offset:49152
	ds_read_b128 v[168:171], v201 offset:50176
	ds_read_b128 v[172:175], v201 offset:51200
	ds_read_b128 v[186:189], v201 offset:52224
	ds_read_b128 v[202:205], v201 offset:53248
	ds_read_b128 v[206:209], v201 offset:54272
	ds_read_b128 v[210:213], v201 offset:55296
	ds_read_b128 v[214:217], v201 offset:56320
	s_add_u32 s98, s58, 0x80
	s_addc_u32 s99, s59, 0
	s_add_i32 s56, s77, s33
	s_mov_b32 m0, s56
	s_nop 0
	global_load_lds_dwordx4 v152, s[98:99]
	s_add_i32 m0, s56, 0x2000
	s_nop 0
	global_load_lds_dwordx4 v148, s[98:99]
	s_add_u32 s56, s58, 0x20080
	s_addc_u32 s57, s59, 0
	s_add_i32 s58, s62, s33
	s_mov_b32 m0, s58
	s_nop 0
	global_load_lds_dwordx4 v152, s[56:57]
	s_add_i32 m0, s58, 0x2000
	s_nop 0
	global_load_lds_dwordx4 v148, s[56:57]
	s_waitcnt vmcnt(4)
	s_waitcnt lgkmcnt(0)
	s_barrier
	v_mfma_f32_16x16x32_bf16 v[62:65], v[130:133], v[164:167], v[62:65]
	v_mfma_f32_16x16x32_bf16 v[62:65], v[134:137], v[168:171], v[62:65]
	v_mfma_f32_16x16x32_bf16 v[54:57], v[130:133], v[172:175], v[54:57]
	v_mfma_f32_16x16x32_bf16 v[54:57], v[134:137], v[186:189], v[54:57]
	v_mfma_f32_16x16x32_bf16 v[46:49], v[130:133], v[202:205], v[46:49]
	v_mfma_f32_16x16x32_bf16 v[46:49], v[134:137], v[206:209], v[46:49]
	v_mfma_f32_16x16x32_bf16 v[38:41], v[130:133], v[210:213], v[38:41]
	v_mfma_f32_16x16x32_bf16 v[38:41], v[134:137], v[214:217], v[38:41]
	v_mfma_f32_16x16x32_bf16 v[58:61], v[138:141], v[164:167], v[58:61]
	v_mfma_f32_16x16x32_bf16 v[58:61], v[142:145], v[168:171], v[58:61]
	v_mfma_f32_16x16x32_bf16 v[50:53], v[138:141], v[172:175], v[50:53]
	v_mfma_f32_16x16x32_bf16 v[50:53], v[142:145], v[186:189], v[50:53]
	v_mfma_f32_16x16x32_bf16 v[42:45], v[138:141], v[202:205], v[42:45]
	v_mfma_f32_16x16x32_bf16 v[42:45], v[142:145], v[206:209], v[42:45]
	v_mfma_f32_16x16x32_bf16 v[34:37], v[138:141], v[210:213], v[34:37]
	v_mfma_f32_16x16x32_bf16 v[34:37], v[142:145], v[214:217], v[34:37]
	v_mfma_f32_16x16x32_bf16 v[30:33], v[218:221], v[164:167], v[30:33]
	v_mfma_f32_16x16x32_bf16 v[30:33], v[222:225], v[168:171], v[30:33]
	v_mfma_f32_16x16x32_bf16 v[22:25], v[218:221], v[172:175], v[22:25]
	v_mfma_f32_16x16x32_bf16 v[22:25], v[222:225], v[186:189], v[22:25]
	v_mfma_f32_16x16x32_bf16 v[14:17], v[218:221], v[202:205], v[14:17]
	v_mfma_f32_16x16x32_bf16 v[14:17], v[222:225], v[206:209], v[14:17]
	v_mfma_f32_16x16x32_bf16 v[6:9], v[218:221], v[210:213], v[6:9]
	v_mfma_f32_16x16x32_bf16 v[6:9], v[222:225], v[214:217], v[6:9]
	v_mfma_f32_16x16x32_bf16 v[26:29], v[226:229], v[164:167], v[26:29]
	v_mfma_f32_16x16x32_bf16 v[26:29], v[244:247], v[168:171], v[26:29]
	v_mfma_f32_16x16x32_bf16 v[18:21], v[226:229], v[172:175], v[18:21]
	v_mfma_f32_16x16x32_bf16 v[18:21], v[244:247], v[186:189], v[18:21]
	v_mfma_f32_16x16x32_bf16 v[10:13], v[226:229], v[202:205], v[10:13]
	v_mfma_f32_16x16x32_bf16 v[10:13], v[244:247], v[206:209], v[10:13]
	v_mfma_f32_16x16x32_bf16 v[2:5], v[226:229], v[210:213], v[2:5]
	v_mfma_f32_16x16x32_bf16 v[2:5], v[244:247], v[214:217], v[2:5]
	s_add_i32 s76, s76, 2
	s_add_u32 s30, s30, 0x100
	s_addc_u32 s51, s51, 0
	s_cmp_gt_u32 s76, 5
	s_mov_b64 s[56:57], s[6:7]
	s_barrier
; __device__ __forceinline__ unsigned cvt_pk_bf16(float lo, float hi) { const f32x2_t v = {lo, hi}; return __builtin_bit_cast(unsigned, __builtin_convertvector(v, bf16x2_t)); }
;     __device__ __forceinline__ void operator()(f32x4 (&acc)[2][2][4][2], const Unit& u, int wr, int wc, int fr, int fq) const {
;         const int row0 = u.pm * BM + wr * 64 + fr;
; #pragma unroll
;         for (int ai = 0; ai < 2; ++ai) {
;             f32x4 s0[4], s1[4]; float rstd[4];
; #pragma unroll
;             for (int m = 0; m < 4; ++m) { const float* sp = SSQ + (size_t)(row0 + ai * HALF + m * 16) * 16 + 8; s0[m] = *(const f32x4*)sp; s1[m] = *(const f32x4*)(sp + 4); }
; #pragma unroll
;             for (int m = 0; m < 4; ++m) rstd[m] = rsqrtf(((s0[m][0] + s0[m][1]) + (s0[m][2] + s0[m][3]) + (s1[m][0] + s1[m][1]) + (s1[m][2] + s1[m][3])) * (1.0f / 512.0f) + EPS);
;             if (u.pn < 4) {
; #pragma unroll
;                 for (int m = 0; m < 4; ++m)
; #pragma unroll
;                     for (int bj = 0; bj < 2; ++bj) { const int c0 = u.pn * BM + bj * HALF + wc * 32 + 8 * fq; const f32x4 v0 = acc[ai][bj][m][0] * rstd[m], v1 = acc[ai][bj][m][1] * rstd[m];
;                         u32x4 w; w.x = cvt_pk_bf16(v0[0], v0[1]); w.y = cvt_pk_bf16(v0[2], v0[3]); w.z = cvt_pk_bf16(v1[0], v1[1]); w.w = cvt_pk_bf16(v1[2], v1[3]);
;                         *(u32x4*)(KM + (size_t)(row0 + ai * HALF + m * 16) * 1536 + (c0 >> 7) * 192 + (c0 & 127)) = w; }
;             } else {
; #pragma unroll
;                 for (int m = 0; m < 4; ++m)
; #pragma unroll
;                     for (int bj = 0; bj < 2; ++bj) { const int c0 = u.pn * BM + bj * HALF + wc * 32 + 8 * fq; const f32x4 v0 = acc[ai][bj][m][0] * rstd[m], v1 = acc[ai][bj][m][1] * rstd[m];
;                         u32x4 w; w.x = cvt_pk_bf16(v0[0], v0[1]); w.y = cvt_pk_bf16(v0[2], v0[3]); w.z = cvt_pk_bf16(v1[0], v1[1]); w.w = cvt_pk_bf16(v1[2], v1[3]);
;                         *(u32x4*)(VM + (size_t)(row0 + ai * HALF + m * 16) * 1024 + (c0 - 1024)) = w; }
	s_cbranch_scc0 .LBB0_571
	v_lshl_add_u32 v164, s72, 8, v196
	v_ashrrev_i32_e32 v165, 31, v164
	v_lshlrev_b64 v[130:131], 6, v[164:165]
	v_readlane_b32 s76, v255, 26
	s_cmp_gt_i32 s71, 5
	v_lshl_add_u64 v[172:173], s[26:27], 0, v[130:131]
	s_mov_b64 s[6:7], -1
	v_or_b32_e32 v168, 16, v164
	v_or_b32_e32 v166, 32, v164
	v_or_b32_e32 v170, 48, v164
	v_readlane_b32 s77, v255, 27
	s_cbranch_scc0 .LBB0_582
	v_ashrrev_i32_e32 v169, 31, v168
	v_lshlrev_b64 v[130:131], 6, v[168:169]
	v_lshl_add_u64 v[130:131], s[26:27], 0, v[130:131]
	global_load_dwordx4 v[174:177], v[172:173], off offset:48
	global_load_dwordx4 v[186:189], v[172:173], off offset:32
	global_load_dwordx4 v[202:205], v[130:131], off offset:48
	global_load_dwordx4 v[206:209], v[130:131], off offset:32
	v_ashrrev_i32_e32 v167, 31, v166
	v_lshlrev_b64 v[130:131], 6, v[166:167]
	v_lshl_add_u64 v[130:131], s[26:27], 0, v[130:131]
	v_ashrrev_i32_e32 v171, 31, v170
	global_load_dwordx4 v[134:137], v[130:131], off offset:48
	global_load_dwordx4 v[138:141], v[130:131], off offset:32
	v_lshlrev_b64 v[130:131], 6, v[170:171]
	v_lshl_add_u64 v[142:143], s[26:27], 0, v[130:131]
	global_load_dwordx4 v[130:133], v[142:143], off offset:48
	s_nop 0
	global_load_dwordx4 v[142:145], v[142:143], off offset:32
	s_mov_b32 s6, 0x3727c5ac
	s_add_i32 s28, s71, -6
	s_cmp_gt_u32 s28, 3
	s_cselect_b64 s[56:57], -1, 0
	s_cmp_lt_u32 s28, 4
	v_lshl_or_b32 v178, s28, 8, v158
	s_waitcnt vmcnt(0)
	v_mov_b32_e32 v184, v176
	v_mov_b32_e32 v182, v187
	v_mov_b32_e32 v183, v188
	v_mov_b32_e32 v187, v189
	v_mov_b32_e32 v185, v174
	v_mov_b32_e32 v174, v177
	v_mov_b32_e32 v176, v207
	v_mov_b32_e32 v177, v208
	v_mov_b32_e32 v207, v209
	v_pk_add_f32 v[182:183], v[182:183], v[186:187]
	v_pk_add_f32 v[174:175], v[184:185], v[174:175]
	v_pk_add_f32 v[176:177], v[176:177], v[206:207]
	v_mov_b32_e32 v184, v204
	v_mov_b32_e32 v185, v202
	v_mov_b32_e32 v202, v205
	v_pk_add_f32 v[184:185], v[184:185], v[202:203]
	v_mov_b32_e32 v186, v176
	v_mov_b32_e32 v187, v182
	v_mov_b32_e32 v182, v177
	v_pk_add_f32 v[176:177], v[186:187], v[182:183]
	v_mov_b32_e32 v182, v185
	v_mov_b32_e32 v183, v175
	v_pk_add_f32 v[176:177], v[176:177], v[182:183]
	v_mov_b32_e32 v185, v174
	v_pk_add_f32 v[174:175], v[184:185], v[176:177]
	v_mov_b64_e32 v[186:187], s[6:7]
	v_pk_fma_f32 v[176:177], v[174:175], s[42:43], v[186:187] op_sel_hi:[1,0,0]
	v_mov_b32_e32 v182, v139
	v_mul_f32_e32 v174, 0x4b800000, v177
	v_cmp_gt_f32_e64 s[6:7], s85, v177
	v_mov_b32_e32 v183, v140
	v_mov_b32_e32 v139, v141
	v_mov_b32_e32 v140, v136
	v_mov_b32_e32 v141, v134
	v_mov_b32_e32 v134, v137
	v_mov_b32_e32 v136, v143
	v_mov_b32_e32 v137, v144
	v_mov_b32_e32 v143, v145
	v_cndmask_b32_e64 v174, v177, v174, s[6:7]
	v_pk_add_f32 v[138:139], v[182:183], v[138:139]
	v_pk_add_f32 v[134:135], v[140:141], v[134:135]
	v_pk_add_f32 v[136:137], v[136:137], v[142:143]
	v_mov_b32_e32 v140, v132
	v_mov_b32_e32 v141, v130
	v_mov_b32_e32 v130, v133
	v_rsq_f32_e32 v174, v174
	v_pk_add_f32 v[130:131], v[140:141], v[130:131]
	v_mov_b32_e32 v132, v136
	v_mov_b32_e32 v133, v138
	v_mov_b32_e32 v138, v137
	v_pk_add_f32 v[132:133], v[132:133], v[138:139]
	v_mov_b32_e32 v136, v131
	v_mov_b32_e32 v137, v135
	v_pk_add_f32 v[132:133], v[132:133], v[136:137]
	v_mov_b32_e32 v131, v134
	v_pk_add_f32 v[130:131], v[130:131], v[132:133]
	v_mul_f32_e32 v175, 0x45800000, v174
	v_pk_fma_f32 v[130:131], v[130:131], s[42:43], v[186:187] op_sel_hi:[1,0,0]
	v_cmp_gt_f32_e32 vcc, s85, v176
	v_cndmask_b32_e64 v174, v174, v175, s[6:7]
	v_mul_f32_e32 v175, 0x4b800000, v176
	v_mul_f32_e32 v132, 0x4b800000, v131
	v_cmp_gt_f32_e64 s[6:7], s85, v131
	v_cndmask_b32_e32 v175, v176, v175, vcc
	v_rsq_f32_e32 v175, v175
	v_cndmask_b32_e64 v131, v131, v132, s[6:7]
	v_rsq_f32_e32 v131, v131
	v_mul_f32_e32 v176, 0x45800000, v175
	v_cndmask_b32_e32 v176, v175, v176, vcc
	v_mul_f32_e32 v132, 0x45800000, v131
	v_cmp_gt_f32_e32 vcc, s85, v130
	v_cndmask_b32_e64 v138, v131, v132, s[6:7]
	v_mul_f32_e32 v131, 0x4b800000, v130
	v_cndmask_b32_e32 v130, v130, v131, vcc
	v_rsq_f32_e32 v130, v130
	v_pk_mul_f32 v[132:133], v[128:129], v[174:175] op_sel_hi:[1,0]
	v_pk_mul_f32 v[134:135], v[124:125], v[174:175] op_sel_hi:[1,0]
	v_pk_mul_f32 v[136:137], v[122:123], v[174:175] op_sel_hi:[1,0]
	v_mul_f32_e32 v131, 0x45800000, v130
	v_cndmask_b32_e32 v140, v130, v131, vcc
	v_pk_mul_f32 v[130:131], v[126:127], v[174:175] op_sel_hi:[1,0]
	v_pk_mul_f32 v[142:143], v[92:93], v[174:175] op_sel_hi:[1,0]
	v_cvt_pk_bf16_f32 v130, v130, v131
	v_cvt_pk_bf16_f32 v131, v132, v133
	v_cvt_pk_bf16_f32 v132, v136, v137
	v_cvt_pk_bf16_f32 v133, v134, v135
	v_pk_mul_f32 v[136:137], v[96:97], v[174:175] op_sel_hi:[1,0]
	v_pk_mul_f32 v[134:135], v[94:95], v[174:175] op_sel_hi:[1,0]
	v_pk_mul_f32 v[144:145], v[90:91], v[174:175] op_sel_hi:[1,0]
	v_cvt_pk_bf16_f32 v134, v134, v135
	v_cvt_pk_bf16_f32 v135, v136, v137
	v_cvt_pk_bf16_f32 v136, v144, v145
	v_cvt_pk_bf16_f32 v137, v142, v143
	s_mov_b64 s[6:7], -1
	s_cbranch_scc1 .LBB0_575
; __device__ __forceinline__ unsigned cvt_pk_bf16(float lo, float hi) { const f32x2_t v = {lo, hi}; return __builtin_bit_cast(unsigned, __builtin_convertvector(v, bf16x2_t)); }
;     __device__ __forceinline__ void operator()(f32x4 (&acc)[2][2][4][2], const Unit& u, int wr, int wc, int fr, int fq) const {
;     ...
;             } else {
; #pragma unroll
;                 for (int m = 0; m < 4; ++m)
; #pragma unroll
;                     for (int bj = 0; bj < 2; ++bj) { const int c0 = u.pn * BM + bj * HALF + wc * 32 + 8 * fq; const f32x4 v0 = acc[ai][bj][m][0] * rstd[m], v1 = acc[ai][bj][m][1] * rstd[m];
;                         u32x4 w; w.x = cvt_pk_bf16(v0[0], v0[1]); w.y = cvt_pk_bf16(v0[2], v0[3]); w.z = cvt_pk_bf16(v1[0], v1[1]); w.w = cvt_pk_bf16(v1[2], v1[3]);
;                         *(u32x4*)(VM + (size_t)(row0 + ai * HALF + m * 16) * 1024 + (c0 - 1024)) = w; }
;             }
	v_lshlrev_b64 v[142:143], 11, v[164:165]
	v_lshl_add_u64 v[142:143], s[24:25], 0, v[142:143]
	v_lshlrev_b64 v[174:175], 1, v[178:179]
	v_lshl_add_u64 v[142:143], v[142:143], 0, v[174:175]
	v_lshlrev_b64 v[182:183], 11, v[168:169]
	global_store_dwordx4 v[142:143], v[130:133], off offset:-2048
	global_store_dwordx4 v[142:143], v[134:137], off offset:-1792
	v_pk_mul_f32 v[144:145], v[120:121], v[176:177] op_sel_hi:[1,0]
	v_pk_mul_f32 v[142:143], v[118:119], v[176:177] op_sel_hi:[1,0]
	v_pk_mul_f32 v[184:185], v[116:117], v[176:177] op_sel_hi:[1,0]
	v_pk_mul_f32 v[186:187], v[114:115], v[176:177] op_sel_hi:[1,0]
	v_lshl_add_u64 v[182:183], s[24:25], 0, v[182:183]
	v_cvt_pk_bf16_f32 v142, v142, v143
	v_cvt_pk_bf16_f32 v143, v144, v145
	v_cvt_pk_bf16_f32 v144, v186, v187
	v_cvt_pk_bf16_f32 v145, v184, v185
	v_lshl_add_u64 v[182:183], v[182:183], 0, v[174:175]
	global_store_dwordx4 v[182:183], v[142:145], off offset:-2048
	v_pk_mul_f32 v[184:185], v[84:85], v[176:177] op_sel_hi:[1,0]
	v_pk_mul_f32 v[186:187], v[82:83], v[176:177] op_sel_hi:[1,0]
	v_pk_mul_f32 v[144:145], v[88:89], v[176:177] op_sel_hi:[1,0]
	v_pk_mul_f32 v[142:143], v[86:87], v[176:177] op_sel_hi:[1,0]
	s_mov_b64 s[6:7], 0
	v_cvt_pk_bf16_f32 v142, v142, v143
	v_cvt_pk_bf16_f32 v143, v144, v145
	v_cvt_pk_bf16_f32 v144, v186, v187
	v_cvt_pk_bf16_f32 v145, v184, v185
	global_store_dwordx4 v[182:183], v[142:145], off offset:-1792
	v_lshlrev_b64 v[182:183], 11, v[166:167]
	v_pk_mul_f32 v[184:185], v[108:109], v[138:139] op_sel_hi:[1,0]
	v_pk_mul_f32 v[144:145], v[112:113], v[138:139] op_sel_hi:[1,0]
	v_pk_mul_f32 v[142:143], v[110:111], v[138:139] op_sel_hi:[1,0]
	v_pk_mul_f32 v[186:187], v[106:107], v[138:139] op_sel_hi:[1,0]
	v_lshl_add_u64 v[182:183], s[24:25], 0, v[182:183]
	v_cvt_pk_bf16_f32 v142, v142, v143
	v_cvt_pk_bf16_f32 v143, v144, v145
	v_cvt_pk_bf16_f32 v144, v186, v187
	v_cvt_pk_bf16_f32 v145, v184, v185
	v_lshl_add_u64 v[182:183], v[182:183], 0, v[174:175]
	global_store_dwordx4 v[182:183], v[142:145], off offset:-2048
	v_pk_mul_f32 v[184:185], v[76:77], v[138:139] op_sel_hi:[1,0]
	v_pk_mul_f32 v[186:187], v[74:75], v[138:139] op_sel_hi:[1,0]
	v_pk_mul_f32 v[144:145], v[80:81], v[138:139] op_sel_hi:[1,0]
	v_pk_mul_f32 v[142:143], v[78:79], v[138:139] op_sel_hi:[1,0]
	s_nop 0
	v_cvt_pk_bf16_f32 v142, v142, v143
	v_cvt_pk_bf16_f32 v143, v144, v145
	v_cvt_pk_bf16_f32 v144, v186, v187
	v_cvt_pk_bf16_f32 v145, v184, v185
	global_store_dwordx4 v[182:183], v[142:145], off offset:-1792
	v_lshlrev_b64 v[182:183], 11, v[170:171]
	v_pk_mul_f32 v[184:185], v[100:101], v[140:141] op_sel_hi:[1,0]
	v_pk_mul_f32 v[144:145], v[104:105], v[140:141] op_sel_hi:[1,0]
	v_pk_mul_f32 v[142:143], v[102:103], v[140:141] op_sel_hi:[1,0]
	v_pk_mul_f32 v[186:187], v[98:99], v[140:141] op_sel_hi:[1,0]
	v_lshl_add_u64 v[182:183], s[24:25], 0, v[182:183]
	v_cvt_pk_bf16_f32 v142, v142, v143
	v_cvt_pk_bf16_f32 v143, v144, v145
	v_cvt_pk_bf16_f32 v144, v186, v187
	v_cvt_pk_bf16_f32 v145, v184, v185
	v_lshl_add_u64 v[174:175], v[182:183], 0, v[174:175]
	global_store_dwordx4 v[174:175], v[142:145], off offset:-2048
	v_pk_mul_f32 v[182:183], v[68:69], v[140:141] op_sel_hi:[1,0]
	v_pk_mul_f32 v[184:185], v[66:67], v[140:141] op_sel_hi:[1,0]
	v_pk_mul_f32 v[144:145], v[72:73], v[140:141] op_sel_hi:[1,0]
	v_pk_mul_f32 v[142:143], v[70:71], v[140:141] op_sel_hi:[1,0]
	s_nop 0
	v_cvt_pk_bf16_f32 v142, v142, v143
	v_cvt_pk_bf16_f32 v143, v144, v145
	v_cvt_pk_bf16_f32 v144, v184, v185
	v_cvt_pk_bf16_f32 v145, v182, v183
	global_store_dwordx4 v[174:175], v[142:145], off offset:-1792

; #define PG8_STAGE(bufoff, gbase, voff) do { _Pragma("unroll") for (int _i = 0; _i < 2; ++_i) \
;         __builtin_amdgcn_global_load_lds((const unsigned*)((const char*)(gbase) + (voff)[_i]), (LAS unsigned*)(lds + (bufoff) + ldsw + _i * 8192), 16, 0, 0); } while (0)
; #define PG8_LDA(dst, b, h) do { _Pragma("unroll") for (int m = 0; m < 4; ++m) _Pragma("unroll") for (int k = 0; k < 2; ++k) dst[m][k] = *(const LAS bf16x8*)(lds + PG8_SA(b, h) + aoff + m * 2048 + k * 1024); } while (0)
; #define PG8_WAIT_V(n) asm volatile("s_waitcnt vmcnt(" #n ")" ::: "memory")
; template <class Epi, class Sched>
; __device__ __forceinline__ void gemm_phase(LAS unsigned char* lds, const Gemm g, const Sched& S, const Epi& E) {
;     ...
;         for (int t = 0; t < ntu; t += 2) {
;             const bool last = (t == ntu - 2);
;             const char* a1 = cA + (size_t)(t + 1) * kstep;
;             const char* a2 = last ? nA : cA + (size_t)(t + 2) * kstep; const char* b2 = last ? nB : cB + (size_t)(t + 2) * kstep;
;             const char* a3 = a2 + kstep; const char* b3 = b2 + kstep;
;             if (last && has_next) S.a_ready(nxt);
;             PG8_LDB(B0, 0, 0); PG8_SCHED; PG8_LDA(At, 0, 0); PG8_STAGE(PG8_SA(1, 1), a1 + hstepA, voffA);
;             PG8_WAIT_L(8); PG8_BAR; PG8_WAIT_L(0); PG8_MMA(0, 0, At, B0); PG8_BAR; PG8_SCHED;
;             PG8_LDB(B1, 0, 1); PG8_STAGE(PG8_SB(0, 0), b2, voffB);
;             PG8_BAR; PG8_WAIT_L(0); PG8_MMA(0, 1, At, B1); PG8_BAR;
;             PG8_LDA(At, 0, 1); PG8_STAGE(PG8_SA(0, 0), a2, voffA);
;             PG8_BAR; PG8_WAIT_L(0); PG8_MMA(1, 0, At, B0); PG8_BAR; PG8_SCHED;
;             PG8_STAGE(PG8_SB(0, 1), b2 + hstepB, voffB);
;             PG8_WAIT_V(6); PG8_BAR; PG8_MMA(1, 1, At, B1); PG8_BAR;
;             PG8_LDB(B0, 1, 0); PG8_SCHED; PG8_LDA(At, 1, 0); PG8_STAGE(PG8_SA(0, 1), a2 + hstepA, voffA);
;             PG8_WAIT_L(8); PG8_BAR; PG8_WAIT_L(0); PG8_MMA(0, 0, At, B0); PG8_BAR; PG8_SCHED;
;             PG8_LDB(B1, 1, 1); PG8_STAGE(PG8_SB(1, 0), b3, voffB);
;             PG8_BAR; PG8_WAIT_L(0); PG8_MMA(0, 1, At, B1); PG8_BAR;
;             PG8_LDA(At, 1, 1); PG8_STAGE(PG8_SA(1, 0), a3, voffA);
;             PG8_BAR; PG8_WAIT_L(0); PG8_MMA(1, 0, At, B0); PG8_BAR; PG8_SCHED;
;             PG8_STAGE(PG8_SB(1, 1), b3 + hstepB, voffB);
;             PG8_WAIT_V(6); PG8_BAR; PG8_MMA(1, 1, At, B1); PG8_BAR;
.LBB0_871:
	s_add_i32 s63, s28, 2
	s_add_u32 s6, s68, 0xfffc0080
	s_addc_u32 s7, s69, -1
	s_add_i32 s35, 0, 0x10000
	v_add_u32_e32 v1, s35, v207
	ds_read_b128 v[130:133], v1
	ds_read_b128 v[134:137], v1 offset:1024
	ds_read_b128 v[138:141], v1 offset:2048
	ds_read_b128 v[142:145], v1 offset:3072
	s_cmp_eq_u32 s23, s28
	s_cselect_b32 s28, s24, s6
	s_cselect_b32 s29, s25, s7
	s_cselect_b32 s27, s13, s59
	s_cselect_b32 s26, s21, s55
	ds_read_b128 v[146:149], v209
	ds_read_b128 v[150:153], v209 offset:1024
	ds_read_b128 v[154:157], v209 offset:2048
	ds_read_b128 v[158:161], v209 offset:3072
	ds_read_b128 v[162:165], v209 offset:4096
	ds_read_b128 v[182:185], v209 offset:5120
	ds_read_b128 v[192:195], v209 offset:6144
	ds_read_b128 v[196:199], v209 offset:7168
	s_add_u32 s98, s68, 0xfffc0000
	s_addc_u32 s99, s69, -1
	s_mov_b32 m0, s76
	s_nop 0
	global_load_lds_dwordx4 v188, s[98:99]
	s_mov_b32 m0, s77
	s_nop 0
	global_load_lds_dwordx4 v190, s[98:99]
	s_add_i32 m0, s79, 0xc000
	s_nop 0
	global_load_lds_dwordx4 v188, s[68:69]
	s_add_i32 m0, s79, 0xe000
	s_nop 0
	global_load_lds_dwordx4 v190, s[68:69]
	s_add_i32 s37, 0, 0x14000
	v_add_u32_e32 v1, s37, v207
	ds_read_b128 v[200:203], v1
	ds_read_b128 v[210:213], v1 offset:1024
	ds_read_b128 v[214:217], v1 offset:2048
	ds_read_b128 v[218:221], v1 offset:3072
	s_waitcnt lgkmcnt(0)
	s_barrier
	v_mfma_f32_16x16x32_bf16 v[126:129], v[130:133], v[146:149], v[126:129]
	v_mfma_f32_16x16x32_bf16 v[126:129], v[134:137], v[150:153], v[126:129]
	v_mfma_f32_16x16x32_bf16 v[118:121], v[130:133], v[154:157], v[118:121]
	v_mfma_f32_16x16x32_bf16 v[118:121], v[134:137], v[158:161], v[118:121]
	v_mfma_f32_16x16x32_bf16 v[110:113], v[130:133], v[162:165], v[110:113]
	v_mfma_f32_16x16x32_bf16 v[110:113], v[134:137], v[182:185], v[110:113]
	v_mfma_f32_16x16x32_bf16 v[102:105], v[130:133], v[192:195], v[102:105]
	v_mfma_f32_16x16x32_bf16 v[102:105], v[134:137], v[196:199], v[102:105]
	v_mfma_f32_16x16x32_bf16 v[122:125], v[138:141], v[146:149], v[122:125]
	v_mfma_f32_16x16x32_bf16 v[122:125], v[142:145], v[150:153], v[122:125]
	v_mfma_f32_16x16x32_bf16 v[114:117], v[138:141], v[154:157], v[114:117]
	v_mfma_f32_16x16x32_bf16 v[114:117], v[142:145], v[158:161], v[114:117]
	v_mfma_f32_16x16x32_bf16 v[106:109], v[138:141], v[162:165], v[106:109]
	v_mfma_f32_16x16x32_bf16 v[106:109], v[142:145], v[182:185], v[106:109]
	v_mfma_f32_16x16x32_bf16 v[98:101], v[138:141], v[192:195], v[98:101]
	v_mfma_f32_16x16x32_bf16 v[98:101], v[142:145], v[196:199], v[98:101]
	v_mfma_f32_16x16x32_bf16 v[94:97], v[200:203], v[146:149], v[94:97]
	v_mfma_f32_16x16x32_bf16 v[94:97], v[210:213], v[150:153], v[94:97]
	v_mfma_f32_16x16x32_bf16 v[86:89], v[200:203], v[154:157], v[86:89]
	v_mfma_f32_16x16x32_bf16 v[86:89], v[210:213], v[158:161], v[86:89]
	v_mfma_f32_16x16x32_bf16 v[78:81], v[200:203], v[162:165], v[78:81]
	v_mfma_f32_16x16x32_bf16 v[78:81], v[210:213], v[182:185], v[78:81]
	v_mfma_f32_16x16x32_bf16 v[70:73], v[200:203], v[192:195], v[70:73]
	v_mfma_f32_16x16x32_bf16 v[70:73], v[210:213], v[196:199], v[70:73]
	v_mfma_f32_16x16x32_bf16 v[90:93], v[214:217], v[146:149], v[90:93]
	v_mfma_f32_16x16x32_bf16 v[90:93], v[218:221], v[150:153], v[90:93]
	v_mfma_f32_16x16x32_bf16 v[82:85], v[214:217], v[154:157], v[82:85]
	v_mfma_f32_16x16x32_bf16 v[82:85], v[218:221], v[158:161], v[82:85]
	v_mfma_f32_16x16x32_bf16 v[74:77], v[214:217], v[162:165], v[74:77]
	v_mfma_f32_16x16x32_bf16 v[74:77], v[218:221], v[182:185], v[74:77]
	v_mfma_f32_16x16x32_bf16 v[66:69], v[214:217], v[192:195], v[66:69]
	v_mfma_f32_16x16x32_bf16 v[66:69], v[218:221], v[196:199], v[66:69]
	s_barrier
	ds_read_b128 v[146:149], v209 offset:16384
	ds_read_b128 v[150:153], v209 offset:17408
	ds_read_b128 v[154:157], v209 offset:18432
	ds_read_b128 v[158:161], v209 offset:19456
	ds_read_b128 v[162:165], v209 offset:20480
	ds_read_b128 v[182:185], v209 offset:21504
	ds_read_b128 v[192:195], v209 offset:22528
	ds_read_b128 v[196:199], v209 offset:23552
	s_add_i32 s6, s35, s89
	s_mov_b32 m0, s6
	s_nop 0
	global_load_lds_dwordx4 v178, s[26:27]
	s_add_i32 m0, s6, 0x2000
	s_nop 0
	global_load_lds_dwordx4 v172, s[26:27]
	s_add_u32 s6, s26, 0x40000
	s_addc_u32 s7, s27, 0
	s_add_i32 s35, s37, s89
	s_mov_b32 m0, s35
	s_nop 0
	global_load_lds_dwordx4 v178, s[6:7]
	s_add_i32 m0, s35, 0x2000
	s_nop 0
	global_load_lds_dwordx4 v172, s[6:7]
	s_waitcnt vmcnt(4)
	s_waitcnt lgkmcnt(0)
	s_barrier
	v_mfma_f32_16x16x32_bf16 v[62:65], v[130:133], v[146:149], v[62:65]
	v_mfma_f32_16x16x32_bf16 v[62:65], v[134:137], v[150:153], v[62:65]
	v_mfma_f32_16x16x32_bf16 v[54:57], v[130:133], v[154:157], v[54:57]
	v_mfma_f32_16x16x32_bf16 v[54:57], v[134:137], v[158:161], v[54:57]
	v_mfma_f32_16x16x32_bf16 v[46:49], v[130:133], v[162:165], v[46:49]
	v_mfma_f32_16x16x32_bf16 v[46:49], v[134:137], v[182:185], v[46:49]
	v_mfma_f32_16x16x32_bf16 v[38:41], v[130:133], v[192:195], v[38:41]
	v_mfma_f32_16x16x32_bf16 v[38:41], v[134:137], v[196:199], v[38:41]
	v_mfma_f32_16x16x32_bf16 v[58:61], v[138:141], v[146:149], v[58:61]
	v_mfma_f32_16x16x32_bf16 v[58:61], v[142:145], v[150:153], v[58:61]
	v_mfma_f32_16x16x32_bf16 v[50:53], v[138:141], v[154:157], v[50:53]
	v_mfma_f32_16x16x32_bf16 v[50:53], v[142:145], v[158:161], v[50:53]
	v_mfma_f32_16x16x32_bf16 v[42:45], v[138:141], v[162:165], v[42:45]
	v_mfma_f32_16x16x32_bf16 v[42:45], v[142:145], v[182:185], v[42:45]
	v_mfma_f32_16x16x32_bf16 v[34:37], v[138:141], v[192:195], v[34:37]
	v_mfma_f32_16x16x32_bf16 v[34:37], v[142:145], v[196:199], v[34:37]
	v_mfma_f32_16x16x32_bf16 v[30:33], v[200:203], v[146:149], v[30:33]
	v_mfma_f32_16x16x32_bf16 v[30:33], v[210:213], v[150:153], v[30:33]
	v_mfma_f32_16x16x32_bf16 v[22:25], v[200:203], v[154:157], v[22:25]
	v_mfma_f32_16x16x32_bf16 v[22:25], v[210:213], v[158:161], v[22:25]
	v_mfma_f32_16x16x32_bf16 v[14:17], v[200:203], v[162:165], v[14:17]
	v_mfma_f32_16x16x32_bf16 v[14:17], v[210:213], v[182:185], v[14:17]
	v_mfma_f32_16x16x32_bf16 v[6:9], v[200:203], v[192:195], v[6:9]
	v_mfma_f32_16x16x32_bf16 v[6:9], v[210:213], v[196:199], v[6:9]
	v_mfma_f32_16x16x32_bf16 v[26:29], v[214:217], v[146:149], v[26:29]
	v_mfma_f32_16x16x32_bf16 v[26:29], v[218:221], v[150:153], v[26:29]
	v_mfma_f32_16x16x32_bf16 v[18:21], v[214:217], v[154:157], v[18:21]
	v_mfma_f32_16x16x32_bf16 v[18:21], v[218:221], v[158:161], v[18:21]
	v_mfma_f32_16x16x32_bf16 v[10:13], v[214:217], v[162:165], v[10:13]
	v_mfma_f32_16x16x32_bf16 v[10:13], v[218:221], v[182:185], v[10:13]
	v_mfma_f32_16x16x32_bf16 v[2:5], v[214:217], v[192:195], v[2:5]
	v_mfma_f32_16x16x32_bf16 v[2:5], v[218:221], v[196:199], v[2:5]
	s_add_i32 s35, 0, 0x18000
	v_add_u32_e32 v1, s35, v207
	s_barrier
; #define PG8_STAGE(bufoff, gbase, voff) do { _Pragma("unroll") for (int _i = 0; _i < 2; ++_i) \
;         __builtin_amdgcn_global_load_lds((const unsigned*)((const char*)(gbase) + (voff)[_i]), (LAS unsigned*)(lds + (bufoff) + ldsw + _i * 8192), 16, 0, 0); } while (0)
; #define PG8_LDA(dst, b, h) do { _Pragma("unroll") for (int m = 0; m < 4; ++m) _Pragma("unroll") for (int k = 0; k < 2; ++k) dst[m][k] = *(const LAS bf16x8*)(lds + PG8_SA(b, h) + aoff + m * 2048 + k * 1024); } while (0)
; #define PG8_LDB(dst, b, h) do { _Pragma("unroll") for (int n = 0; n < 2; ++n) _Pragma("unroll") for (int k = 0; k < 2; ++k) dst[n][k] = *(const LAS bf16x8*)(lds + PG8_SB(b, h) + boff + n * 2048 + k * 1024); } while (0)
; #define PG8_WAIT_V(n) asm volatile("s_waitcnt vmcnt(" #n ")" ::: "memory")
; #define PG8_WAIT_L(n) asm volatile("s_waitcnt lgkmcnt(" #n ")" ::: "memory")
; #define PG8_BAR __builtin_amdgcn_s_barrier()
; #define PG8_SCHED __builtin_amdgcn_sched_barrier(0)
; template <class Epi, class Sched>
; __device__ __forceinline__ void gemm_phase(LAS unsigned char* lds, const Gemm g, const Sched& S, const Epi& E) {
;     ...
;             PG8_LDB(B0, 0, 0); PG8_SCHED; PG8_LDA(At, 0, 0); PG8_STAGE(PG8_SA(1, 1), a1 + hstepA, voffA);
;             PG8_WAIT_L(8); PG8_BAR; PG8_WAIT_L(0); PG8_MMA(0, 0, At, B0); PG8_BAR; PG8_SCHED;
;             PG8_LDB(B1, 0, 1); PG8_STAGE(PG8_SB(0, 0), b2, voffB);
;             PG8_BAR; PG8_WAIT_L(0); PG8_MMA(0, 1, At, B1); PG8_BAR;
;             PG8_LDA(At, 0, 1); PG8_STAGE(PG8_SA(0, 0), a2, voffA);
;             PG8_BAR; PG8_WAIT_L(0); PG8_MMA(1, 0, At, B0); PG8_BAR; PG8_SCHED;
;             PG8_STAGE(PG8_SB(0, 1), b2 + hstepB, voffB);
;             PG8_WAIT_V(6); PG8_BAR; PG8_MMA(1, 1, At, B1); PG8_BAR;
;             PG8_LDB(B0, 1, 0); PG8_SCHED; PG8_LDA(At, 1, 0); PG8_STAGE(PG8_SA(0, 1), a2 + hstepA, voffA);
;             PG8_WAIT_L(8); PG8_BAR; PG8_WAIT_L(0); PG8_MMA(0, 0, At, B0); PG8_BAR; PG8_SCHED;
;             PG8_LDB(B1, 1, 1); PG8_STAGE(PG8_SB(1, 0), b3, voffB);
;             PG8_BAR; PG8_WAIT_L(0); PG8_MMA(0, 1, At, B1); PG8_BAR;
;             PG8_LDA(At, 1, 1); PG8_STAGE(PG8_SA(1, 0), a3, voffA);
;             PG8_BAR; PG8_WAIT_L(0); PG8_MMA(1, 0, At, B0); PG8_BAR; PG8_SCHED;
;             PG8_STAGE(PG8_SB(1, 1), b3 + hstepB, voffB);
;             PG8_WAIT_V(6); PG8_BAR; PG8_MMA(1, 1, At, B1); PG8_BAR;
;         }
	ds_read_b128 v[130:133], v1
	ds_read_b128 v[134:137], v1 offset:1024
	ds_read_b128 v[138:141], v1 offset:2048
	ds_read_b128 v[142:145], v1 offset:3072
	ds_read_b128 v[146:149], v209 offset:32768
	ds_read_b128 v[150:153], v209 offset:33792
	ds_read_b128 v[154:157], v209 offset:34816
	ds_read_b128 v[158:161], v209 offset:35840
	ds_read_b128 v[162:165], v209 offset:36864
	ds_read_b128 v[182:185], v209 offset:37888
	ds_read_b128 v[192:195], v209 offset:38912
	ds_read_b128 v[196:199], v209 offset:39936
	s_mov_b32 m0, s79
	s_nop 0
	global_load_lds_dwordx4 v168, s[28:29]
	s_mov_b32 m0, s46
	s_nop 0
	global_load_lds_dwordx4 v170, s[28:29]
	s_add_u32 s6, s28, 0x40000
	s_addc_u32 s7, s29, 0
	s_mov_b32 m0, s33
	s_nop 0
	global_load_lds_dwordx4 v168, s[6:7]
	s_mov_b32 m0, s83
	s_nop 0
	global_load_lds_dwordx4 v170, s[6:7]
	s_add_i32 s28, 0, 0x1c000
	v_add_u32_e32 v1, s28, v207
	ds_read_b128 v[200:203], v1
	ds_read_b128 v[210:213], v1 offset:1024
	ds_read_b128 v[214:217], v1 offset:2048
	ds_read_b128 v[218:221], v1 offset:3072
	s_waitcnt lgkmcnt(0)
	s_barrier
	v_mfma_f32_16x16x32_bf16 v[126:129], v[130:133], v[146:149], v[126:129]
	v_mfma_f32_16x16x32_bf16 v[126:129], v[134:137], v[150:153], v[126:129]
	v_mfma_f32_16x16x32_bf16 v[118:121], v[130:133], v[154:157], v[118:121]
	v_mfma_f32_16x16x32_bf16 v[118:121], v[134:137], v[158:161], v[118:121]
	v_mfma_f32_16x16x32_bf16 v[110:113], v[130:133], v[162:165], v[110:113]
	v_mfma_f32_16x16x32_bf16 v[110:113], v[134:137], v[182:185], v[110:113]
	v_mfma_f32_16x16x32_bf16 v[102:105], v[130:133], v[192:195], v[102:105]
	v_mfma_f32_16x16x32_bf16 v[102:105], v[134:137], v[196:199], v[102:105]
	v_mfma_f32_16x16x32_bf16 v[122:125], v[138:141], v[146:149], v[122:125]
	v_mfma_f32_16x16x32_bf16 v[122:125], v[142:145], v[150:153], v[122:125]
	v_mfma_f32_16x16x32_bf16 v[114:117], v[138:141], v[154:157], v[114:117]
	v_mfma_f32_16x16x32_bf16 v[114:117], v[142:145], v[158:161], v[114:117]
	v_mfma_f32_16x16x32_bf16 v[106:109], v[138:141], v[162:165], v[106:109]
	v_mfma_f32_16x16x32_bf16 v[106:109], v[142:145], v[182:185], v[106:109]
	v_mfma_f32_16x16x32_bf16 v[98:101], v[138:141], v[192:195], v[98:101]
	v_mfma_f32_16x16x32_bf16 v[98:101], v[142:145], v[196:199], v[98:101]
	v_mfma_f32_16x16x32_bf16 v[94:97], v[200:203], v[146:149], v[94:97]
	v_mfma_f32_16x16x32_bf16 v[94:97], v[210:213], v[150:153], v[94:97]
	v_mfma_f32_16x16x32_bf16 v[86:89], v[200:203], v[154:157], v[86:89]
	v_mfma_f32_16x16x32_bf16 v[86:89], v[210:213], v[158:161], v[86:89]
	v_mfma_f32_16x16x32_bf16 v[78:81], v[200:203], v[162:165], v[78:81]
	v_mfma_f32_16x16x32_bf16 v[78:81], v[210:213], v[182:185], v[78:81]
	v_mfma_f32_16x16x32_bf16 v[70:73], v[200:203], v[192:195], v[70:73]
	v_mfma_f32_16x16x32_bf16 v[70:73], v[210:213], v[196:199], v[70:73]
	v_mfma_f32_16x16x32_bf16 v[90:93], v[214:217], v[146:149], v[90:93]
	v_mfma_f32_16x16x32_bf16 v[90:93], v[218:221], v[150:153], v[90:93]
	v_mfma_f32_16x16x32_bf16 v[82:85], v[214:217], v[154:157], v[82:85]
	v_mfma_f32_16x16x32_bf16 v[82:85], v[218:221], v[158:161], v[82:85]
	v_mfma_f32_16x16x32_bf16 v[74:77], v[214:217], v[162:165], v[74:77]
	v_mfma_f32_16x16x32_bf16 v[74:77], v[218:221], v[182:185], v[74:77]
	v_mfma_f32_16x16x32_bf16 v[66:69], v[214:217], v[192:195], v[66:69]
	v_mfma_f32_16x16x32_bf16 v[66:69], v[218:221], v[196:199], v[66:69]
	s_barrier
	ds_read_b128 v[146:149], v209 offset:49152
	ds_read_b128 v[150:153], v209 offset:50176
	ds_read_b128 v[154:157], v209 offset:51200
	ds_read_b128 v[158:161], v209 offset:52224
	ds_read_b128 v[162:165], v209 offset:53248
	ds_read_b128 v[182:185], v209 offset:54272
	ds_read_b128 v[192:195], v209 offset:55296
	ds_read_b128 v[196:199], v209 offset:56320
	s_add_u32 s98, s26, 0x80
	s_addc_u32 s99, s27, 0
	s_add_i32 s6, s35, s89
	s_mov_b32 m0, s6
	s_nop 0
	global_load_lds_dwordx4 v178, s[98:99]
	s_add_i32 m0, s6, 0x2000
	s_nop 0
	global_load_lds_dwordx4 v172, s[98:99]
	s_add_u32 s6, s26, 0x40080
	s_addc_u32 s7, s27, 0
	s_add_i32 s26, s28, s89
	s_mov_b32 m0, s26
	s_nop 0
	global_load_lds_dwordx4 v178, s[6:7]
	s_add_i32 m0, s26, 0x2000
	s_nop 0
	global_load_lds_dwordx4 v172, s[6:7]
	s_waitcnt vmcnt(4)
	s_waitcnt lgkmcnt(0)
	s_barrier
	v_mfma_f32_16x16x32_bf16 v[62:65], v[130:133], v[146:149], v[62:65]
	v_mfma_f32_16x16x32_bf16 v[62:65], v[134:137], v[150:153], v[62:65]
	v_mfma_f32_16x16x32_bf16 v[54:57], v[130:133], v[154:157], v[54:57]
	v_mfma_f32_16x16x32_bf16 v[54:57], v[134:137], v[158:161], v[54:57]
	v_mfma_f32_16x16x32_bf16 v[46:49], v[130:133], v[162:165], v[46:49]
	v_mfma_f32_16x16x32_bf16 v[46:49], v[134:137], v[182:185], v[46:49]
	v_mfma_f32_16x16x32_bf16 v[38:41], v[130:133], v[192:195], v[38:41]
	v_mfma_f32_16x16x32_bf16 v[38:41], v[134:137], v[196:199], v[38:41]
	v_mfma_f32_16x16x32_bf16 v[58:61], v[138:141], v[146:149], v[58:61]
	v_mfma_f32_16x16x32_bf16 v[58:61], v[142:145], v[150:153], v[58:61]
	v_mfma_f32_16x16x32_bf16 v[50:53], v[138:141], v[154:157], v[50:53]
	v_mfma_f32_16x16x32_bf16 v[50:53], v[142:145], v[158:161], v[50:53]
	v_mfma_f32_16x16x32_bf16 v[42:45], v[138:141], v[162:165], v[42:45]
	v_mfma_f32_16x16x32_bf16 v[42:45], v[142:145], v[182:185], v[42:45]
	v_mfma_f32_16x16x32_bf16 v[34:37], v[138:141], v[192:195], v[34:37]
	v_mfma_f32_16x16x32_bf16 v[34:37], v[142:145], v[196:199], v[34:37]
	v_mfma_f32_16x16x32_bf16 v[30:33], v[200:203], v[146:149], v[30:33]
	v_mfma_f32_16x16x32_bf16 v[30:33], v[210:213], v[150:153], v[30:33]
	v_mfma_f32_16x16x32_bf16 v[22:25], v[200:203], v[154:157], v[22:25]
	v_mfma_f32_16x16x32_bf16 v[22:25], v[210:213], v[158:161], v[22:25]
	v_mfma_f32_16x16x32_bf16 v[14:17], v[200:203], v[162:165], v[14:17]
	v_mfma_f32_16x16x32_bf16 v[14:17], v[210:213], v[182:185], v[14:17]
	v_mfma_f32_16x16x32_bf16 v[6:9], v[200:203], v[192:195], v[6:9]
	v_mfma_f32_16x16x32_bf16 v[6:9], v[210:213], v[196:199], v[6:9]
	v_mfma_f32_16x16x32_bf16 v[26:29], v[214:217], v[146:149], v[26:29]
	v_mfma_f32_16x16x32_bf16 v[26:29], v[218:221], v[150:153], v[26:29]
	v_mfma_f32_16x16x32_bf16 v[18:21], v[214:217], v[154:157], v[18:21]
	v_mfma_f32_16x16x32_bf16 v[18:21], v[218:221], v[158:161], v[18:21]
	v_mfma_f32_16x16x32_bf16 v[10:13], v[214:217], v[162:165], v[10:13]
	v_mfma_f32_16x16x32_bf16 v[10:13], v[218:221], v[182:185], v[10:13]
	v_mfma_f32_16x16x32_bf16 v[2:5], v[214:217], v[192:195], v[2:5]
	v_mfma_f32_16x16x32_bf16 v[2:5], v[218:221], v[196:199], v[2:5]
	s_add_u32 s68, s68, 0x100
	s_addc_u32 s69, s69, 0
	s_add_u32 s55, s55, 0x100
	s_addc_u32 s59, s59, 0
	s_cmp_ge_i32 s63, s1
	s_mov_b32 s28, s63
	s_barrier
; __device__ __forceinline__ unsigned cvt_pk_bf16(float lo, float hi) { const f32x2_t v = {lo, hi}; return __builtin_bit_cast(unsigned, __builtin_convertvector(v, bf16x2_t)); }
;     __device__ __forceinline__ void operator()(f32x4 (&acc)[2][2][4][2], const Unit& u, int wr, int wc, int fr, int fq) const {
;     ...
;         if (u.nt) {
;             const int tile = (u.pm - 64) * 8 + u.pn, w = wr * 4 + wc;
;             const auto rsrc = __builtin_amdgcn_make_buffer_rsrc((void*)PM, 0, 96 * 131072, 0x00020000);
;             const unsigned pbase = (unsigned)(tile * 3) * 131072u + (unsigned)((w * 16 * 64 + fq * 16 + fr) * 16);
; #pragma unroll
;             for (int ai = 0; ai < 2; ++ai) {
;                 u32x4 ra[4][2];
; #pragma unroll
;                 for (int m = 0; m < 4; ++m)
; #pragma unroll
;                     for (int bj = 0; bj < 2; ++bj) ra[m][bj] = *(const u32x4*)(gl + (size_t)u.seg * 8 * 65536 + ((ai * 4 + m) * 2 + bj) * 512);
; #pragma unroll
;                 for (int m = 0; m < 4; ++m)
; #pragma unroll
;                     for (int bj = 0; bj < 2; ++bj) { float f[8]; unpack8(ra[m][bj], f);
;                         const f32x4 v0 = acc[ai][bj][m][0], v1 = acc[ai][bj][m][1];
;                         u32x4 wv; wv.x = cvt_pk_bf16(v0[0] * f[0], v0[1] * f[1]); wv.y = cvt_pk_bf16(v0[2] * f[2], v0[3] * f[3]); wv.z = cvt_pk_bf16(v1[0] * f[4], v1[1] * f[5]); wv.w = cvt_pk_bf16(v1[2] * f[6], v1[3] * f[7]);
;                         __builtin_amdgcn_raw_buffer_store_b128(wv, rsrc, pbase + (unsigned)u.seg * 131072u + (unsigned)(((ai * 4 + m) * 2 + bj) * 1024), 0,   16); }
	s_cbranch_scc0 .LBB0_871
	s_lshl_b64 s[6:7], s[66:67], 17
	v_lshl_add_u32 v210, s20, 8, v206
	v_lshl_or_b32 v194, s12, 8, v167
	v_lshl_add_u64 v[192:193], v[176:177], 0, s[6:7]
	s_andn2_b64 vcc, exec, vcc
	s_mov_b64 s[26:27], -1
	s_cbranch_vccnz .LBB0_880
	s_ashr_i32 s23, s22, 31
	s_lshl_b64 s[6:7], s[22:23], 20
	v_lshl_add_u64 v[158:159], v[192:193], 0, s[6:7]
	global_load_dwordx4 v[162:165], v[158:159], off
	global_load_dwordx4 v[154:157], v[158:159], off offset:1024
	global_load_dwordx4 v[150:153], v[158:159], off offset:2048
	global_load_dwordx4 v[146:149], v[158:159], off offset:3072
	v_add_co_u32_e32 v130, vcc, s48, v158
	s_movk_i32 s6, 0x2000
	s_nop 0
	v_addc_co_u32_e32 v131, vcc, 0, v159, vcc
	v_add_co_u32_e32 v160, vcc, s6, v158
	s_lshl_b32 s1, s20, 3
	s_nop 0
	v_addc_co_u32_e32 v161, vcc, 0, v159, vcc
	global_load_dwordx4 v[142:145], v[160:161], off offset:-4096
	global_load_dwordx4 v[138:141], v[130:131], off offset:1024
	global_load_dwordx4 v[134:137], v[130:131], off offset:2048
	s_nop 0
	global_load_dwordx4 v[130:133], v[130:131], off offset:3072
	s_add_i32 s1, s12, s1
	s_addk_i32 s1, 0xfe00
	s_mul_i32 s12, s1, 0x60000
	s_lshl_b32 s6, s22, 17
	s_add_i32 s12, s12, s6
	s_movk_i32 s6, 0x3000
	s_waitcnt vmcnt(0)
	v_lshlrev_b32_e32 v182, 16, v162
	v_and_b32_e32 v183, 0xffff0000, v162
	v_lshlrev_b32_e32 v162, 16, v163
	v_and_b32_e32 v163, 0xffff0000, v163
	v_pk_mul_f32 v[182:183], v[126:127], v[182:183]
	v_pk_mul_f32 v[162:163], v[128:129], v[162:163]
	v_cvt_pk_bf16_f32 v182, v182, v183
	v_cvt_pk_bf16_f32 v183, v162, v163
	v_lshlrev_b32_e32 v162, 16, v164
	v_and_b32_e32 v163, 0xffff0000, v164
	v_pk_mul_f32 v[162:163], v[122:123], v[162:163]
	v_lshlrev_b32_e32 v164, 16, v154
	v_cvt_pk_bf16_f32 v184, v162, v163
	v_lshlrev_b32_e32 v162, 16, v165
	v_and_b32_e32 v163, 0xffff0000, v165
	v_and_b32_e32 v165, 0xffff0000, v154
	v_pk_mul_f32 v[164:165], v[94:95], v[164:165]
	v_pk_mul_f32 v[162:163], v[124:125], v[162:163]
	v_cvt_pk_bf16_f32 v154, v164, v165
	v_lshlrev_b32_e32 v164, 16, v155
	v_and_b32_e32 v165, 0xffff0000, v155
	v_pk_mul_f32 v[164:165], v[96:97], v[164:165]
	v_cvt_pk_bf16_f32 v185, v162, v163
	v_cvt_pk_bf16_f32 v155, v164, v165
	v_lshlrev_b32_e32 v164, 16, v156
	v_and_b32_e32 v165, 0xffff0000, v156
	v_pk_mul_f32 v[164:165], v[90:91], v[164:165]
	v_add_u32_e32 v162, s12, v208
	v_cvt_pk_bf16_f32 v156, v164, v165
	v_lshlrev_b32_e32 v164, 16, v157
	v_and_b32_e32 v165, 0xffff0000, v157
	v_pk_mul_f32 v[164:165], v[92:93], v[164:165]
	v_add_u32_e32 v1, 0x1000, v162
	v_cvt_pk_bf16_f32 v157, v164, v165
	buffer_store_dwordx4 v[154:157], v162, s[16:19], 0 offen offset:1024 sc1
	buffer_store_dwordx4 v[182:185], v162, s[16:19], 0 offen sc1
	s_nop 0
	v_lshlrev_b32_e32 v154, 16, v150
	v_and_b32_e32 v155, 0xffff0000, v150
	v_pk_mul_f32 v[154:155], v[118:119], v[154:155]
	s_nop 0
	v_cvt_pk_bf16_f32 v150, v154, v155
	v_lshlrev_b32_e32 v154, 16, v151
	v_and_b32_e32 v155, 0xffff0000, v151
	v_pk_mul_f32 v[154:155], v[120:121], v[154:155]
	s_nop 0
	v_cvt_pk_bf16_f32 v151, v154, v155
	v_lshlrev_b32_e32 v154, 16, v152
	v_and_b32_e32 v155, 0xffff0000, v152
	v_pk_mul_f32 v[154:155], v[114:115], v[154:155]
	s_nop 0
	v_cvt_pk_bf16_f32 v152, v154, v155
	v_lshlrev_b32_e32 v154, 16, v153
	v_and_b32_e32 v155, 0xffff0000, v153
	v_pk_mul_f32 v[154:155], v[116:117], v[154:155]
	s_nop 0
	v_cvt_pk_bf16_f32 v153, v154, v155
	buffer_store_dwordx4 v[150:153], v162, s[16:19], 0 offen offset:2048 sc1
	s_nop 1
	v_lshlrev_b32_e32 v150, 16, v146
	v_and_b32_e32 v151, 0xffff0000, v146
	v_pk_mul_f32 v[150:151], v[86:87], v[150:151]
	s_nop 0
	v_cvt_pk_bf16_f32 v146, v150, v151
	v_lshlrev_b32_e32 v150, 16, v147
	v_and_b32_e32 v151, 0xffff0000, v147
	v_pk_mul_f32 v[150:151], v[88:89], v[150:151]
	s_nop 0
	v_cvt_pk_bf16_f32 v147, v150, v151
	v_lshlrev_b32_e32 v150, 16, v148
	v_and_b32_e32 v151, 0xffff0000, v148
	v_pk_mul_f32 v[150:151], v[82:83], v[150:151]
	s_nop 0
	v_cvt_pk_bf16_f32 v148, v150, v151
	v_lshlrev_b32_e32 v150, 16, v149
	v_and_b32_e32 v151, 0xffff0000, v149
	v_pk_mul_f32 v[150:151], v[84:85], v[150:151]
	s_nop 0
	v_cvt_pk_bf16_f32 v149, v150, v151
	buffer_store_dwordx4 v[146:149], v162, s[16:19], 0 offen offset:3072 sc1
	s_nop 1
	v_lshlrev_b32_e32 v146, 16, v142
	v_and_b32_e32 v147, 0xffff0000, v142
	v_pk_mul_f32 v[146:147], v[110:111], v[146:147]
	s_nop 0
	v_cvt_pk_bf16_f32 v142, v146, v147
	v_lshlrev_b32_e32 v146, 16, v143
	v_and_b32_e32 v147, 0xffff0000, v143
	v_pk_mul_f32 v[146:147], v[112:113], v[146:147]
	s_nop 0
	v_cvt_pk_bf16_f32 v143, v146, v147
	v_lshlrev_b32_e32 v146, 16, v144
	v_and_b32_e32 v147, 0xffff0000, v144
	v_pk_mul_f32 v[146:147], v[106:107], v[146:147]
	s_nop 0
	v_cvt_pk_bf16_f32 v144, v146, v147
	v_lshlrev_b32_e32 v146, 16, v145
	v_and_b32_e32 v147, 0xffff0000, v145
	v_pk_mul_f32 v[146:147], v[108:109], v[146:147]
	s_nop 0
	v_cvt_pk_bf16_f32 v145, v146, v147
	buffer_store_dwordx4 v[142:145], v1, s[16:19], 0 offen sc1
	s_nop 1
	v_lshlrev_b32_e32 v142, 16, v138
	v_and_b32_e32 v143, 0xffff0000, v138
	v_pk_mul_f32 v[142:143], v[78:79], v[142:143]
	s_nop 0
	v_cvt_pk_bf16_f32 v138, v142, v143
	v_lshlrev_b32_e32 v142, 16, v139
	v_and_b32_e32 v143, 0xffff0000, v139
	v_pk_mul_f32 v[142:143], v[80:81], v[142:143]
	s_nop 0
	v_cvt_pk_bf16_f32 v139, v142, v143
	v_lshlrev_b32_e32 v142, 16, v140
	v_and_b32_e32 v143, 0xffff0000, v140
	v_pk_mul_f32 v[142:143], v[74:75], v[142:143]
	s_nop 0
	v_cvt_pk_bf16_f32 v140, v142, v143
	v_lshlrev_b32_e32 v142, 16, v141
	v_and_b32_e32 v143, 0xffff0000, v141
	v_pk_mul_f32 v[142:143], v[76:77], v[142:143]
	s_nop 0
	v_cvt_pk_bf16_f32 v141, v142, v143
	buffer_store_dwordx4 v[138:141], v1, s[16:19], 0 offen offset:1024 sc1
; __device__ __forceinline__ unsigned cvt_pk_bf16(float lo, float hi) { const f32x2_t v = {lo, hi}; return __builtin_bit_cast(unsigned, __builtin_convertvector(v, bf16x2_t)); }
;     __device__ __forceinline__ void operator()(f32x4 (&acc)[2][2][4][2], const Unit& u, int wr, int wc, int fr, int fq) const {
;     ...
;                 for (int m = 0; m < 4; ++m)
; #pragma unroll
;                     for (int bj = 0; bj < 2; ++bj) ra[m][bj] = *(const u32x4*)(gl + (size_t)u.seg * 8 * 65536 + ((ai * 4 + m) * 2 + bj) * 512);
; #pragma unroll
;                 for (int m = 0; m < 4; ++m)
; #pragma unroll
;                     for (int bj = 0; bj < 2; ++bj) { float f[8]; unpack8(ra[m][bj], f);
;                         const f32x4 v0 = acc[ai][bj][m][0], v1 = acc[ai][bj][m][1];
;                         u32x4 wv; wv.x = cvt_pk_bf16(v0[0] * f[0], v0[1] * f[1]); wv.y = cvt_pk_bf16(v0[2] * f[2], v0[3] * f[3]); wv.z = cvt_pk_bf16(v1[0] * f[4], v1[1] * f[5]); wv.w = cvt_pk_bf16(v1[2] * f[6], v1[3] * f[7]);
;                         __builtin_amdgcn_raw_buffer_store_b128(wv, rsrc, pbase + (unsigned)u.seg * 131072u + (unsigned)(((ai * 4 + m) * 2 + bj) * 1024), 0,   16); }
	s_nop 1
	v_lshlrev_b32_e32 v138, 16, v134
	v_and_b32_e32 v139, 0xffff0000, v134
	v_pk_mul_f32 v[138:139], v[102:103], v[138:139]
	s_nop 0
	v_cvt_pk_bf16_f32 v134, v138, v139
	v_lshlrev_b32_e32 v138, 16, v135
	v_and_b32_e32 v139, 0xffff0000, v135
	v_pk_mul_f32 v[138:139], v[104:105], v[138:139]
	s_nop 0
	v_cvt_pk_bf16_f32 v135, v138, v139
	v_lshlrev_b32_e32 v138, 16, v136
	v_and_b32_e32 v139, 0xffff0000, v136
	v_pk_mul_f32 v[138:139], v[98:99], v[138:139]
	s_nop 0
	v_cvt_pk_bf16_f32 v136, v138, v139
	v_lshlrev_b32_e32 v138, 16, v137
	v_and_b32_e32 v139, 0xffff0000, v137
	v_pk_mul_f32 v[138:139], v[100:101], v[138:139]
	s_nop 0
	v_cvt_pk_bf16_f32 v137, v138, v139
	buffer_store_dwordx4 v[134:137], v1, s[16:19], 0 offen offset:2048 sc1
	s_nop 1
	v_lshlrev_b32_e32 v134, 16, v130
	v_and_b32_e32 v135, 0xffff0000, v130
	v_pk_mul_f32 v[134:135], v[70:71], v[134:135]
	s_nop 0
	v_cvt_pk_bf16_f32 v130, v134, v135
	v_lshlrev_b32_e32 v134, 16, v131
	v_and_b32_e32 v135, 0xffff0000, v131
	v_pk_mul_f32 v[134:135], v[72:73], v[134:135]
	s_nop 0
	v_cvt_pk_bf16_f32 v131, v134, v135
	v_lshlrev_b32_e32 v134, 16, v132
	v_and_b32_e32 v135, 0xffff0000, v132
	v_pk_mul_f32 v[134:135], v[66:67], v[134:135]
	s_nop 0
	v_cvt_pk_bf16_f32 v132, v134, v135
	v_lshlrev_b32_e32 v134, 16, v133
	v_and_b32_e32 v135, 0xffff0000, v133
	v_pk_mul_f32 v[134:135], v[68:69], v[134:135]
	s_nop 0
	v_cvt_pk_bf16_f32 v133, v134, v135
	buffer_store_dwordx4 v[130:133], v1, s[16:19], 0 offen offset:3072 sc1
	global_load_dwordx4 v[134:137], v[160:161], off
	global_load_dwordx4 v[138:141], v[160:161], off offset:1024
	global_load_dwordx4 v[142:145], v[160:161], off offset:2048
	global_load_dwordx4 v[146:149], v[160:161], off offset:3072
	v_add_co_u32_e32 v130, vcc, s6, v158
	v_add_u32_e32 v1, 0x2000, v162
	s_nop 0
	v_addc_co_u32_e32 v131, vcc, 0, v159, vcc
	global_load_dwordx4 v[150:153], v[130:131], off
	global_load_dwordx4 v[154:157], v[130:131], off offset:1024
	global_load_dwordx4 v[158:161], v[130:131], off offset:2048
	s_nop 0
	global_load_dwordx4 v[130:133], v[130:131], off offset:3072
	s_waitcnt vmcnt(0)
; __device__ __forceinline__ unsigned cvt_pk_bf16(float lo, float hi) { const f32x2_t v = {lo, hi}; return __builtin_bit_cast(unsigned, __builtin_convertvector(v, bf16x2_t)); }
;     __device__ __forceinline__ void operator()(f32x4 (&acc)[2][2][4][2], const Unit& u, int wr, int wc, int fr, int fq) const {
;     ...
;                 for (int m = 0; m < 4; ++m)
; #pragma unroll
;                     for (int bj = 0; bj < 2; ++bj) ra[m][bj] = *(const u32x4*)(gl + (size_t)u.seg * 8 * 65536 + ((ai * 4 + m) * 2 + bj) * 512);
; #pragma unroll
;                 for (int m = 0; m < 4; ++m)
; #pragma unroll
;                     for (int bj = 0; bj < 2; ++bj) { float f[8]; unpack8(ra[m][bj], f);
;                         const f32x4 v0 = acc[ai][bj][m][0], v1 = acc[ai][bj][m][1];
;                         u32x4 wv; wv.x = cvt_pk_bf16(v0[0] * f[0], v0[1] * f[1]); wv.y = cvt_pk_bf16(v0[2] * f[2], v0[3] * f[3]); wv.z = cvt_pk_bf16(v1[0] * f[4], v1[1] * f[5]); wv.w = cvt_pk_bf16(v1[2] * f[6], v1[3] * f[7]);
;                         __builtin_amdgcn_raw_buffer_store_b128(wv, rsrc, pbase + (unsigned)u.seg * 131072u + (unsigned)(((ai * 4 + m) * 2 + bj) * 1024), 0,   16); }
;             }
;             asm volatile("s_waitcnt vmcnt(0)" ::: "memory");
;             unsigned old = 0; if ((fq | fr) == 0) old = __hip_atomic_fetch_add(cnt + tile * 8 + w, 1u, __ATOMIC_RELAXED, __HIP_MEMORY_SCOPE_AGENT);
;             old = (unsigned)__builtin_amdgcn_readfirstlane((int)old);
;             if (old == 2) {
	v_lshlrev_b32_e32 v164, 16, v134
	v_and_b32_e32 v165, 0xffff0000, v134
	v_pk_mul_f32 v[164:165], v[62:63], v[164:165]
	s_nop 0
	v_cvt_pk_bf16_f32 v134, v164, v165
	v_lshlrev_b32_e32 v164, 16, v135
	v_and_b32_e32 v165, 0xffff0000, v135
	v_pk_mul_f32 v[164:165], v[64:65], v[164:165]
	s_nop 0
	v_cvt_pk_bf16_f32 v135, v164, v165
	v_lshlrev_b32_e32 v164, 16, v136
	v_and_b32_e32 v165, 0xffff0000, v136
	v_pk_mul_f32 v[164:165], v[58:59], v[164:165]
	s_nop 0
	v_cvt_pk_bf16_f32 v136, v164, v165
	v_lshlrev_b32_e32 v164, 16, v137
	v_and_b32_e32 v165, 0xffff0000, v137
	v_pk_mul_f32 v[164:165], v[60:61], v[164:165]
	s_nop 0
	v_cvt_pk_bf16_f32 v137, v164, v165
	buffer_store_dwordx4 v[134:137], v1, s[16:19], 0 offen sc1
	s_nop 1
	v_lshlrev_b32_e32 v134, 16, v138
	v_and_b32_e32 v135, 0xffff0000, v138
	v_lshlrev_b32_e32 v136, 16, v139
	v_and_b32_e32 v137, 0xffff0000, v139
	v_pk_mul_f32 v[134:135], v[30:31], v[134:135]
	v_pk_mul_f32 v[136:137], v[32:33], v[136:137]
	v_cvt_pk_bf16_f32 v134, v134, v135
	v_cvt_pk_bf16_f32 v135, v136, v137
	v_lshlrev_b32_e32 v136, 16, v140
	v_and_b32_e32 v137, 0xffff0000, v140
	v_lshlrev_b32_e32 v138, 16, v141
	v_and_b32_e32 v139, 0xffff0000, v141
	v_pk_mul_f32 v[136:137], v[26:27], v[136:137]
	v_pk_mul_f32 v[138:139], v[28:29], v[138:139]
	v_cvt_pk_bf16_f32 v136, v136, v137
	v_cvt_pk_bf16_f32 v137, v138, v139
	buffer_store_dwordx4 v[134:137], v1, s[16:19], 0 offen offset:1024 sc1
	v_lshlrev_b32_e32 v138, 16, v145
	v_and_b32_e32 v139, 0xffff0000, v145
	v_lshlrev_b32_e32 v134, 16, v142
	v_and_b32_e32 v135, 0xffff0000, v142
	v_lshlrev_b32_e32 v136, 16, v143
	v_and_b32_e32 v137, 0xffff0000, v143
	v_pk_mul_f32 v[134:135], v[54:55], v[134:135]
	v_pk_mul_f32 v[136:137], v[56:57], v[136:137]
	v_cvt_pk_bf16_f32 v134, v134, v135
	v_cvt_pk_bf16_f32 v135, v136, v137
	v_lshlrev_b32_e32 v136, 16, v144
	v_and_b32_e32 v137, 0xffff0000, v144
	v_pk_mul_f32 v[136:137], v[50:51], v[136:137]
	v_pk_mul_f32 v[138:139], v[52:53], v[138:139]
	v_cvt_pk_bf16_f32 v136, v136, v137
	v_cvt_pk_bf16_f32 v137, v138, v139
	buffer_store_dwordx4 v[134:137], v1, s[16:19], 0 offen offset:2048 sc1
	v_lshlrev_b32_e32 v138, 16, v149
	v_and_b32_e32 v139, 0xffff0000, v149
	v_lshlrev_b32_e32 v134, 16, v146
	v_and_b32_e32 v135, 0xffff0000, v146
	v_lshlrev_b32_e32 v136, 16, v147
	v_and_b32_e32 v137, 0xffff0000, v147
	v_pk_mul_f32 v[134:135], v[22:23], v[134:135]
	v_pk_mul_f32 v[136:137], v[24:25], v[136:137]
	v_cvt_pk_bf16_f32 v134, v134, v135
	v_cvt_pk_bf16_f32 v135, v136, v137
	v_lshlrev_b32_e32 v136, 16, v148
	v_and_b32_e32 v137, 0xffff0000, v148
	v_pk_mul_f32 v[136:137], v[18:19], v[136:137]
	v_pk_mul_f32 v[138:139], v[20:21], v[138:139]
	v_cvt_pk_bf16_f32 v136, v136, v137
	v_cvt_pk_bf16_f32 v137, v138, v139
	buffer_store_dwordx4 v[134:137], v1, s[16:19], 0 offen offset:3072 sc1
	v_lshlrev_b32_e32 v138, 16, v153
	v_and_b32_e32 v139, 0xffff0000, v153
	v_lshlrev_b32_e32 v134, 16, v150
	v_and_b32_e32 v135, 0xffff0000, v150
	v_lshlrev_b32_e32 v136, 16, v151
	v_and_b32_e32 v137, 0xffff0000, v151
	v_pk_mul_f32 v[134:135], v[46:47], v[134:135]
	v_pk_mul_f32 v[136:137], v[48:49], v[136:137]
	v_cvt_pk_bf16_f32 v134, v134, v135
	v_cvt_pk_bf16_f32 v135, v136, v137
	v_lshlrev_b32_e32 v136, 16, v152
	v_and_b32_e32 v137, 0xffff0000, v152
	v_pk_mul_f32 v[136:137], v[42:43], v[136:137]
	v_pk_mul_f32 v[138:139], v[44:45], v[138:139]
	v_cvt_pk_bf16_f32 v136, v136, v137
	v_cvt_pk_bf16_f32 v137, v138, v139
	v_add_u32_e32 v1, 0x3000, v162
	buffer_store_dwordx4 v[134:137], v1, s[16:19], 0 offen sc1
	v_lshlrev_b32_e32 v138, 16, v157
	v_and_b32_e32 v139, 0xffff0000, v157
	v_lshlrev_b32_e32 v134, 16, v154
	v_and_b32_e32 v135, 0xffff0000, v154
	v_lshlrev_b32_e32 v136, 16, v155
	v_and_b32_e32 v137, 0xffff0000, v155
	v_pk_mul_f32 v[134:135], v[14:15], v[134:135]
	v_pk_mul_f32 v[136:137], v[16:17], v[136:137]
	v_cvt_pk_bf16_f32 v134, v134, v135
	v_cvt_pk_bf16_f32 v135, v136, v137
	v_lshlrev_b32_e32 v136, 16, v156
	v_and_b32_e32 v137, 0xffff0000, v156
	v_pk_mul_f32 v[136:137], v[10:11], v[136:137]
	v_pk_mul_f32 v[138:139], v[12:13], v[138:139]
	v_cvt_pk_bf16_f32 v136, v136, v137
	v_cvt_pk_bf16_f32 v137, v138, v139
	buffer_store_dwordx4 v[134:137], v1, s[16:19], 0 offen offset:1024 sc1
	v_lshlrev_b32_e32 v138, 16, v161
	v_and_b32_e32 v139, 0xffff0000, v161
	v_lshlrev_b32_e32 v134, 16, v158
	v_and_b32_e32 v135, 0xffff0000, v158
	v_lshlrev_b32_e32 v136, 16, v159
	v_and_b32_e32 v137, 0xffff0000, v159
	v_pk_mul_f32 v[134:135], v[38:39], v[134:135]
	v_pk_mul_f32 v[136:137], v[40:41], v[136:137]
	v_cvt_pk_bf16_f32 v134, v134, v135
	v_cvt_pk_bf16_f32 v135, v136, v137
	v_lshlrev_b32_e32 v136, 16, v160
	v_and_b32_e32 v137, 0xffff0000, v160
	v_pk_mul_f32 v[136:137], v[34:35], v[136:137]
	v_pk_mul_f32 v[138:139], v[36:37], v[138:139]
	v_cvt_pk_bf16_f32 v136, v136, v137
	v_cvt_pk_bf16_f32 v137, v138, v139
	buffer_store_dwordx4 v[134:137], v1, s[16:19], 0 offen offset:2048 sc1
	s_nop 1
	v_lshlrev_b32_e32 v134, 16, v130
	v_and_b32_e32 v135, 0xffff0000, v130
	v_pk_mul_f32 v[134:135], v[6:7], v[134:135]
	s_nop 0
	v_cvt_pk_bf16_f32 v130, v134, v135
	v_lshlrev_b32_e32 v134, 16, v131
	v_and_b32_e32 v135, 0xffff0000, v131
	v_pk_mul_f32 v[134:135], v[8:9], v[134:135]
	s_nop 0
	v_cvt_pk_bf16_f32 v131, v134, v135
	v_lshlrev_b32_e32 v134, 16, v132
	v_and_b32_e32 v135, 0xffff0000, v132
	v_pk_mul_f32 v[134:135], v[2:3], v[134:135]
	s_nop 0
	v_cvt_pk_bf16_f32 v132, v134, v135
	v_lshlrev_b32_e32 v134, 16, v133
	v_and_b32_e32 v135, 0xffff0000, v133
	v_pk_mul_f32 v[134:135], v[4:5], v[134:135]
	s_nop 0
	v_cvt_pk_bf16_f32 v133, v134, v135
	buffer_store_dwordx4 v[130:133], v1, s[16:19], 0 offen offset:3072 sc1
	s_waitcnt vmcnt(0)
	s_nop 1
	v_mov_b32_e32 v130, 0
	s_and_saveexec_b64 s[12:13], s[4:5]
	s_cbranch_execz .LBB0_877
	s_mov_b64 s[26:27], exec
	v_mbcnt_lo_u32_b32 v1, s26, 0
	v_mbcnt_hi_u32_b32 v130, s27, v1
	v_cmp_eq_u32_e32 vcc, 0, v130
	s_and_saveexec_b64 s[20:21], vcc
	s_cbranch_execz .LBB0_876
	s_lshl_b32 s6, s1, 3
	s_ashr_i32 s7, s6, 31
	s_lshl_b64 s[6:7], s[6:7], 2
	v_readlane_b32 s23, v255, 36
	s_add_u32 s6, s23, s6
	v_readlane_b32 s23, v255, 37
	s_addc_u32 s7, s23, s7
	s_bcnt1_i32_b64 s23, s[26:27]
	v_mov_b32_e32 v1, s23
	global_atomic_add v131, v179, v1, s[6:7] sc0

; #define PG8_STAGE(bufoff, gbase, voff) do { _Pragma("unroll") for (int _i = 0; _i < 2; ++_i) \
;         __builtin_amdgcn_global_load_lds((const unsigned*)((const char*)(gbase) + (voff)[_i]), (LAS unsigned*)(lds + (bufoff) + ldsw + _i * 8192), 16, 0, 0); } while (0)
; #define PG8_LDA(dst, b, h) do { _Pragma("unroll") for (int m = 0; m < 4; ++m) _Pragma("unroll") for (int k = 0; k < 2; ++k) dst[m][k] = *(const LAS bf16x8*)(lds + PG8_SA(b, h) + aoff + m * 2048 + k * 1024); } while (0)
; #define PG8_WAIT_V(n) asm volatile("s_waitcnt vmcnt(" #n ")" ::: "memory")
; template <class Epi, class Sched>
; __device__ __forceinline__ void gemm_phase(LAS unsigned char* lds, const Gemm g, const Sched& S, const Epi& E) {
;     ...
;         for (int t = 0; t < ntu; t += 2) {
;             const bool last = (t == ntu - 2);
;             const char* a1 = cA + (size_t)(t + 1) * kstep;
;             const char* a2 = last ? nA : cA + (size_t)(t + 2) * kstep; const char* b2 = last ? nB : cB + (size_t)(t + 2) * kstep;
;             const char* a3 = a2 + kstep; const char* b3 = b2 + kstep;
;             if (last && has_next) S.a_ready(nxt);
;             PG8_LDB(B0, 0, 0); PG8_SCHED; PG8_LDA(At, 0, 0); PG8_STAGE(PG8_SA(1, 1), a1 + hstepA, voffA);
;             PG8_WAIT_L(8); PG8_BAR; PG8_WAIT_L(0); PG8_MMA(0, 0, At, B0); PG8_BAR; PG8_SCHED;
;             PG8_LDB(B1, 0, 1); PG8_STAGE(PG8_SB(0, 0), b2, voffB);
;             PG8_BAR; PG8_WAIT_L(0); PG8_MMA(0, 1, At, B1); PG8_BAR;
;             PG8_LDA(At, 0, 1); PG8_STAGE(PG8_SA(0, 0), a2, voffA);
;             PG8_BAR; PG8_WAIT_L(0); PG8_MMA(1, 0, At, B0); PG8_BAR; PG8_SCHED;
;             PG8_STAGE(PG8_SB(0, 1), b2 + hstepB, voffB);
;             PG8_WAIT_V(6); PG8_BAR; PG8_MMA(1, 1, At, B1); PG8_BAR;
;             PG8_LDB(B0, 1, 0); PG8_SCHED; PG8_LDA(At, 1, 0); PG8_STAGE(PG8_SA(0, 1), a2 + hstepA, voffA);
;             PG8_WAIT_L(8); PG8_BAR; PG8_WAIT_L(0); PG8_MMA(0, 0, At, B0); PG8_BAR; PG8_SCHED;
;             PG8_LDB(B1, 1, 1); PG8_STAGE(PG8_SB(1, 0), b3, voffB);
;             PG8_BAR; PG8_WAIT_L(0); PG8_MMA(0, 1, At, B1); PG8_BAR;
;             PG8_LDA(At, 1, 1); PG8_STAGE(PG8_SA(1, 0), a3, voffA);
;             PG8_BAR; PG8_WAIT_L(0); PG8_MMA(1, 0, At, B0); PG8_BAR; PG8_SCHED;
;             PG8_STAGE(PG8_SB(1, 1), b3 + hstepB, voffB);
;             PG8_WAIT_V(6); PG8_BAR; PG8_MMA(1, 1, At, B1); PG8_BAR;
.LBB0_985:
	s_add_i32 s72, s28, 2
	s_add_u32 s54, s52, 0x100
	s_addc_u32 s55, s53, 0
	s_add_i32 s35, 0, 0x10000
	v_add_u32_e32 v1, s35, v141
	ds_read_b128 v[144:147], v1
	ds_read_b128 v[148:151], v1 offset:1024
	ds_read_b128 v[152:155], v1 offset:2048
	ds_read_b128 v[156:159], v1 offset:3072
	s_cmp_eq_u32 s21, s28
	s_cselect_b32 s28, s24, s54
	s_cselect_b32 s29, s25, s55
	s_cselect_b32 s57, s27, s71
	s_cselect_b32 s56, s26, s70
	ds_read_b128 v[160:163], v143
	ds_read_b128 v[164:167], v143 offset:1024
	ds_read_b128 v[168:171], v143 offset:2048
	ds_read_b128 v[172:175], v143 offset:3072
	ds_read_b128 v[182:185], v143 offset:4096
	ds_read_b128 v[186:189], v143 offset:5120
	ds_read_b128 v[190:193], v143 offset:6144
	ds_read_b128 v[194:197], v143 offset:7168
	s_add_u32 s98, s52, 0xfff7c000
	s_addc_u32 s99, s53, -1
	s_mov_b32 m0, s62
	s_nop 0
	global_load_lds_dwordx4 v136, s[98:99]
	s_mov_b32 m0, s63
	s_nop 0
	global_load_lds_dwordx4 v138, s[98:99]
	s_add_i32 m0, s9, 0xc000
	s_nop 0
	global_load_lds_dwordx4 v136, s[52:53]
	s_add_i32 m0, s9, 0xe000
	s_nop 0
	global_load_lds_dwordx4 v138, s[52:53]
	s_add_i32 s76, 0, 0x14000
	v_add_u32_e32 v1, s76, v141
	ds_read_b128 v[198:201], v1
	ds_read_b128 v[202:205], v1 offset:1024
	ds_read_b128 v[206:209], v1 offset:2048
	ds_read_b128 v[210:213], v1 offset:3072
	s_waitcnt lgkmcnt(0)
	s_barrier
	v_mfma_f32_16x16x32_bf16 v[126:129], v[144:147], v[160:163], v[126:129]
	v_mfma_f32_16x16x32_bf16 v[126:129], v[148:151], v[164:167], v[126:129]
	v_mfma_f32_16x16x32_bf16 v[110:113], v[144:147], v[168:171], v[110:113]
	v_mfma_f32_16x16x32_bf16 v[110:113], v[148:151], v[172:175], v[110:113]
	v_mfma_f32_16x16x32_bf16 v[94:97], v[144:147], v[182:185], v[94:97]
	v_mfma_f32_16x16x32_bf16 v[94:97], v[148:151], v[186:189], v[94:97]
	v_mfma_f32_16x16x32_bf16 v[78:81], v[144:147], v[190:193], v[78:81]
	v_mfma_f32_16x16x32_bf16 v[78:81], v[148:151], v[194:197], v[78:81]
	v_mfma_f32_16x16x32_bf16 v[122:125], v[152:155], v[160:163], v[122:125]
	v_mfma_f32_16x16x32_bf16 v[122:125], v[156:159], v[164:167], v[122:125]
	v_mfma_f32_16x16x32_bf16 v[106:109], v[152:155], v[168:171], v[106:109]
	v_mfma_f32_16x16x32_bf16 v[106:109], v[156:159], v[172:175], v[106:109]
	v_mfma_f32_16x16x32_bf16 v[90:93], v[152:155], v[182:185], v[90:93]
	v_mfma_f32_16x16x32_bf16 v[90:93], v[156:159], v[186:189], v[90:93]
	v_mfma_f32_16x16x32_bf16 v[74:77], v[152:155], v[190:193], v[74:77]
	v_mfma_f32_16x16x32_bf16 v[74:77], v[156:159], v[194:197], v[74:77]
	v_mfma_f32_16x16x32_bf16 v[118:121], v[198:201], v[160:163], v[118:121]
	v_mfma_f32_16x16x32_bf16 v[118:121], v[202:205], v[164:167], v[118:121]
	v_mfma_f32_16x16x32_bf16 v[102:105], v[198:201], v[168:171], v[102:105]
	v_mfma_f32_16x16x32_bf16 v[102:105], v[202:205], v[172:175], v[102:105]
	v_mfma_f32_16x16x32_bf16 v[86:89], v[198:201], v[182:185], v[86:89]
	v_mfma_f32_16x16x32_bf16 v[86:89], v[202:205], v[186:189], v[86:89]
	v_mfma_f32_16x16x32_bf16 v[70:73], v[198:201], v[190:193], v[70:73]
	v_mfma_f32_16x16x32_bf16 v[70:73], v[202:205], v[194:197], v[70:73]
	v_mfma_f32_16x16x32_bf16 v[114:117], v[206:209], v[160:163], v[114:117]
	v_mfma_f32_16x16x32_bf16 v[114:117], v[210:213], v[164:167], v[114:117]
	v_mfma_f32_16x16x32_bf16 v[98:101], v[206:209], v[168:171], v[98:101]
	v_mfma_f32_16x16x32_bf16 v[98:101], v[210:213], v[172:175], v[98:101]
	v_mfma_f32_16x16x32_bf16 v[82:85], v[206:209], v[182:185], v[82:85]
	v_mfma_f32_16x16x32_bf16 v[82:85], v[210:213], v[186:189], v[82:85]
	v_mfma_f32_16x16x32_bf16 v[66:69], v[206:209], v[190:193], v[66:69]
	v_mfma_f32_16x16x32_bf16 v[66:69], v[210:213], v[194:197], v[66:69]
	s_barrier
	ds_read_b128 v[160:163], v143 offset:16384
	ds_read_b128 v[164:167], v143 offset:17408
	ds_read_b128 v[168:171], v143 offset:18432
	ds_read_b128 v[172:175], v143 offset:19456
	ds_read_b128 v[182:185], v143 offset:20480
	ds_read_b128 v[186:189], v143 offset:21504
	ds_read_b128 v[190:193], v143 offset:22528
	ds_read_b128 v[194:197], v143 offset:23552
	s_add_i32 s35, s35, s46
	s_mov_b32 m0, s35
	s_nop 0
	global_load_lds_dwordx4 v178, s[56:57]
	s_add_i32 m0, s35, 0x2000
	s_nop 0
	global_load_lds_dwordx4 v134, s[56:57]
	s_add_u32 s52, s56, 0x80000
	s_addc_u32 s53, s57, 0
	s_add_i32 s35, s76, s46
	s_mov_b32 m0, s35
	s_nop 0
	global_load_lds_dwordx4 v178, s[52:53]
	s_add_i32 m0, s35, 0x2000
	s_nop 0
	global_load_lds_dwordx4 v134, s[52:53]
	s_waitcnt vmcnt(4)
	s_waitcnt lgkmcnt(0)
	s_barrier
	v_mfma_f32_16x16x32_bf16 v[62:65], v[144:147], v[160:163], v[62:65]
	v_mfma_f32_16x16x32_bf16 v[62:65], v[148:151], v[164:167], v[62:65]
	v_mfma_f32_16x16x32_bf16 v[46:49], v[144:147], v[168:171], v[46:49]
	v_mfma_f32_16x16x32_bf16 v[46:49], v[148:151], v[172:175], v[46:49]
	v_mfma_f32_16x16x32_bf16 v[30:33], v[144:147], v[182:185], v[30:33]
	v_mfma_f32_16x16x32_bf16 v[30:33], v[148:151], v[186:189], v[30:33]
	v_mfma_f32_16x16x32_bf16 v[14:17], v[144:147], v[190:193], v[14:17]
	v_mfma_f32_16x16x32_bf16 v[14:17], v[148:151], v[194:197], v[14:17]
	v_mfma_f32_16x16x32_bf16 v[58:61], v[152:155], v[160:163], v[58:61]
	v_mfma_f32_16x16x32_bf16 v[58:61], v[156:159], v[164:167], v[58:61]
	v_mfma_f32_16x16x32_bf16 v[42:45], v[152:155], v[168:171], v[42:45]
	v_mfma_f32_16x16x32_bf16 v[42:45], v[156:159], v[172:175], v[42:45]
	v_mfma_f32_16x16x32_bf16 v[26:29], v[152:155], v[182:185], v[26:29]
	v_mfma_f32_16x16x32_bf16 v[26:29], v[156:159], v[186:189], v[26:29]
	v_mfma_f32_16x16x32_bf16 v[10:13], v[152:155], v[190:193], v[10:13]
	v_mfma_f32_16x16x32_bf16 v[10:13], v[156:159], v[194:197], v[10:13]
	v_mfma_f32_16x16x32_bf16 v[54:57], v[198:201], v[160:163], v[54:57]
	v_mfma_f32_16x16x32_bf16 v[54:57], v[202:205], v[164:167], v[54:57]
	v_mfma_f32_16x16x32_bf16 v[38:41], v[198:201], v[168:171], v[38:41]
	v_mfma_f32_16x16x32_bf16 v[38:41], v[202:205], v[172:175], v[38:41]
	v_mfma_f32_16x16x32_bf16 v[22:25], v[198:201], v[182:185], v[22:25]
	v_mfma_f32_16x16x32_bf16 v[22:25], v[202:205], v[186:189], v[22:25]
	v_mfma_f32_16x16x32_bf16 v[6:9], v[198:201], v[190:193], v[6:9]
	v_mfma_f32_16x16x32_bf16 v[6:9], v[202:205], v[194:197], v[6:9]
	v_mfma_f32_16x16x32_bf16 v[50:53], v[206:209], v[160:163], v[50:53]
	v_mfma_f32_16x16x32_bf16 v[50:53], v[210:213], v[164:167], v[50:53]
	v_mfma_f32_16x16x32_bf16 v[34:37], v[206:209], v[168:171], v[34:37]
	v_mfma_f32_16x16x32_bf16 v[34:37], v[210:213], v[172:175], v[34:37]
	v_mfma_f32_16x16x32_bf16 v[18:21], v[206:209], v[182:185], v[18:21]
	v_mfma_f32_16x16x32_bf16 v[18:21], v[210:213], v[186:189], v[18:21]
	v_mfma_f32_16x16x32_bf16 v[2:5], v[206:209], v[190:193], v[2:5]
	v_mfma_f32_16x16x32_bf16 v[2:5], v[210:213], v[194:197], v[2:5]
	s_add_i32 s35, 0, 0x18000
	v_add_u32_e32 v1, s35, v141
	s_barrier
; #define PG8_STAGE(bufoff, gbase, voff) do { _Pragma("unroll") for (int _i = 0; _i < 2; ++_i) \
;         __builtin_amdgcn_global_load_lds((const unsigned*)((const char*)(gbase) + (voff)[_i]), (LAS unsigned*)(lds + (bufoff) + ldsw + _i * 8192), 16, 0, 0); } while (0)
; #define PG8_LDA(dst, b, h) do { _Pragma("unroll") for (int m = 0; m < 4; ++m) _Pragma("unroll") for (int k = 0; k < 2; ++k) dst[m][k] = *(const LAS bf16x8*)(lds + PG8_SA(b, h) + aoff + m * 2048 + k * 1024); } while (0)
; #define PG8_WAIT_V(n) asm volatile("s_waitcnt vmcnt(" #n ")" ::: "memory")
; template <class Epi, class Sched>
; __device__ __forceinline__ void gemm_phase(LAS unsigned char* lds, const Gemm g, const Sched& S, const Epi& E) {
;     ...
;         for (int t = 0; t < ntu; t += 2) {
;             const bool last = (t == ntu - 2);
;             const char* a1 = cA + (size_t)(t + 1) * kstep;
;             const char* a2 = last ? nA : cA + (size_t)(t + 2) * kstep; const char* b2 = last ? nB : cB + (size_t)(t + 2) * kstep;
;             const char* a3 = a2 + kstep; const char* b3 = b2 + kstep;
;             if (last && has_next) S.a_ready(nxt);
;             PG8_LDB(B0, 0, 0); PG8_SCHED; PG8_LDA(At, 0, 0); PG8_STAGE(PG8_SA(1, 1), a1 + hstepA, voffA);
;             PG8_WAIT_L(8); PG8_BAR; PG8_WAIT_L(0); PG8_MMA(0, 0, At, B0); PG8_BAR; PG8_SCHED;
;             PG8_LDB(B1, 0, 1); PG8_STAGE(PG8_SB(0, 0), b2, voffB);
;             PG8_BAR; PG8_WAIT_L(0); PG8_MMA(0, 1, At, B1); PG8_BAR;
;             PG8_LDA(At, 0, 1); PG8_STAGE(PG8_SA(0, 0), a2, voffA);
;             PG8_BAR; PG8_WAIT_L(0); PG8_MMA(1, 0, At, B0); PG8_BAR; PG8_SCHED;
;             PG8_STAGE(PG8_SB(0, 1), b2 + hstepB, voffB);
;             PG8_WAIT_V(6); PG8_BAR; PG8_MMA(1, 1, At, B1); PG8_BAR;
;             PG8_LDB(B0, 1, 0); PG8_SCHED; PG8_LDA(At, 1, 0); PG8_STAGE(PG8_SA(0, 1), a2 + hstepA, voffA);
;             PG8_WAIT_L(8); PG8_BAR; PG8_WAIT_L(0); PG8_MMA(0, 0, At, B0); PG8_BAR; PG8_SCHED;
;             PG8_LDB(B1, 1, 1); PG8_STAGE(PG8_SB(1, 0), b3, voffB);
;             PG8_BAR; PG8_WAIT_L(0); PG8_MMA(0, 1, At, B1); PG8_BAR;
;             PG8_LDA(At, 1, 1); PG8_STAGE(PG8_SA(1, 0), a3, voffA);
;             PG8_BAR; PG8_WAIT_L(0); PG8_MMA(1, 0, At, B0); PG8_BAR; PG8_SCHED;
;             PG8_STAGE(PG8_SB(1, 1), b3 + hstepB, voffB);
;             PG8_WAIT_V(6); PG8_BAR; PG8_MMA(1, 1, At, B1); PG8_BAR;
;         }
	ds_read_b128 v[144:147], v1
	ds_read_b128 v[148:151], v1 offset:1024
	ds_read_b128 v[152:155], v1 offset:2048
	ds_read_b128 v[156:159], v1 offset:3072
	ds_read_b128 v[160:163], v143 offset:32768
	ds_read_b128 v[164:167], v143 offset:33792
	ds_read_b128 v[168:171], v143 offset:34816
	ds_read_b128 v[172:175], v143 offset:35840
	ds_read_b128 v[182:185], v143 offset:36864
	ds_read_b128 v[186:189], v143 offset:37888
	ds_read_b128 v[190:193], v143 offset:38912
	ds_read_b128 v[194:197], v143 offset:39936
	s_mov_b32 m0, s9
	s_nop 0
	global_load_lds_dwordx4 v130, s[28:29]
	s_mov_b32 m0, s11
	s_nop 0
	global_load_lds_dwordx4 v132, s[28:29]
	s_add_u32 s28, s28, 0x84000
	s_addc_u32 s29, s29, 0
	s_mov_b32 m0, s58
	s_nop 0
	global_load_lds_dwordx4 v130, s[28:29]
	s_mov_b32 m0, s59
	s_nop 0
	global_load_lds_dwordx4 v132, s[28:29]
	s_add_i32 s52, 0, 0x1c000
	v_add_u32_e32 v1, s52, v141
	ds_read_b128 v[198:201], v1
	ds_read_b128 v[202:205], v1 offset:1024
	ds_read_b128 v[206:209], v1 offset:2048
	ds_read_b128 v[210:213], v1 offset:3072
	s_waitcnt lgkmcnt(0)
	s_barrier
	v_mfma_f32_16x16x32_bf16 v[126:129], v[144:147], v[160:163], v[126:129]
	v_mfma_f32_16x16x32_bf16 v[126:129], v[148:151], v[164:167], v[126:129]
	v_mfma_f32_16x16x32_bf16 v[110:113], v[144:147], v[168:171], v[110:113]
	v_mfma_f32_16x16x32_bf16 v[110:113], v[148:151], v[172:175], v[110:113]
	v_mfma_f32_16x16x32_bf16 v[94:97], v[144:147], v[182:185], v[94:97]
	v_mfma_f32_16x16x32_bf16 v[94:97], v[148:151], v[186:189], v[94:97]
	v_mfma_f32_16x16x32_bf16 v[78:81], v[144:147], v[190:193], v[78:81]
	v_mfma_f32_16x16x32_bf16 v[78:81], v[148:151], v[194:197], v[78:81]
	v_mfma_f32_16x16x32_bf16 v[122:125], v[152:155], v[160:163], v[122:125]
	v_mfma_f32_16x16x32_bf16 v[122:125], v[156:159], v[164:167], v[122:125]
	v_mfma_f32_16x16x32_bf16 v[106:109], v[152:155], v[168:171], v[106:109]
	v_mfma_f32_16x16x32_bf16 v[106:109], v[156:159], v[172:175], v[106:109]
	v_mfma_f32_16x16x32_bf16 v[90:93], v[152:155], v[182:185], v[90:93]
	v_mfma_f32_16x16x32_bf16 v[90:93], v[156:159], v[186:189], v[90:93]
	v_mfma_f32_16x16x32_bf16 v[74:77], v[152:155], v[190:193], v[74:77]
	v_mfma_f32_16x16x32_bf16 v[74:77], v[156:159], v[194:197], v[74:77]
	v_mfma_f32_16x16x32_bf16 v[118:121], v[198:201], v[160:163], v[118:121]
	v_mfma_f32_16x16x32_bf16 v[118:121], v[202:205], v[164:167], v[118:121]
	v_mfma_f32_16x16x32_bf16 v[102:105], v[198:201], v[168:171], v[102:105]
	v_mfma_f32_16x16x32_bf16 v[102:105], v[202:205], v[172:175], v[102:105]
	v_mfma_f32_16x16x32_bf16 v[86:89], v[198:201], v[182:185], v[86:89]
	v_mfma_f32_16x16x32_bf16 v[86:89], v[202:205], v[186:189], v[86:89]
	v_mfma_f32_16x16x32_bf16 v[70:73], v[198:201], v[190:193], v[70:73]
	v_mfma_f32_16x16x32_bf16 v[70:73], v[202:205], v[194:197], v[70:73]
	v_mfma_f32_16x16x32_bf16 v[114:117], v[206:209], v[160:163], v[114:117]
	v_mfma_f32_16x16x32_bf16 v[114:117], v[210:213], v[164:167], v[114:117]
	v_mfma_f32_16x16x32_bf16 v[98:101], v[206:209], v[168:171], v[98:101]
	v_mfma_f32_16x16x32_bf16 v[98:101], v[210:213], v[172:175], v[98:101]
	v_mfma_f32_16x16x32_bf16 v[82:85], v[206:209], v[182:185], v[82:85]
	v_mfma_f32_16x16x32_bf16 v[82:85], v[210:213], v[186:189], v[82:85]
	v_mfma_f32_16x16x32_bf16 v[66:69], v[206:209], v[190:193], v[66:69]
	v_mfma_f32_16x16x32_bf16 v[66:69], v[210:213], v[194:197], v[66:69]
	s_barrier
	ds_read_b128 v[160:163], v143 offset:49152
	ds_read_b128 v[164:167], v143 offset:50176
	ds_read_b128 v[168:171], v143 offset:51200
	ds_read_b128 v[172:175], v143 offset:52224
	ds_read_b128 v[182:185], v143 offset:53248
	ds_read_b128 v[186:189], v143 offset:54272
	ds_read_b128 v[190:193], v143 offset:55296
	ds_read_b128 v[194:197], v143 offset:56320
	s_add_u32 s98, s56, 0x80
	s_addc_u32 s99, s57, 0
	s_add_i32 s28, s35, s46
	s_mov_b32 m0, s28
	s_nop 0
	global_load_lds_dwordx4 v178, s[98:99]
	s_add_i32 m0, s28, 0x2000
	s_nop 0
	global_load_lds_dwordx4 v134, s[98:99]
	s_add_u32 s28, s56, 0x80080
	s_addc_u32 s29, s57, 0
	s_add_i32 s35, s52, s46
	s_mov_b32 m0, s35
	s_nop 0
	global_load_lds_dwordx4 v178, s[28:29]
	s_add_i32 m0, s35, 0x2000
	s_nop 0
	global_load_lds_dwordx4 v134, s[28:29]
	s_waitcnt vmcnt(4)
	s_waitcnt lgkmcnt(0)
	s_barrier
	v_mfma_f32_16x16x32_bf16 v[62:65], v[144:147], v[160:163], v[62:65]
	v_mfma_f32_16x16x32_bf16 v[62:65], v[148:151], v[164:167], v[62:65]
	v_mfma_f32_16x16x32_bf16 v[46:49], v[144:147], v[168:171], v[46:49]
	v_mfma_f32_16x16x32_bf16 v[46:49], v[148:151], v[172:175], v[46:49]
	v_mfma_f32_16x16x32_bf16 v[30:33], v[144:147], v[182:185], v[30:33]
	v_mfma_f32_16x16x32_bf16 v[30:33], v[148:151], v[186:189], v[30:33]
	v_mfma_f32_16x16x32_bf16 v[14:17], v[144:147], v[190:193], v[14:17]
	v_mfma_f32_16x16x32_bf16 v[14:17], v[148:151], v[194:197], v[14:17]
	v_mfma_f32_16x16x32_bf16 v[58:61], v[152:155], v[160:163], v[58:61]
	v_mfma_f32_16x16x32_bf16 v[58:61], v[156:159], v[164:167], v[58:61]
	v_mfma_f32_16x16x32_bf16 v[42:45], v[152:155], v[168:171], v[42:45]
	v_mfma_f32_16x16x32_bf16 v[42:45], v[156:159], v[172:175], v[42:45]
	v_mfma_f32_16x16x32_bf16 v[26:29], v[152:155], v[182:185], v[26:29]
	v_mfma_f32_16x16x32_bf16 v[26:29], v[156:159], v[186:189], v[26:29]
	v_mfma_f32_16x16x32_bf16 v[10:13], v[152:155], v[190:193], v[10:13]
	v_mfma_f32_16x16x32_bf16 v[10:13], v[156:159], v[194:197], v[10:13]
	v_mfma_f32_16x16x32_bf16 v[54:57], v[198:201], v[160:163], v[54:57]
	v_mfma_f32_16x16x32_bf16 v[54:57], v[202:205], v[164:167], v[54:57]
	v_mfma_f32_16x16x32_bf16 v[38:41], v[198:201], v[168:171], v[38:41]
	v_mfma_f32_16x16x32_bf16 v[38:41], v[202:205], v[172:175], v[38:41]
	v_mfma_f32_16x16x32_bf16 v[22:25], v[198:201], v[182:185], v[22:25]
	v_mfma_f32_16x16x32_bf16 v[22:25], v[202:205], v[186:189], v[22:25]
	v_mfma_f32_16x16x32_bf16 v[6:9], v[198:201], v[190:193], v[6:9]
	v_mfma_f32_16x16x32_bf16 v[6:9], v[202:205], v[194:197], v[6:9]
	v_mfma_f32_16x16x32_bf16 v[50:53], v[206:209], v[160:163], v[50:53]
	v_mfma_f32_16x16x32_bf16 v[50:53], v[210:213], v[164:167], v[50:53]
	v_mfma_f32_16x16x32_bf16 v[34:37], v[206:209], v[168:171], v[34:37]
	v_mfma_f32_16x16x32_bf16 v[34:37], v[210:213], v[172:175], v[34:37]
	v_mfma_f32_16x16x32_bf16 v[18:21], v[206:209], v[182:185], v[18:21]
	v_mfma_f32_16x16x32_bf16 v[18:21], v[210:213], v[186:189], v[18:21]
	v_mfma_f32_16x16x32_bf16 v[2:5], v[206:209], v[190:193], v[2:5]
	v_mfma_f32_16x16x32_bf16 v[2:5], v[210:213], v[194:197], v[2:5]
	s_add_u32 s70, s70, 0x100
	s_addc_u32 s71, s71, 0
	s_cmp_ge_i32 s72, s17
	s_mov_b64 s[52:53], s[54:55]
	s_mov_b32 s28, s72
	s_barrier
	s_cbranch_scc0 .LBB0_985
	v_readlane_b32 s70, v255, 24
	v_readlane_b32 s76, v255, 26
	v_readlane_b32 s71, v255, 25
	v_readlane_b32 s77, v255, 27
	s_andn2_b64 vcc, exec, s[50:51]
	s_mov_b64 s[28:29], s[12:13]
	s_cbranch_vccnz .LBB0_967
	s_branch .LBB0_966

; #define PG8_STAGE(bufoff, gbase, voff) do { _Pragma("unroll") for (int _i = 0; _i < 2; ++_i) \
;         __builtin_amdgcn_global_load_lds((const unsigned*)((const char*)(gbase) + (voff)[_i]), (LAS unsigned*)(lds + (bufoff) + ldsw + _i * 8192), 16, 0, 0); } while (0)
; #define PG8_LDA(dst, b, h) do { _Pragma("unroll") for (int m = 0; m < 4; ++m) _Pragma("unroll") for (int k = 0; k < 2; ++k) dst[m][k] = *(const LAS bf16x8*)(lds + PG8_SA(b, h) + aoff + m * 2048 + k * 1024); } while (0)
; #define PG8_WAIT_V(n) asm volatile("s_waitcnt vmcnt(" #n ")" ::: "memory")
; template <class Epi, class Sched>
; __device__ __forceinline__ void gemm_phase(LAS unsigned char* lds, const Gemm g, const Sched& S, const Epi& E) {
;     ...
;         for (int t = 0; t < ntu; t += 2) {
;             const bool last = (t == ntu - 2);
;             const char* a1 = cA + (size_t)(t + 1) * kstep;
;             const char* a2 = last ? nA : cA + (size_t)(t + 2) * kstep; const char* b2 = last ? nB : cB + (size_t)(t + 2) * kstep;
;             const char* a3 = a2 + kstep; const char* b3 = b2 + kstep;
;             if (last && has_next) S.a_ready(nxt);
;             PG8_LDB(B0, 0, 0); PG8_SCHED; PG8_LDA(At, 0, 0); PG8_STAGE(PG8_SA(1, 1), a1 + hstepA, voffA);
;             PG8_WAIT_L(8); PG8_BAR; PG8_WAIT_L(0); PG8_MMA(0, 0, At, B0); PG8_BAR; PG8_SCHED;
;             PG8_LDB(B1, 0, 1); PG8_STAGE(PG8_SB(0, 0), b2, voffB);
;             PG8_BAR; PG8_WAIT_L(0); PG8_MMA(0, 1, At, B1); PG8_BAR;
;             PG8_LDA(At, 0, 1); PG8_STAGE(PG8_SA(0, 0), a2, voffA);
;             PG8_BAR; PG8_WAIT_L(0); PG8_MMA(1, 0, At, B0); PG8_BAR; PG8_SCHED;
;             PG8_STAGE(PG8_SB(0, 1), b2 + hstepB, voffB);
;             PG8_WAIT_V(6); PG8_BAR; PG8_MMA(1, 1, At, B1); PG8_BAR;
;             PG8_LDB(B0, 1, 0); PG8_SCHED; PG8_LDA(At, 1, 0); PG8_STAGE(PG8_SA(0, 1), a2 + hstepA, voffA);
;             PG8_WAIT_L(8); PG8_BAR; PG8_WAIT_L(0); PG8_MMA(0, 0, At, B0); PG8_BAR; PG8_SCHED;
;             PG8_LDB(B1, 1, 1); PG8_STAGE(PG8_SB(1, 0), b3, voffB);
;             PG8_BAR; PG8_WAIT_L(0); PG8_MMA(0, 1, At, B1); PG8_BAR;
;             PG8_LDA(At, 1, 1); PG8_STAGE(PG8_SA(1, 0), a3, voffA);
;             PG8_BAR; PG8_WAIT_L(0); PG8_MMA(1, 0, At, B0); PG8_BAR; PG8_SCHED;
;             PG8_STAGE(PG8_SB(1, 1), b3 + hstepB, voffB);
;             PG8_WAIT_V(6); PG8_BAR; PG8_MMA(1, 1, At, B1); PG8_BAR;
.LBB0_1140:
	s_add_u32 s28, s26, 0xfff80080
	s_addc_u32 s29, s27, -1
	s_add_i32 s35, 0, 0x10000
	v_add_u32_e32 v1, s35, v143
	ds_read_b128 v[146:149], v1
	ds_read_b128 v[150:153], v1 offset:1024
	ds_read_b128 v[154:157], v1 offset:2048
	ds_read_b128 v[158:161], v1 offset:3072
	s_cmp_eq_u32 s63, 28
	s_cselect_b32 s29, s13, s29
	s_cselect_b32 s28, s57, s28
	s_cselect_b32 s51, s11, s62
	s_cselect_b32 s50, s58, s59
	ds_read_b128 v[162:165], v145
	ds_read_b128 v[166:169], v145 offset:1024
	ds_read_b128 v[170:173], v145 offset:2048
	ds_read_b128 v[174:177], v145 offset:3072
	ds_read_b128 v[182:185], v145 offset:4096
	ds_read_b128 v[186:189], v145 offset:5120
	ds_read_b128 v[190:193], v145 offset:6144
	ds_read_b128 v[194:197], v145 offset:7168
	s_add_u32 s98, s26, 0xfff80000
	s_addc_u32 s99, s27, -1
	s_mov_b32 m0, s54
	s_nop 0
	global_load_lds_dwordx4 v136, s[98:99]
	s_mov_b32 m0, s55
	s_nop 0
	global_load_lds_dwordx4 v138, s[98:99]
	s_add_i32 m0, s23, 0xc000
	s_nop 0
	global_load_lds_dwordx4 v136, s[26:27]
	s_add_i32 m0, s23, 0xe000
	s_nop 0
	global_load_lds_dwordx4 v138, s[26:27]
	s_add_i32 s66, 0, 0x14000
	v_add_u32_e32 v1, s66, v143
	ds_read_b128 v[198:201], v1
	ds_read_b128 v[202:205], v1 offset:1024
	ds_read_b128 v[206:209], v1 offset:2048
	ds_read_b128 v[210:213], v1 offset:3072
	s_waitcnt lgkmcnt(0)
	s_barrier
	v_mfma_f32_16x16x32_bf16 v[126:129], v[146:149], v[162:165], v[126:129]
	v_mfma_f32_16x16x32_bf16 v[126:129], v[150:153], v[166:169], v[126:129]
	v_mfma_f32_16x16x32_bf16 v[110:113], v[146:149], v[170:173], v[110:113]
	v_mfma_f32_16x16x32_bf16 v[110:113], v[150:153], v[174:177], v[110:113]
	v_mfma_f32_16x16x32_bf16 v[94:97], v[146:149], v[182:185], v[94:97]
	v_mfma_f32_16x16x32_bf16 v[94:97], v[150:153], v[186:189], v[94:97]
	v_mfma_f32_16x16x32_bf16 v[78:81], v[146:149], v[190:193], v[78:81]
	v_mfma_f32_16x16x32_bf16 v[78:81], v[150:153], v[194:197], v[78:81]
	v_mfma_f32_16x16x32_bf16 v[118:121], v[154:157], v[162:165], v[118:121]
	v_mfma_f32_16x16x32_bf16 v[118:121], v[158:161], v[166:169], v[118:121]
	v_mfma_f32_16x16x32_bf16 v[102:105], v[154:157], v[170:173], v[102:105]
	v_mfma_f32_16x16x32_bf16 v[102:105], v[158:161], v[174:177], v[102:105]
	v_mfma_f32_16x16x32_bf16 v[86:89], v[154:157], v[182:185], v[86:89]
	v_mfma_f32_16x16x32_bf16 v[86:89], v[158:161], v[186:189], v[86:89]
	v_mfma_f32_16x16x32_bf16 v[70:73], v[154:157], v[190:193], v[70:73]
	v_mfma_f32_16x16x32_bf16 v[70:73], v[158:161], v[194:197], v[70:73]
	v_mfma_f32_16x16x32_bf16 v[122:125], v[198:201], v[162:165], v[122:125]
	v_mfma_f32_16x16x32_bf16 v[122:125], v[202:205], v[166:169], v[122:125]
	v_mfma_f32_16x16x32_bf16 v[106:109], v[198:201], v[170:173], v[106:109]
	v_mfma_f32_16x16x32_bf16 v[106:109], v[202:205], v[174:177], v[106:109]
	v_mfma_f32_16x16x32_bf16 v[90:93], v[198:201], v[182:185], v[90:93]
	v_mfma_f32_16x16x32_bf16 v[90:93], v[202:205], v[186:189], v[90:93]
	v_mfma_f32_16x16x32_bf16 v[74:77], v[198:201], v[190:193], v[74:77]
	v_mfma_f32_16x16x32_bf16 v[74:77], v[202:205], v[194:197], v[74:77]
	v_mfma_f32_16x16x32_bf16 v[114:117], v[206:209], v[162:165], v[114:117]
	v_mfma_f32_16x16x32_bf16 v[114:117], v[210:213], v[166:169], v[114:117]
	v_mfma_f32_16x16x32_bf16 v[98:101], v[206:209], v[170:173], v[98:101]
	v_mfma_f32_16x16x32_bf16 v[98:101], v[210:213], v[174:177], v[98:101]
	v_mfma_f32_16x16x32_bf16 v[82:85], v[206:209], v[182:185], v[82:85]
	v_mfma_f32_16x16x32_bf16 v[82:85], v[210:213], v[186:189], v[82:85]
	v_mfma_f32_16x16x32_bf16 v[66:69], v[206:209], v[190:193], v[66:69]
	v_mfma_f32_16x16x32_bf16 v[66:69], v[210:213], v[194:197], v[66:69]
	s_barrier
	ds_read_b128 v[162:165], v145 offset:16384
	ds_read_b128 v[166:169], v145 offset:17408
	ds_read_b128 v[170:173], v145 offset:18432
	ds_read_b128 v[174:177], v145 offset:19456
	ds_read_b128 v[182:185], v145 offset:20480
	ds_read_b128 v[186:189], v145 offset:21504
	ds_read_b128 v[190:193], v145 offset:22528
	ds_read_b128 v[194:197], v145 offset:23552
	s_add_i32 s35, s35, s46
	s_mov_b32 m0, s35
	s_nop 0
	global_load_lds_dwordx4 v178, s[50:51]
	s_add_i32 m0, s35, 0x2000
	s_nop 0
	global_load_lds_dwordx4 v134, s[50:51]
	s_add_u32 s64, s50, 0x80000
	s_addc_u32 s65, s51, 0
	s_add_i32 s35, s66, s46
	s_mov_b32 m0, s35
	s_nop 0
	global_load_lds_dwordx4 v178, s[64:65]
	s_add_i32 m0, s35, 0x2000
	s_nop 0
	global_load_lds_dwordx4 v134, s[64:65]
	s_waitcnt vmcnt(4)
	s_waitcnt lgkmcnt(0)
	s_barrier
	v_mfma_f32_16x16x32_bf16 v[62:65], v[146:149], v[162:165], v[62:65]
	v_mfma_f32_16x16x32_bf16 v[62:65], v[150:153], v[166:169], v[62:65]
	v_mfma_f32_16x16x32_bf16 v[46:49], v[146:149], v[170:173], v[46:49]
	v_mfma_f32_16x16x32_bf16 v[46:49], v[150:153], v[174:177], v[46:49]
	v_mfma_f32_16x16x32_bf16 v[30:33], v[146:149], v[182:185], v[30:33]
	v_mfma_f32_16x16x32_bf16 v[30:33], v[150:153], v[186:189], v[30:33]
	v_mfma_f32_16x16x32_bf16 v[14:17], v[146:149], v[190:193], v[14:17]
	v_mfma_f32_16x16x32_bf16 v[14:17], v[150:153], v[194:197], v[14:17]
	v_mfma_f32_16x16x32_bf16 v[54:57], v[154:157], v[162:165], v[54:57]
	v_mfma_f32_16x16x32_bf16 v[54:57], v[158:161], v[166:169], v[54:57]
	v_mfma_f32_16x16x32_bf16 v[38:41], v[154:157], v[170:173], v[38:41]
	v_mfma_f32_16x16x32_bf16 v[38:41], v[158:161], v[174:177], v[38:41]
	v_mfma_f32_16x16x32_bf16 v[22:25], v[154:157], v[182:185], v[22:25]
	v_mfma_f32_16x16x32_bf16 v[22:25], v[158:161], v[186:189], v[22:25]
	v_mfma_f32_16x16x32_bf16 v[6:9], v[154:157], v[190:193], v[6:9]
	v_mfma_f32_16x16x32_bf16 v[6:9], v[158:161], v[194:197], v[6:9]
	v_mfma_f32_16x16x32_bf16 v[58:61], v[198:201], v[162:165], v[58:61]
	v_mfma_f32_16x16x32_bf16 v[58:61], v[202:205], v[166:169], v[58:61]
	v_mfma_f32_16x16x32_bf16 v[42:45], v[198:201], v[170:173], v[42:45]
	v_mfma_f32_16x16x32_bf16 v[42:45], v[202:205], v[174:177], v[42:45]
	v_mfma_f32_16x16x32_bf16 v[26:29], v[198:201], v[182:185], v[26:29]
	v_mfma_f32_16x16x32_bf16 v[26:29], v[202:205], v[186:189], v[26:29]
	v_mfma_f32_16x16x32_bf16 v[10:13], v[198:201], v[190:193], v[10:13]
	v_mfma_f32_16x16x32_bf16 v[10:13], v[202:205], v[194:197], v[10:13]
	v_mfma_f32_16x16x32_bf16 v[50:53], v[206:209], v[162:165], v[50:53]
	v_mfma_f32_16x16x32_bf16 v[50:53], v[210:213], v[166:169], v[50:53]
	v_mfma_f32_16x16x32_bf16 v[34:37], v[206:209], v[170:173], v[34:37]
	v_mfma_f32_16x16x32_bf16 v[34:37], v[210:213], v[174:177], v[34:37]
	v_mfma_f32_16x16x32_bf16 v[18:21], v[206:209], v[182:185], v[18:21]
	v_mfma_f32_16x16x32_bf16 v[18:21], v[210:213], v[186:189], v[18:21]
	v_mfma_f32_16x16x32_bf16 v[2:5], v[206:209], v[190:193], v[2:5]
	v_mfma_f32_16x16x32_bf16 v[2:5], v[210:213], v[194:197], v[2:5]
	s_add_i32 s35, 0, 0x18000
	v_add_u32_e32 v1, s35, v143
	s_barrier
; #define PG8_STAGE(bufoff, gbase, voff) do { _Pragma("unroll") for (int _i = 0; _i < 2; ++_i) \
;         __builtin_amdgcn_global_load_lds((const unsigned*)((const char*)(gbase) + (voff)[_i]), (LAS unsigned*)(lds + (bufoff) + ldsw + _i * 8192), 16, 0, 0); } while (0)
; #define PG8_LDA(dst, b, h) do { _Pragma("unroll") for (int m = 0; m < 4; ++m) _Pragma("unroll") for (int k = 0; k < 2; ++k) dst[m][k] = *(const LAS bf16x8*)(lds + PG8_SA(b, h) + aoff + m * 2048 + k * 1024); } while (0)
; #define PG8_LDB(dst, b, h) do { _Pragma("unroll") for (int n = 0; n < 2; ++n) _Pragma("unroll") for (int k = 0; k < 2; ++k) dst[n][k] = *(const LAS bf16x8*)(lds + PG8_SB(b, h) + boff + n * 2048 + k * 1024); } while (0)
; #define PG8_WAIT_V(n) asm volatile("s_waitcnt vmcnt(" #n ")" ::: "memory")
; #define PG8_WAIT_L(n) asm volatile("s_waitcnt lgkmcnt(" #n ")" ::: "memory")
; #define PG8_BAR __builtin_amdgcn_s_barrier()
; #define PG8_SCHED __builtin_amdgcn_sched_barrier(0)
; template <class Epi, class Sched>
; __device__ __forceinline__ void gemm_phase(LAS unsigned char* lds, const Gemm g, const Sched& S, const Epi& E) {
;     ...
;             PG8_LDB(B0, 0, 0); PG8_SCHED; PG8_LDA(At, 0, 0); PG8_STAGE(PG8_SA(1, 1), a1 + hstepA, voffA);
;             PG8_WAIT_L(8); PG8_BAR; PG8_WAIT_L(0); PG8_MMA(0, 0, At, B0); PG8_BAR; PG8_SCHED;
;             PG8_LDB(B1, 0, 1); PG8_STAGE(PG8_SB(0, 0), b2, voffB);
;             PG8_BAR; PG8_WAIT_L(0); PG8_MMA(0, 1, At, B1); PG8_BAR;
;             PG8_LDA(At, 0, 1); PG8_STAGE(PG8_SA(0, 0), a2, voffA);
;             PG8_BAR; PG8_WAIT_L(0); PG8_MMA(1, 0, At, B0); PG8_BAR; PG8_SCHED;
;             PG8_STAGE(PG8_SB(0, 1), b2 + hstepB, voffB);
;             PG8_WAIT_V(6); PG8_BAR; PG8_MMA(1, 1, At, B1); PG8_BAR;
;             PG8_LDB(B0, 1, 0); PG8_SCHED; PG8_LDA(At, 1, 0); PG8_STAGE(PG8_SA(0, 1), a2 + hstepA, voffA);
;             PG8_WAIT_L(8); PG8_BAR; PG8_WAIT_L(0); PG8_MMA(0, 0, At, B0); PG8_BAR; PG8_SCHED;
;             PG8_LDB(B1, 1, 1); PG8_STAGE(PG8_SB(1, 0), b3, voffB);
;             PG8_BAR; PG8_WAIT_L(0); PG8_MMA(0, 1, At, B1); PG8_BAR;
;             PG8_LDA(At, 1, 1); PG8_STAGE(PG8_SA(1, 0), a3, voffA);
;             PG8_BAR; PG8_WAIT_L(0); PG8_MMA(1, 0, At, B0); PG8_BAR; PG8_SCHED;
;             PG8_STAGE(PG8_SB(1, 1), b3 + hstepB, voffB);
;             PG8_WAIT_V(6); PG8_BAR; PG8_MMA(1, 1, At, B1); PG8_BAR;
;         }
	ds_read_b128 v[146:149], v1
	ds_read_b128 v[150:153], v1 offset:1024
	ds_read_b128 v[154:157], v1 offset:2048
	ds_read_b128 v[158:161], v1 offset:3072
	ds_read_b128 v[162:165], v145 offset:32768
	ds_read_b128 v[166:169], v145 offset:33792
	ds_read_b128 v[170:173], v145 offset:34816
	ds_read_b128 v[174:177], v145 offset:35840
	ds_read_b128 v[182:185], v145 offset:36864
	ds_read_b128 v[186:189], v145 offset:37888
	ds_read_b128 v[190:193], v145 offset:38912
	ds_read_b128 v[194:197], v145 offset:39936
	s_mov_b32 m0, s23
	s_nop 0
	global_load_lds_dwordx4 v130, s[28:29]
	s_mov_b32 m0, s25
	s_nop 0
	global_load_lds_dwordx4 v132, s[28:29]
	s_add_u32 s28, s28, 0x80000
	s_addc_u32 s29, s29, 0
	s_mov_b32 m0, s52
	s_nop 0
	global_load_lds_dwordx4 v130, s[28:29]
	s_mov_b32 m0, s53
	s_nop 0
	global_load_lds_dwordx4 v132, s[28:29]
	s_add_i32 s64, 0, 0x1c000
	v_add_u32_e32 v1, s64, v143
	ds_read_b128 v[198:201], v1
	ds_read_b128 v[202:205], v1 offset:1024
	ds_read_b128 v[206:209], v1 offset:2048
	ds_read_b128 v[210:213], v1 offset:3072
	s_waitcnt lgkmcnt(0)
	s_barrier
	v_mfma_f32_16x16x32_bf16 v[126:129], v[146:149], v[162:165], v[126:129]
	v_mfma_f32_16x16x32_bf16 v[126:129], v[150:153], v[166:169], v[126:129]
	v_mfma_f32_16x16x32_bf16 v[110:113], v[146:149], v[170:173], v[110:113]
	v_mfma_f32_16x16x32_bf16 v[110:113], v[150:153], v[174:177], v[110:113]
	v_mfma_f32_16x16x32_bf16 v[94:97], v[146:149], v[182:185], v[94:97]
	v_mfma_f32_16x16x32_bf16 v[94:97], v[150:153], v[186:189], v[94:97]
	v_mfma_f32_16x16x32_bf16 v[78:81], v[146:149], v[190:193], v[78:81]
	v_mfma_f32_16x16x32_bf16 v[78:81], v[150:153], v[194:197], v[78:81]
	v_mfma_f32_16x16x32_bf16 v[118:121], v[154:157], v[162:165], v[118:121]
	v_mfma_f32_16x16x32_bf16 v[118:121], v[158:161], v[166:169], v[118:121]
	v_mfma_f32_16x16x32_bf16 v[102:105], v[154:157], v[170:173], v[102:105]
	v_mfma_f32_16x16x32_bf16 v[102:105], v[158:161], v[174:177], v[102:105]
	v_mfma_f32_16x16x32_bf16 v[86:89], v[154:157], v[182:185], v[86:89]
	v_mfma_f32_16x16x32_bf16 v[86:89], v[158:161], v[186:189], v[86:89]
	v_mfma_f32_16x16x32_bf16 v[70:73], v[154:157], v[190:193], v[70:73]
	v_mfma_f32_16x16x32_bf16 v[70:73], v[158:161], v[194:197], v[70:73]
	v_mfma_f32_16x16x32_bf16 v[122:125], v[198:201], v[162:165], v[122:125]
	v_mfma_f32_16x16x32_bf16 v[122:125], v[202:205], v[166:169], v[122:125]
	v_mfma_f32_16x16x32_bf16 v[106:109], v[198:201], v[170:173], v[106:109]
	v_mfma_f32_16x16x32_bf16 v[106:109], v[202:205], v[174:177], v[106:109]
	v_mfma_f32_16x16x32_bf16 v[90:93], v[198:201], v[182:185], v[90:93]
	v_mfma_f32_16x16x32_bf16 v[90:93], v[202:205], v[186:189], v[90:93]
	v_mfma_f32_16x16x32_bf16 v[74:77], v[198:201], v[190:193], v[74:77]
	v_mfma_f32_16x16x32_bf16 v[74:77], v[202:205], v[194:197], v[74:77]
	v_mfma_f32_16x16x32_bf16 v[114:117], v[206:209], v[162:165], v[114:117]
	v_mfma_f32_16x16x32_bf16 v[114:117], v[210:213], v[166:169], v[114:117]
	v_mfma_f32_16x16x32_bf16 v[98:101], v[206:209], v[170:173], v[98:101]
	v_mfma_f32_16x16x32_bf16 v[98:101], v[210:213], v[174:177], v[98:101]
	v_mfma_f32_16x16x32_bf16 v[82:85], v[206:209], v[182:185], v[82:85]
	v_mfma_f32_16x16x32_bf16 v[82:85], v[210:213], v[186:189], v[82:85]
	v_mfma_f32_16x16x32_bf16 v[66:69], v[206:209], v[190:193], v[66:69]
	v_mfma_f32_16x16x32_bf16 v[66:69], v[210:213], v[194:197], v[66:69]
	s_barrier
	ds_read_b128 v[162:165], v145 offset:49152
	ds_read_b128 v[166:169], v145 offset:50176
	ds_read_b128 v[170:173], v145 offset:51200
	ds_read_b128 v[174:177], v145 offset:52224
	ds_read_b128 v[182:185], v145 offset:53248
	ds_read_b128 v[186:189], v145 offset:54272
	ds_read_b128 v[190:193], v145 offset:55296
	ds_read_b128 v[194:197], v145 offset:56320
	s_add_u32 s98, s50, 0x80
	s_addc_u32 s99, s51, 0
	s_add_i32 s28, s35, s46
	s_mov_b32 m0, s28
	s_nop 0
	global_load_lds_dwordx4 v178, s[98:99]
	s_add_i32 m0, s28, 0x2000
	s_nop 0
	global_load_lds_dwordx4 v134, s[98:99]
	s_add_u32 s28, s50, 0x80080
	s_addc_u32 s29, s51, 0
	s_add_i32 s35, s64, s46
	s_mov_b32 m0, s35
	s_nop 0
	global_load_lds_dwordx4 v178, s[28:29]
	s_add_i32 m0, s35, 0x2000
	s_nop 0
	global_load_lds_dwordx4 v134, s[28:29]
	s_waitcnt vmcnt(4)
	s_waitcnt lgkmcnt(0)
	s_barrier
	v_mfma_f32_16x16x32_bf16 v[62:65], v[146:149], v[162:165], v[62:65]
	v_mfma_f32_16x16x32_bf16 v[62:65], v[150:153], v[166:169], v[62:65]
	v_mfma_f32_16x16x32_bf16 v[46:49], v[146:149], v[170:173], v[46:49]
	v_mfma_f32_16x16x32_bf16 v[46:49], v[150:153], v[174:177], v[46:49]
	v_mfma_f32_16x16x32_bf16 v[30:33], v[146:149], v[182:185], v[30:33]
	v_mfma_f32_16x16x32_bf16 v[30:33], v[150:153], v[186:189], v[30:33]
	v_mfma_f32_16x16x32_bf16 v[14:17], v[146:149], v[190:193], v[14:17]
	v_mfma_f32_16x16x32_bf16 v[14:17], v[150:153], v[194:197], v[14:17]
	v_mfma_f32_16x16x32_bf16 v[54:57], v[154:157], v[162:165], v[54:57]
	v_mfma_f32_16x16x32_bf16 v[54:57], v[158:161], v[166:169], v[54:57]
	v_mfma_f32_16x16x32_bf16 v[38:41], v[154:157], v[170:173], v[38:41]
	v_mfma_f32_16x16x32_bf16 v[38:41], v[158:161], v[174:177], v[38:41]
	v_mfma_f32_16x16x32_bf16 v[22:25], v[154:157], v[182:185], v[22:25]
	v_mfma_f32_16x16x32_bf16 v[22:25], v[158:161], v[186:189], v[22:25]
	v_mfma_f32_16x16x32_bf16 v[6:9], v[154:157], v[190:193], v[6:9]
	v_mfma_f32_16x16x32_bf16 v[6:9], v[158:161], v[194:197], v[6:9]
	v_mfma_f32_16x16x32_bf16 v[58:61], v[198:201], v[162:165], v[58:61]
	v_mfma_f32_16x16x32_bf16 v[58:61], v[202:205], v[166:169], v[58:61]
	v_mfma_f32_16x16x32_bf16 v[42:45], v[198:201], v[170:173], v[42:45]
	v_mfma_f32_16x16x32_bf16 v[42:45], v[202:205], v[174:177], v[42:45]
	v_mfma_f32_16x16x32_bf16 v[26:29], v[198:201], v[182:185], v[26:29]
	v_mfma_f32_16x16x32_bf16 v[26:29], v[202:205], v[186:189], v[26:29]
	v_mfma_f32_16x16x32_bf16 v[10:13], v[198:201], v[190:193], v[10:13]
	v_mfma_f32_16x16x32_bf16 v[10:13], v[202:205], v[194:197], v[10:13]
	v_mfma_f32_16x16x32_bf16 v[50:53], v[206:209], v[162:165], v[50:53]
	v_mfma_f32_16x16x32_bf16 v[50:53], v[210:213], v[166:169], v[50:53]
	v_mfma_f32_16x16x32_bf16 v[34:37], v[206:209], v[170:173], v[34:37]
	v_mfma_f32_16x16x32_bf16 v[34:37], v[210:213], v[174:177], v[34:37]
	v_mfma_f32_16x16x32_bf16 v[18:21], v[206:209], v[182:185], v[18:21]
	v_mfma_f32_16x16x32_bf16 v[18:21], v[210:213], v[186:189], v[18:21]
	v_mfma_f32_16x16x32_bf16 v[2:5], v[206:209], v[190:193], v[2:5]
	v_mfma_f32_16x16x32_bf16 v[2:5], v[210:213], v[194:197], v[2:5]
	s_add_i32 s63, s63, 2
	s_add_u32 s26, s26, 0x100
	s_addc_u32 s27, s27, 0
	s_add_u32 s59, s59, 0x100
	s_addc_u32 s62, s62, 0
	s_cmp_gt_u32 s63, 29
	s_barrier
; __device__ __forceinline__ unsigned cvt_pk_bf16(float lo, float hi) { const f32x2_t v = {lo, hi}; return __builtin_bit_cast(unsigned, __builtin_convertvector(v, bf16x2_t)); }
;     __device__ __forceinline__ void operator()(f32x4 (&acc)[2][2][4][2], const Unit& u, int wr, int wc, int fr, int fq) const {
;         const int row0 = u.pm * BM + wr * 64 + fr, col0 = u.pn * HALF + wc * 32 + 8 * fq;
; #pragma unroll
;         for (int ai = 0; ai < 2; ++ai)
; #pragma unroll
;             for (int m = 0; m < 4; ++m) { bf16_t* rowp = O + (size_t)(row0 + ai * HALF + m * 16) * FF + col0;
;                 float h[8];
; #pragma unroll
;                 for (int n = 0; n < 2; ++n)
; #pragma unroll
;                     for (int e = 0; e < 4; ++e) { const float g = acc[ai][0][m][n][e], up = acc[ai][1][m][n][e]; h[n * 4 + e] = g * __builtin_amdgcn_rcpf(1.0f + __builtin_amdgcn_exp2f(-1.4426950408889634f * g)) * up; }
;                 u32x4 w; w.x = cvt_pk_bf16(h[0], h[1]); w.y = cvt_pk_bf16(h[2], h[3]); w.z = cvt_pk_bf16(h[4], h[5]); w.w = cvt_pk_bf16(h[6], h[7]);
;                 __builtin_nontemporal_store(w, (u32x4*)rowp); }
	s_cbranch_scc0 .LBB0_1140
	v_mul_f32_e32 v1, 0xbfb8aa3b, v126
	v_exp_f32_e32 v1, v1
	v_lshl_or_b32 v148, s22, 7, v144
	v_lshl_add_u32 v146, s24, 8, v142
	v_ashrrev_i32_e32 v149, 31, v148
	v_add_f32_e32 v1, 1.0, v1
	v_rcp_f32_e32 v152, v1
	v_mul_f32_e32 v1, 0xbfb8aa3b, v127
	v_exp_f32_e32 v1, v1
	v_mov_b64_e32 v[140:141], s[8:9]
	v_mad_i64_i32 v[150:151], s[26:27], v146, s61, v[140:141]
	v_add_f32_e32 v1, 1.0, v1
	v_rcp_f32_e32 v153, v1
	v_mul_f32_e32 v1, 0xbfb8aa3b, v128
	v_exp_f32_e32 v1, v1
	s_and_b64 vcc, exec, s[6:7]
	v_pk_mul_f32 v[126:127], v[126:127], v[152:153]
	s_mov_b32 s22, s10
	v_add_f32_e32 v1, 1.0, v1
	v_pk_mul_f32 v[122:123], v[126:127], v[122:123]
	v_rcp_f32_e32 v126, v1
	v_mul_f32_e32 v1, 0xbfb8aa3b, v129
	v_exp_f32_e32 v1, v1
	s_mov_b32 s24, s12
	s_mov_b64 s[50:51], s[20:21]
	v_add_f32_e32 v1, 1.0, v1
	v_rcp_f32_e32 v127, v1
	v_mul_f32_e32 v1, 0xbfb8aa3b, v118
	v_exp_f32_e32 v1, v1
	v_pk_mul_f32 v[126:127], v[128:129], v[126:127]
	s_nop 0
	v_pk_mul_f32 v[124:125], v[126:127], v[124:125]
	v_add_f32_e32 v1, 1.0, v1
	v_rcp_f32_e32 v126, v1
	v_mul_f32_e32 v1, 0xbfb8aa3b, v119
	v_exp_f32_e32 v1, v1
	s_nop 0
	v_add_f32_e32 v1, 1.0, v1
	v_rcp_f32_e32 v127, v1
	v_mul_f32_e32 v1, 0xbfb8aa3b, v120
	v_exp_f32_e32 v1, v1
	v_pk_mul_f32 v[118:119], v[118:119], v[126:127]
	s_nop 0
	v_pk_mul_f32 v[118:119], v[118:119], v[114:115]
	v_add_f32_e32 v1, 1.0, v1
	v_rcp_f32_e32 v114, v1
	v_mul_f32_e32 v1, 0xbfb8aa3b, v121
	v_exp_f32_e32 v1, v1
	v_cvt_pk_bf16_f32 v118, v118, v119
	v_add_f32_e32 v1, 1.0, v1
	v_rcp_f32_e32 v115, v1
	v_or_b32_e32 v1, 16, v146
	v_pk_mul_f32 v[114:115], v[120:121], v[114:115]
	s_nop 0
	v_pk_mul_f32 v[120:121], v[114:115], v[116:117]
	v_lshlrev_b64 v[114:115], 1, v[148:149]
	v_lshl_add_u64 v[126:127], v[150:151], 0, v[114:115]
	v_cvt_pk_bf16_f32 v116, v122, v123
	v_cvt_pk_bf16_f32 v117, v124, v125
	v_cvt_pk_bf16_f32 v119, v120, v121
	global_store_dwordx4 v[126:127], v[116:119], off nt
	s_nop 1
	v_mad_i64_i32 v[116:117], s[26:27], v1, s61, v[140:141]
	v_mul_f32_e32 v1, 0xbfb8aa3b, v110
	v_exp_f32_e32 v1, v1
	s_nop 0
	v_add_f32_e32 v1, 1.0, v1
	v_rcp_f32_e32 v118, v1
	v_mul_f32_e32 v1, 0xbfb8aa3b, v111
	v_exp_f32_e32 v1, v1
	s_nop 0
	v_add_f32_e32 v1, 1.0, v1
	v_rcp_f32_e32 v119, v1
	v_mul_f32_e32 v1, 0xbfb8aa3b, v112
	v_exp_f32_e32 v1, v1
	v_pk_mul_f32 v[110:111], v[110:111], v[118:119]
	s_nop 0
	v_pk_mul_f32 v[106:107], v[110:111], v[106:107]
	v_add_f32_e32 v1, 1.0, v1
	v_rcp_f32_e32 v110, v1
	v_mul_f32_e32 v1, 0xbfb8aa3b, v113
	v_exp_f32_e32 v1, v1
	s_nop 0
	v_add_f32_e32 v1, 1.0, v1
	v_rcp_f32_e32 v111, v1
	v_mul_f32_e32 v1, 0xbfb8aa3b, v102
	v_exp_f32_e32 v1, v1
	v_pk_mul_f32 v[110:111], v[112:113], v[110:111]
	s_nop 0
	v_pk_mul_f32 v[108:109], v[110:111], v[108:109]
	v_add_f32_e32 v1, 1.0, v1
	v_rcp_f32_e32 v110, v1
	v_mul_f32_e32 v1, 0xbfb8aa3b, v103
	v_exp_f32_e32 v1, v1
	s_nop 0
	v_add_f32_e32 v1, 1.0, v1
	v_rcp_f32_e32 v111, v1
	v_mul_f32_e32 v1, 0xbfb8aa3b, v104
	v_exp_f32_e32 v1, v1
	v_pk_mul_f32 v[102:103], v[102:103], v[110:111]
	s_nop 0
	v_pk_mul_f32 v[102:103], v[102:103], v[98:99]
	v_add_f32_e32 v1, 1.0, v1
	v_rcp_f32_e32 v98, v1
	v_mul_f32_e32 v1, 0xbfb8aa3b, v105
	v_exp_f32_e32 v1, v1
	v_lshl_add_u64 v[110:111], v[116:117], 0, v[114:115]
	v_add_f32_e32 v1, 1.0, v1
	v_rcp_f32_e32 v99, v1
	v_or_b32_e32 v1, 32, v146
	v_pk_mul_f32 v[98:99], v[104:105], v[98:99]
	s_nop 0
	v_pk_mul_f32 v[104:105], v[98:99], v[100:101]
	v_cvt_pk_bf16_f32 v98, v106, v107
	v_cvt_pk_bf16_f32 v99, v108, v109
	v_cvt_pk_bf16_f32 v100, v102, v103
	v_cvt_pk_bf16_f32 v101, v104, v105
	global_store_dwordx4 v[110:111], v[98:101], off nt
	s_nop 1
	v_mad_i64_i32 v[98:99], s[26:27], v1, s61, v[140:141]
	v_mul_f32_e32 v1, 0xbfb8aa3b, v94
	v_exp_f32_e32 v1, v1
	s_nop 0
	v_add_f32_e32 v1, 1.0, v1
	v_rcp_f32_e32 v100, v1
	v_mul_f32_e32 v1, 0xbfb8aa3b, v95
	v_exp_f32_e32 v1, v1
	s_nop 0
	v_add_f32_e32 v1, 1.0, v1
	v_rcp_f32_e32 v101, v1
	v_mul_f32_e32 v1, 0xbfb8aa3b, v96
	v_exp_f32_e32 v1, v1
	v_pk_mul_f32 v[94:95], v[94:95], v[100:101]
	s_nop 0
	v_pk_mul_f32 v[90:91], v[94:95], v[90:91]
	v_add_f32_e32 v1, 1.0, v1
	v_rcp_f32_e32 v94, v1
	v_mul_f32_e32 v1, 0xbfb8aa3b, v97
	v_exp_f32_e32 v1, v1
	s_nop 0
	v_add_f32_e32 v1, 1.0, v1
	v_rcp_f32_e32 v95, v1
	v_mul_f32_e32 v1, 0xbfb8aa3b, v86
	v_exp_f32_e32 v1, v1
	v_pk_mul_f32 v[94:95], v[96:97], v[94:95]
	s_nop 0
	v_pk_mul_f32 v[92:93], v[94:95], v[92:93]
	v_add_f32_e32 v1, 1.0, v1
	v_rcp_f32_e32 v94, v1
	v_mul_f32_e32 v1, 0xbfb8aa3b, v87
	v_exp_f32_e32 v1, v1
	s_nop 0
	v_add_f32_e32 v1, 1.0, v1
	v_rcp_f32_e32 v95, v1
	v_mul_f32_e32 v1, 0xbfb8aa3b, v88
	v_exp_f32_e32 v1, v1
	v_pk_mul_f32 v[86:87], v[86:87], v[94:95]
	s_nop 0
	v_pk_mul_f32 v[86:87], v[86:87], v[82:83]
	v_add_f32_e32 v1, 1.0, v1
	v_rcp_f32_e32 v82, v1
	v_mul_f32_e32 v1, 0xbfb8aa3b, v89
	v_exp_f32_e32 v1, v1
	v_lshl_add_u64 v[94:95], v[98:99], 0, v[114:115]
	v_add_f32_e32 v1, 1.0, v1
	v_rcp_f32_e32 v83, v1
	v_or_b32_e32 v1, 48, v146
	v_pk_mul_f32 v[82:83], v[88:89], v[82:83]
	s_nop 0
	v_pk_mul_f32 v[88:89], v[82:83], v[84:85]
	v_cvt_pk_bf16_f32 v82, v90, v91
	v_cvt_pk_bf16_f32 v83, v92, v93
	v_cvt_pk_bf16_f32 v84, v86, v87
	v_cvt_pk_bf16_f32 v85, v88, v89
	global_store_dwordx4 v[94:95], v[82:85], off nt
	s_nop 1
	v_mad_i64_i32 v[82:83], s[26:27], v1, s61, v[140:141]
	v_mul_f32_e32 v1, 0xbfb8aa3b, v78
	v_exp_f32_e32 v1, v1
	s_nop 0
	v_add_f32_e32 v1, 1.0, v1
	v_rcp_f32_e32 v84, v1
	v_mul_f32_e32 v1, 0xbfb8aa3b, v79
	v_exp_f32_e32 v1, v1
	s_nop 0
	v_add_f32_e32 v1, 1.0, v1
	v_rcp_f32_e32 v85, v1
	v_mul_f32_e32 v1, 0xbfb8aa3b, v80
	v_exp_f32_e32 v1, v1
	v_pk_mul_f32 v[78:79], v[78:79], v[84:85]
	s_nop 0
	v_pk_mul_f32 v[74:75], v[78:79], v[74:75]
; __device__ __forceinline__ unsigned cvt_pk_bf16(float lo, float hi) { const f32x2_t v = {lo, hi}; return __builtin_bit_cast(unsigned, __builtin_convertvector(v, bf16x2_t)); }
;     __device__ __forceinline__ void operator()(f32x4 (&acc)[2][2][4][2], const Unit& u, int wr, int wc, int fr, int fq) const {
;         const int row0 = u.pm * BM + wr * 64 + fr, col0 = u.pn * HALF + wc * 32 + 8 * fq;
; #pragma unroll
;         for (int ai = 0; ai < 2; ++ai)
; #pragma unroll
;             for (int m = 0; m < 4; ++m) { bf16_t* rowp = O + (size_t)(row0 + ai * HALF + m * 16) * FF + col0;
;                 float h[8];
; #pragma unroll
;                 for (int n = 0; n < 2; ++n)
; #pragma unroll
;                     for (int e = 0; e < 4; ++e) { const float g = acc[ai][0][m][n][e], up = acc[ai][1][m][n][e]; h[n * 4 + e] = g * __builtin_amdgcn_rcpf(1.0f + __builtin_amdgcn_exp2f(-1.4426950408889634f * g)) * up; }
;                 u32x4 w; w.x = cvt_pk_bf16(h[0], h[1]); w.y = cvt_pk_bf16(h[2], h[3]); w.z = cvt_pk_bf16(h[4], h[5]); w.w = cvt_pk_bf16(h[6], h[7]);
;                 __builtin_nontemporal_store(w, (u32x4*)rowp); }
	v_add_f32_e32 v1, 1.0, v1
	v_rcp_f32_e32 v78, v1
	v_mul_f32_e32 v1, 0xbfb8aa3b, v81
	v_exp_f32_e32 v1, v1
	s_nop 0
	v_add_f32_e32 v1, 1.0, v1
	v_rcp_f32_e32 v79, v1
	v_mul_f32_e32 v1, 0xbfb8aa3b, v70
	v_exp_f32_e32 v1, v1
	v_pk_mul_f32 v[78:79], v[80:81], v[78:79]
	s_nop 0
	v_pk_mul_f32 v[76:77], v[78:79], v[76:77]
	v_add_f32_e32 v1, 1.0, v1
	v_rcp_f32_e32 v78, v1
	v_mul_f32_e32 v1, 0xbfb8aa3b, v71
	v_exp_f32_e32 v1, v1
	s_nop 0
	v_add_f32_e32 v1, 1.0, v1
	v_rcp_f32_e32 v79, v1
	v_mul_f32_e32 v1, 0xbfb8aa3b, v72
	v_exp_f32_e32 v1, v1
	v_pk_mul_f32 v[70:71], v[70:71], v[78:79]
	s_nop 0
	v_pk_mul_f32 v[70:71], v[70:71], v[66:67]
	v_add_f32_e32 v1, 1.0, v1
	v_rcp_f32_e32 v66, v1
	v_mul_f32_e32 v1, 0xbfb8aa3b, v73
	v_exp_f32_e32 v1, v1
	v_lshl_add_u64 v[78:79], v[82:83], 0, v[114:115]
	v_add_f32_e32 v1, 1.0, v1
	v_rcp_f32_e32 v67, v1
	v_add_u32_e32 v1, 0x80, v146
	v_pk_mul_f32 v[66:67], v[72:73], v[66:67]
	s_nop 0
	v_pk_mul_f32 v[72:73], v[66:67], v[68:69]
	v_cvt_pk_bf16_f32 v66, v74, v75
	v_cvt_pk_bf16_f32 v67, v76, v77
	v_cvt_pk_bf16_f32 v68, v70, v71
	v_cvt_pk_bf16_f32 v69, v72, v73
	global_store_dwordx4 v[78:79], v[66:69], off nt
	s_nop 1
	v_mad_i64_i32 v[66:67], s[26:27], v1, s61, v[140:141]
	v_mul_f32_e32 v1, 0xbfb8aa3b, v62
	v_exp_f32_e32 v1, v1
	s_nop 0
	v_add_f32_e32 v1, 1.0, v1
	v_rcp_f32_e32 v68, v1
	v_mul_f32_e32 v1, 0xbfb8aa3b, v63
	v_exp_f32_e32 v1, v1
	s_nop 0
	v_add_f32_e32 v1, 1.0, v1
	v_rcp_f32_e32 v69, v1
	v_mul_f32_e32 v1, 0xbfb8aa3b, v64
	v_exp_f32_e32 v1, v1
	v_pk_mul_f32 v[62:63], v[62:63], v[68:69]
	s_nop 0
	v_pk_mul_f32 v[58:59], v[62:63], v[58:59]
	v_add_f32_e32 v1, 1.0, v1
	v_rcp_f32_e32 v62, v1
	v_mul_f32_e32 v1, 0xbfb8aa3b, v65
	v_exp_f32_e32 v1, v1
	s_nop 0
	v_add_f32_e32 v1, 1.0, v1
	v_rcp_f32_e32 v63, v1
	v_mul_f32_e32 v1, 0xbfb8aa3b, v54
	v_exp_f32_e32 v1, v1
	v_pk_mul_f32 v[62:63], v[64:65], v[62:63]
	s_nop 0
	v_pk_mul_f32 v[60:61], v[62:63], v[60:61]
	v_add_f32_e32 v1, 1.0, v1
	v_rcp_f32_e32 v62, v1
	v_mul_f32_e32 v1, 0xbfb8aa3b, v55
	v_exp_f32_e32 v1, v1
	s_nop 0
	v_add_f32_e32 v1, 1.0, v1
	v_rcp_f32_e32 v63, v1
	v_mul_f32_e32 v1, 0xbfb8aa3b, v56
	v_exp_f32_e32 v1, v1
	v_pk_mul_f32 v[54:55], v[54:55], v[62:63]
	s_nop 0
	v_pk_mul_f32 v[54:55], v[54:55], v[50:51]
	v_add_f32_e32 v1, 1.0, v1
	v_rcp_f32_e32 v50, v1
	v_mul_f32_e32 v1, 0xbfb8aa3b, v57
	v_exp_f32_e32 v1, v1
	v_lshl_add_u64 v[62:63], v[66:67], 0, v[114:115]
	v_add_f32_e32 v1, 1.0, v1
	v_rcp_f32_e32 v51, v1
	v_add_u32_e32 v1, 0x90, v146
	v_pk_mul_f32 v[50:51], v[56:57], v[50:51]
	s_nop 0
	v_pk_mul_f32 v[56:57], v[50:51], v[52:53]
	v_cvt_pk_bf16_f32 v50, v58, v59
	v_cvt_pk_bf16_f32 v51, v60, v61
	v_cvt_pk_bf16_f32 v52, v54, v55
	v_cvt_pk_bf16_f32 v53, v56, v57
	global_store_dwordx4 v[62:63], v[50:53], off nt
	s_nop 1
	v_mad_i64_i32 v[50:51], s[26:27], v1, s61, v[140:141]
	v_mul_f32_e32 v1, 0xbfb8aa3b, v46
	v_exp_f32_e32 v1, v1
	s_nop 0
	v_add_f32_e32 v1, 1.0, v1
	v_rcp_f32_e32 v52, v1
	v_mul_f32_e32 v1, 0xbfb8aa3b, v47
	v_exp_f32_e32 v1, v1
	s_nop 0
	v_add_f32_e32 v1, 1.0, v1
	v_rcp_f32_e32 v53, v1
	v_mul_f32_e32 v1, 0xbfb8aa3b, v48
	v_exp_f32_e32 v1, v1
	v_pk_mul_f32 v[46:47], v[46:47], v[52:53]
	s_nop 0
	v_pk_mul_f32 v[42:43], v[46:47], v[42:43]
	v_add_f32_e32 v1, 1.0, v1
	v_rcp_f32_e32 v46, v1
	v_mul_f32_e32 v1, 0xbfb8aa3b, v49
	v_exp_f32_e32 v1, v1
	s_nop 0
	v_add_f32_e32 v1, 1.0, v1
	v_rcp_f32_e32 v47, v1
	v_mul_f32_e32 v1, 0xbfb8aa3b, v38
	v_exp_f32_e32 v1, v1
	v_pk_mul_f32 v[46:47], v[48:49], v[46:47]
	s_nop 0
	v_pk_mul_f32 v[44:45], v[46:47], v[44:45]
	v_add_f32_e32 v1, 1.0, v1
	v_rcp_f32_e32 v46, v1
	v_mul_f32_e32 v1, 0xbfb8aa3b, v39
	v_exp_f32_e32 v1, v1
	s_nop 0
	v_add_f32_e32 v1, 1.0, v1
	v_rcp_f32_e32 v47, v1
	v_mul_f32_e32 v1, 0xbfb8aa3b, v40
	v_exp_f32_e32 v1, v1
	v_pk_mul_f32 v[38:39], v[38:39], v[46:47]
	s_nop 0
; __device__ __forceinline__ unsigned cvt_pk_bf16(float lo, float hi) { const f32x2_t v = {lo, hi}; return __builtin_bit_cast(unsigned, __builtin_convertvector(v, bf16x2_t)); }
; #define PG8_WAIT_V(n) asm volatile("s_waitcnt vmcnt(" #n ")" ::: "memory")
; #define PG8_BAR __builtin_amdgcn_s_barrier()
;     __device__ __forceinline__ void operator()(f32x4 (&acc)[2][2][4][2], const Unit& u, int wr, int wc, int fr, int fq) const {
;         const int row0 = u.pm * BM + wr * 64 + fr, col0 = u.pn * HALF + wc * 32 + 8 * fq;
; #pragma unroll
;         for (int ai = 0; ai < 2; ++ai)
; #pragma unroll
;             for (int m = 0; m < 4; ++m) { bf16_t* rowp = O + (size_t)(row0 + ai * HALF + m * 16) * FF + col0;
;                 float h[8];
; #pragma unroll
;                 for (int n = 0; n < 2; ++n)
; #pragma unroll
;                     for (int e = 0; e < 4; ++e) { const float g = acc[ai][0][m][n][e], up = acc[ai][1][m][n][e]; h[n * 4 + e] = g * __builtin_amdgcn_rcpf(1.0f + __builtin_amdgcn_exp2f(-1.4426950408889634f * g)) * up; }
;                 u32x4 w; w.x = cvt_pk_bf16(h[0], h[1]); w.y = cvt_pk_bf16(h[2], h[3]); w.z = cvt_pk_bf16(h[4], h[5]); w.w = cvt_pk_bf16(h[6], h[7]);
;                 __builtin_nontemporal_store(w, (u32x4*)rowp); }
; template <class Epi, class Sched>
; __device__ __forceinline__ void gemm_phase(LAS unsigned char* lds, const Gemm g, const Sched& S, const Epi& E) {
;     ...
;     PG8_WAIT_V(0);
;     if (wr == 0) PG8_BAR;
;     PG8_BAR;
	v_pk_mul_f32 v[38:39], v[38:39], v[34:35]
	v_add_f32_e32 v1, 1.0, v1
	v_rcp_f32_e32 v34, v1
	v_mul_f32_e32 v1, 0xbfb8aa3b, v41
	v_exp_f32_e32 v1, v1
	v_lshl_add_u64 v[46:47], v[50:51], 0, v[114:115]
	v_add_f32_e32 v1, 1.0, v1
	v_rcp_f32_e32 v35, v1
	v_add_u32_e32 v1, 0xa0, v146
	v_pk_mul_f32 v[34:35], v[40:41], v[34:35]
	s_nop 0
	v_pk_mul_f32 v[40:41], v[34:35], v[36:37]
	v_cvt_pk_bf16_f32 v34, v42, v43
	v_cvt_pk_bf16_f32 v35, v44, v45
	v_cvt_pk_bf16_f32 v36, v38, v39
	v_cvt_pk_bf16_f32 v37, v40, v41
	global_store_dwordx4 v[46:47], v[34:37], off nt
	s_nop 1
	v_mad_i64_i32 v[34:35], s[26:27], v1, s61, v[140:141]
	v_mul_f32_e32 v1, 0xbfb8aa3b, v30
	v_exp_f32_e32 v1, v1
	s_nop 0
	v_add_f32_e32 v1, 1.0, v1
	v_rcp_f32_e32 v36, v1
	v_mul_f32_e32 v1, 0xbfb8aa3b, v31
	v_exp_f32_e32 v1, v1
	s_nop 0
	v_add_f32_e32 v1, 1.0, v1
	v_rcp_f32_e32 v37, v1
	v_mul_f32_e32 v1, 0xbfb8aa3b, v32
	v_exp_f32_e32 v1, v1
	v_pk_mul_f32 v[30:31], v[30:31], v[36:37]
	s_nop 0
	v_pk_mul_f32 v[26:27], v[30:31], v[26:27]
	v_add_f32_e32 v1, 1.0, v1
	v_rcp_f32_e32 v30, v1
	v_mul_f32_e32 v1, 0xbfb8aa3b, v33
	v_exp_f32_e32 v1, v1
	s_nop 0
	v_add_f32_e32 v1, 1.0, v1
	v_rcp_f32_e32 v31, v1
	v_mul_f32_e32 v1, 0xbfb8aa3b, v22
	v_exp_f32_e32 v1, v1
	v_pk_mul_f32 v[30:31], v[32:33], v[30:31]
	s_nop 0
	v_pk_mul_f32 v[28:29], v[30:31], v[28:29]
	v_add_f32_e32 v1, 1.0, v1
	v_rcp_f32_e32 v30, v1
	v_mul_f32_e32 v1, 0xbfb8aa3b, v23
	v_exp_f32_e32 v1, v1
	s_nop 0
	v_add_f32_e32 v1, 1.0, v1
	v_rcp_f32_e32 v31, v1
	v_mul_f32_e32 v1, 0xbfb8aa3b, v24
	v_exp_f32_e32 v1, v1
	v_pk_mul_f32 v[22:23], v[22:23], v[30:31]
	s_nop 0
	v_pk_mul_f32 v[22:23], v[22:23], v[18:19]
	v_add_f32_e32 v1, 1.0, v1
	v_rcp_f32_e32 v18, v1
	v_mul_f32_e32 v1, 0xbfb8aa3b, v25
	v_exp_f32_e32 v1, v1
	v_lshl_add_u64 v[30:31], v[34:35], 0, v[114:115]
	v_add_f32_e32 v1, 1.0, v1
	v_rcp_f32_e32 v19, v1
	v_add_u32_e32 v1, 0xb0, v146
	v_pk_mul_f32 v[18:19], v[24:25], v[18:19]
	s_nop 0
	v_pk_mul_f32 v[24:25], v[18:19], v[20:21]
	v_cvt_pk_bf16_f32 v18, v26, v27
	v_cvt_pk_bf16_f32 v19, v28, v29
	v_cvt_pk_bf16_f32 v20, v22, v23
	v_cvt_pk_bf16_f32 v21, v24, v25
	global_store_dwordx4 v[30:31], v[18:21], off nt
	s_nop 1
	v_mad_i64_i32 v[18:19], s[26:27], v1, s61, v[140:141]
	v_mul_f32_e32 v1, 0xbfb8aa3b, v14
	v_exp_f32_e32 v1, v1
	s_mov_b64 s[26:27], s[16:17]
	v_add_f32_e32 v1, 1.0, v1
	v_rcp_f32_e32 v20, v1
	v_mul_f32_e32 v1, 0xbfb8aa3b, v15
	v_exp_f32_e32 v1, v1
	s_nop 0
	v_add_f32_e32 v1, 1.0, v1
	v_rcp_f32_e32 v21, v1
	v_mul_f32_e32 v1, 0xbfb8aa3b, v16
	v_exp_f32_e32 v1, v1
	v_pk_mul_f32 v[14:15], v[14:15], v[20:21]
	s_nop 0
	v_pk_mul_f32 v[10:11], v[14:15], v[10:11]
	v_add_f32_e32 v1, 1.0, v1
	v_rcp_f32_e32 v14, v1
	v_mul_f32_e32 v1, 0xbfb8aa3b, v17
	v_exp_f32_e32 v1, v1
	s_nop 0
	v_add_f32_e32 v1, 1.0, v1
	v_rcp_f32_e32 v15, v1
	v_mul_f32_e32 v1, 0xbfb8aa3b, v6
	v_exp_f32_e32 v1, v1
	v_pk_mul_f32 v[14:15], v[16:17], v[14:15]
	s_nop 0
	v_pk_mul_f32 v[12:13], v[14:15], v[12:13]
	v_add_f32_e32 v1, 1.0, v1
	v_rcp_f32_e32 v14, v1
	v_mul_f32_e32 v1, 0xbfb8aa3b, v7
	v_exp_f32_e32 v1, v1
	s_nop 0
	v_add_f32_e32 v1, 1.0, v1
	v_rcp_f32_e32 v15, v1
	v_mul_f32_e32 v1, 0xbfb8aa3b, v8
	v_exp_f32_e32 v1, v1
	v_pk_mul_f32 v[6:7], v[6:7], v[14:15]
	s_nop 0
	v_pk_mul_f32 v[6:7], v[6:7], v[2:3]
	v_add_f32_e32 v1, 1.0, v1
	v_rcp_f32_e32 v2, v1
	v_mul_f32_e32 v1, 0xbfb8aa3b, v9
	v_exp_f32_e32 v1, v1
	v_lshl_add_u64 v[14:15], v[18:19], 0, v[114:115]
	v_add_f32_e32 v1, 1.0, v1
	v_rcp_f32_e32 v3, v1
	s_nop 0
	v_pk_mul_f32 v[2:3], v[8:9], v[2:3]
	s_nop 0
	v_pk_mul_f32 v[8:9], v[2:3], v[4:5]
	v_cvt_pk_bf16_f32 v2, v10, v11
	v_cvt_pk_bf16_f32 v3, v12, v13
	v_cvt_pk_bf16_f32 v4, v6, v7
	v_cvt_pk_bf16_f32 v5, v8, v9
	global_store_dwordx4 v[14:15], v[2:5], off nt
	s_cbranch_vccz .LBB0_1136
	s_waitcnt vmcnt(0)
	s_cmpk_gt_u32 s1, 0xff
	s_cbranch_scc1 .LBB0_1144
	s_barrier

; #define PG8_STAGE(bufoff, gbase, voff) do { _Pragma("unroll") for (int _i = 0; _i < 2; ++_i) \
;         __builtin_amdgcn_global_load_lds((const unsigned*)((const char*)(gbase) + (voff)[_i]), (LAS unsigned*)(lds + (bufoff) + ldsw + _i * 8192), 16, 0, 0); } while (0)
; #define PG8_LDA(dst, b, h) do { _Pragma("unroll") for (int m = 0; m < 4; ++m) _Pragma("unroll") for (int k = 0; k < 2; ++k) dst[m][k] = *(const LAS bf16x8*)(lds + PG8_SA(b, h) + aoff + m * 2048 + k * 1024); } while (0)
; #define PG8_WAIT_V(n) asm volatile("s_waitcnt vmcnt(" #n ")" ::: "memory")
; template <class Epi, class Sched>
; __device__ __forceinline__ void gemm_phase(LAS unsigned char* lds, const Gemm g, const Sched& S, const Epi& E) {
;     ...
;         for (int t = 0; t < ntu; t += 2) {
;             const bool last = (t == ntu - 2);
;             const char* a1 = cA + (size_t)(t + 1) * kstep;
;             const char* a2 = last ? nA : cA + (size_t)(t + 2) * kstep; const char* b2 = last ? nB : cB + (size_t)(t + 2) * kstep;
;             const char* a3 = a2 + kstep; const char* b3 = b2 + kstep;
;             if (last && has_next) S.a_ready(nxt);
;             PG8_LDB(B0, 0, 0); PG8_SCHED; PG8_LDA(At, 0, 0); PG8_STAGE(PG8_SA(1, 1), a1 + hstepA, voffA);
;             PG8_WAIT_L(8); PG8_BAR; PG8_WAIT_L(0); PG8_MMA(0, 0, At, B0); PG8_BAR; PG8_SCHED;
;             PG8_LDB(B1, 0, 1); PG8_STAGE(PG8_SB(0, 0), b2, voffB);
;             PG8_BAR; PG8_WAIT_L(0); PG8_MMA(0, 1, At, B1); PG8_BAR;
;             PG8_LDA(At, 0, 1); PG8_STAGE(PG8_SA(0, 0), a2, voffA);
;             PG8_BAR; PG8_WAIT_L(0); PG8_MMA(1, 0, At, B0); PG8_BAR; PG8_SCHED;
;             PG8_STAGE(PG8_SB(0, 1), b2 + hstepB, voffB);
;             PG8_WAIT_V(6); PG8_BAR; PG8_MMA(1, 1, At, B1); PG8_BAR;
;             PG8_LDB(B0, 1, 0); PG8_SCHED; PG8_LDA(At, 1, 0); PG8_STAGE(PG8_SA(0, 1), a2 + hstepA, voffA);
;             PG8_WAIT_L(8); PG8_BAR; PG8_WAIT_L(0); PG8_MMA(0, 0, At, B0); PG8_BAR; PG8_SCHED;
;             PG8_LDB(B1, 1, 1); PG8_STAGE(PG8_SB(1, 0), b3, voffB);
;             PG8_BAR; PG8_WAIT_L(0); PG8_MMA(0, 1, At, B1); PG8_BAR;
;             PG8_LDA(At, 1, 1); PG8_STAGE(PG8_SA(1, 0), a3, voffA);
;             PG8_BAR; PG8_WAIT_L(0); PG8_MMA(1, 0, At, B0); PG8_BAR; PG8_SCHED;
;             PG8_STAGE(PG8_SB(1, 1), b3 + hstepB, voffB);
;             PG8_WAIT_V(6); PG8_BAR; PG8_MMA(1, 1, At, B1); PG8_BAR;
.LBB0_1238:
	s_add_i32 s72, s26, 2
	s_add_u32 s24, s22, 0x100
	s_addc_u32 s25, s23, 0
	s_add_i32 s35, 0, 0x10000
	v_add_u32_e32 v1, s35, v141
	ds_read_b128 v[144:147], v1
	ds_read_b128 v[148:151], v1 offset:1024
	ds_read_b128 v[152:155], v1 offset:2048
	ds_read_b128 v[156:159], v1 offset:3072
	s_cmp_eq_u32 s69, s26
	s_cselect_b32 s26, s16, s70
	s_cselect_b32 s29, s13, s25
	s_cselect_b32 s28, s12, s24
	s_cselect_b32 s27, s17, s71
	ds_read_b128 v[160:163], v143
	ds_read_b128 v[164:167], v143 offset:1024
	ds_read_b128 v[168:171], v143 offset:2048
	ds_read_b128 v[172:175], v143 offset:3072
	ds_read_b128 v[182:185], v143 offset:4096
	ds_read_b128 v[186:189], v143 offset:5120
	ds_read_b128 v[190:193], v143 offset:6144
	ds_read_b128 v[194:197], v143 offset:7168
	s_add_u32 s98, s22, 0xffea0000
	s_addc_u32 s99, s23, -1
	s_mov_b32 m0, s56
	s_nop 0
	global_load_lds_dwordx4 v136, s[98:99]
	s_mov_b32 m0, s57
	s_nop 0
	global_load_lds_dwordx4 v138, s[98:99]
	s_add_i32 m0, s52, 0xc000
	s_nop 0
	global_load_lds_dwordx4 v136, s[22:23]
	s_add_i32 m0, s52, 0xe000
	s_nop 0
	global_load_lds_dwordx4 v138, s[22:23]
	s_add_i32 s76, 0, 0x14000
	v_add_u32_e32 v1, s76, v141
	ds_read_b128 v[198:201], v1
	ds_read_b128 v[202:205], v1 offset:1024
	ds_read_b128 v[206:209], v1 offset:2048
	ds_read_b128 v[210:213], v1 offset:3072
	s_waitcnt lgkmcnt(0)
	s_barrier
	v_mfma_f32_16x16x32_bf16 v[126:129], v[144:147], v[160:163], v[126:129]
	v_mfma_f32_16x16x32_bf16 v[126:129], v[148:151], v[164:167], v[126:129]
	v_mfma_f32_16x16x32_bf16 v[110:113], v[144:147], v[168:171], v[110:113]
	v_mfma_f32_16x16x32_bf16 v[110:113], v[148:151], v[172:175], v[110:113]
	v_mfma_f32_16x16x32_bf16 v[94:97], v[144:147], v[182:185], v[94:97]
	v_mfma_f32_16x16x32_bf16 v[94:97], v[148:151], v[186:189], v[94:97]
	v_mfma_f32_16x16x32_bf16 v[78:81], v[144:147], v[190:193], v[78:81]
	v_mfma_f32_16x16x32_bf16 v[78:81], v[148:151], v[194:197], v[78:81]
	v_mfma_f32_16x16x32_bf16 v[122:125], v[152:155], v[160:163], v[122:125]
	v_mfma_f32_16x16x32_bf16 v[122:125], v[156:159], v[164:167], v[122:125]
	v_mfma_f32_16x16x32_bf16 v[106:109], v[152:155], v[168:171], v[106:109]
	v_mfma_f32_16x16x32_bf16 v[106:109], v[156:159], v[172:175], v[106:109]
	v_mfma_f32_16x16x32_bf16 v[90:93], v[152:155], v[182:185], v[90:93]
	v_mfma_f32_16x16x32_bf16 v[90:93], v[156:159], v[186:189], v[90:93]
	v_mfma_f32_16x16x32_bf16 v[74:77], v[152:155], v[190:193], v[74:77]
	v_mfma_f32_16x16x32_bf16 v[74:77], v[156:159], v[194:197], v[74:77]
	v_mfma_f32_16x16x32_bf16 v[118:121], v[198:201], v[160:163], v[118:121]
	v_mfma_f32_16x16x32_bf16 v[118:121], v[202:205], v[164:167], v[118:121]
	v_mfma_f32_16x16x32_bf16 v[102:105], v[198:201], v[168:171], v[102:105]
	v_mfma_f32_16x16x32_bf16 v[102:105], v[202:205], v[172:175], v[102:105]
	v_mfma_f32_16x16x32_bf16 v[86:89], v[198:201], v[182:185], v[86:89]
	v_mfma_f32_16x16x32_bf16 v[86:89], v[202:205], v[186:189], v[86:89]
	v_mfma_f32_16x16x32_bf16 v[70:73], v[198:201], v[190:193], v[70:73]
	v_mfma_f32_16x16x32_bf16 v[70:73], v[202:205], v[194:197], v[70:73]
	v_mfma_f32_16x16x32_bf16 v[114:117], v[206:209], v[160:163], v[114:117]
	v_mfma_f32_16x16x32_bf16 v[114:117], v[210:213], v[164:167], v[114:117]
	v_mfma_f32_16x16x32_bf16 v[98:101], v[206:209], v[168:171], v[98:101]
	v_mfma_f32_16x16x32_bf16 v[98:101], v[210:213], v[172:175], v[98:101]
	v_mfma_f32_16x16x32_bf16 v[82:85], v[206:209], v[182:185], v[82:85]
	v_mfma_f32_16x16x32_bf16 v[82:85], v[210:213], v[186:189], v[82:85]
	v_mfma_f32_16x16x32_bf16 v[66:69], v[206:209], v[190:193], v[66:69]
	v_mfma_f32_16x16x32_bf16 v[66:69], v[210:213], v[194:197], v[66:69]
	s_barrier
	ds_read_b128 v[160:163], v143 offset:16384
	ds_read_b128 v[164:167], v143 offset:17408
	ds_read_b128 v[168:171], v143 offset:18432
	ds_read_b128 v[172:175], v143 offset:19456
	ds_read_b128 v[182:185], v143 offset:20480
	ds_read_b128 v[186:189], v143 offset:21504
	ds_read_b128 v[190:193], v143 offset:22528
	ds_read_b128 v[194:197], v143 offset:23552
	s_add_i32 s22, s35, s50
	s_mov_b32 m0, s22
	s_nop 0
	global_load_lds_dwordx4 v178, s[26:27]
	s_add_i32 m0, s22, 0x2000
	s_nop 0
	global_load_lds_dwordx4 v134, s[26:27]
	s_add_u32 s22, s26, 0x160000
	s_addc_u32 s23, s27, 0
	s_add_i32 s35, s76, s50
	s_mov_b32 m0, s35
	s_nop 0
	global_load_lds_dwordx4 v178, s[22:23]
	s_add_i32 m0, s35, 0x2000
	s_nop 0
	global_load_lds_dwordx4 v134, s[22:23]
	s_waitcnt vmcnt(4)
	s_waitcnt lgkmcnt(0)
	s_barrier
	v_mfma_f32_16x16x32_bf16 v[62:65], v[144:147], v[160:163], v[62:65]
	v_mfma_f32_16x16x32_bf16 v[62:65], v[148:151], v[164:167], v[62:65]
	v_mfma_f32_16x16x32_bf16 v[46:49], v[144:147], v[168:171], v[46:49]
	v_mfma_f32_16x16x32_bf16 v[46:49], v[148:151], v[172:175], v[46:49]
	v_mfma_f32_16x16x32_bf16 v[30:33], v[144:147], v[182:185], v[30:33]
	v_mfma_f32_16x16x32_bf16 v[30:33], v[148:151], v[186:189], v[30:33]
	v_mfma_f32_16x16x32_bf16 v[14:17], v[144:147], v[190:193], v[14:17]
	v_mfma_f32_16x16x32_bf16 v[14:17], v[148:151], v[194:197], v[14:17]
	v_mfma_f32_16x16x32_bf16 v[58:61], v[152:155], v[160:163], v[58:61]
	v_mfma_f32_16x16x32_bf16 v[58:61], v[156:159], v[164:167], v[58:61]
	v_mfma_f32_16x16x32_bf16 v[42:45], v[152:155], v[168:171], v[42:45]
	v_mfma_f32_16x16x32_bf16 v[42:45], v[156:159], v[172:175], v[42:45]
	v_mfma_f32_16x16x32_bf16 v[26:29], v[152:155], v[182:185], v[26:29]
	v_mfma_f32_16x16x32_bf16 v[26:29], v[156:159], v[186:189], v[26:29]
	v_mfma_f32_16x16x32_bf16 v[10:13], v[152:155], v[190:193], v[10:13]
	v_mfma_f32_16x16x32_bf16 v[10:13], v[156:159], v[194:197], v[10:13]
	v_mfma_f32_16x16x32_bf16 v[54:57], v[198:201], v[160:163], v[54:57]
	v_mfma_f32_16x16x32_bf16 v[54:57], v[202:205], v[164:167], v[54:57]
	v_mfma_f32_16x16x32_bf16 v[38:41], v[198:201], v[168:171], v[38:41]
	v_mfma_f32_16x16x32_bf16 v[38:41], v[202:205], v[172:175], v[38:41]
	v_mfma_f32_16x16x32_bf16 v[22:25], v[198:201], v[182:185], v[22:25]
	v_mfma_f32_16x16x32_bf16 v[22:25], v[202:205], v[186:189], v[22:25]
	v_mfma_f32_16x16x32_bf16 v[6:9], v[198:201], v[190:193], v[6:9]
	v_mfma_f32_16x16x32_bf16 v[6:9], v[202:205], v[194:197], v[6:9]
	v_mfma_f32_16x16x32_bf16 v[50:53], v[206:209], v[160:163], v[50:53]
	v_mfma_f32_16x16x32_bf16 v[50:53], v[210:213], v[164:167], v[50:53]
	v_mfma_f32_16x16x32_bf16 v[34:37], v[206:209], v[168:171], v[34:37]
	v_mfma_f32_16x16x32_bf16 v[34:37], v[210:213], v[172:175], v[34:37]
	v_mfma_f32_16x16x32_bf16 v[18:21], v[206:209], v[182:185], v[18:21]
	v_mfma_f32_16x16x32_bf16 v[18:21], v[210:213], v[186:189], v[18:21]
	v_mfma_f32_16x16x32_bf16 v[2:5], v[206:209], v[190:193], v[2:5]
	v_mfma_f32_16x16x32_bf16 v[2:5], v[210:213], v[194:197], v[2:5]
	s_add_i32 s35, 0, 0x18000
	v_add_u32_e32 v1, s35, v141
	s_barrier
; #define PG8_STAGE(bufoff, gbase, voff) do { _Pragma("unroll") for (int _i = 0; _i < 2; ++_i) \
;         __builtin_amdgcn_global_load_lds((const unsigned*)((const char*)(gbase) + (voff)[_i]), (LAS unsigned*)(lds + (bufoff) + ldsw + _i * 8192), 16, 0, 0); } while (0)
; #define PG8_LDA(dst, b, h) do { _Pragma("unroll") for (int m = 0; m < 4; ++m) _Pragma("unroll") for (int k = 0; k < 2; ++k) dst[m][k] = *(const LAS bf16x8*)(lds + PG8_SA(b, h) + aoff + m * 2048 + k * 1024); } while (0)
; #define PG8_LDB(dst, b, h) do { _Pragma("unroll") for (int n = 0; n < 2; ++n) _Pragma("unroll") for (int k = 0; k < 2; ++k) dst[n][k] = *(const LAS bf16x8*)(lds + PG8_SB(b, h) + boff + n * 2048 + k * 1024); } while (0)
; #define PG8_WAIT_V(n) asm volatile("s_waitcnt vmcnt(" #n ")" ::: "memory")
; #define PG8_WAIT_L(n) asm volatile("s_waitcnt lgkmcnt(" #n ")" ::: "memory")
; #define PG8_BAR __builtin_amdgcn_s_barrier()
; #define PG8_SCHED __builtin_amdgcn_sched_barrier(0)
; template <class Epi, class Sched>
; __device__ __forceinline__ void gemm_phase(LAS unsigned char* lds, const Gemm g, const Sched& S, const Epi& E) {
;     ...
;             PG8_LDB(B0, 0, 0); PG8_SCHED; PG8_LDA(At, 0, 0); PG8_STAGE(PG8_SA(1, 1), a1 + hstepA, voffA);
;             PG8_WAIT_L(8); PG8_BAR; PG8_WAIT_L(0); PG8_MMA(0, 0, At, B0); PG8_BAR; PG8_SCHED;
;             PG8_LDB(B1, 0, 1); PG8_STAGE(PG8_SB(0, 0), b2, voffB);
;             PG8_BAR; PG8_WAIT_L(0); PG8_MMA(0, 1, At, B1); PG8_BAR;
;             PG8_LDA(At, 0, 1); PG8_STAGE(PG8_SA(0, 0), a2, voffA);
;             PG8_BAR; PG8_WAIT_L(0); PG8_MMA(1, 0, At, B0); PG8_BAR; PG8_SCHED;
;             PG8_STAGE(PG8_SB(0, 1), b2 + hstepB, voffB);
;             PG8_WAIT_V(6); PG8_BAR; PG8_MMA(1, 1, At, B1); PG8_BAR;
;             PG8_LDB(B0, 1, 0); PG8_SCHED; PG8_LDA(At, 1, 0); PG8_STAGE(PG8_SA(0, 1), a2 + hstepA, voffA);
;             PG8_WAIT_L(8); PG8_BAR; PG8_WAIT_L(0); PG8_MMA(0, 0, At, B0); PG8_BAR; PG8_SCHED;
;             PG8_LDB(B1, 1, 1); PG8_STAGE(PG8_SB(1, 0), b3, voffB);
;             PG8_BAR; PG8_WAIT_L(0); PG8_MMA(0, 1, At, B1); PG8_BAR;
;             PG8_LDA(At, 1, 1); PG8_STAGE(PG8_SA(1, 0), a3, voffA);
;             PG8_BAR; PG8_WAIT_L(0); PG8_MMA(1, 0, At, B0); PG8_BAR; PG8_SCHED;
;             PG8_STAGE(PG8_SB(1, 1), b3 + hstepB, voffB);
;             PG8_WAIT_V(6); PG8_BAR; PG8_MMA(1, 1, At, B1); PG8_BAR;
;         }
	ds_read_b128 v[144:147], v1
	ds_read_b128 v[148:151], v1 offset:1024
	ds_read_b128 v[152:155], v1 offset:2048
	ds_read_b128 v[156:159], v1 offset:3072
	ds_read_b128 v[160:163], v143 offset:32768
	ds_read_b128 v[164:167], v143 offset:33792
	ds_read_b128 v[168:171], v143 offset:34816
	ds_read_b128 v[172:175], v143 offset:35840
	ds_read_b128 v[182:185], v143 offset:36864
	ds_read_b128 v[186:189], v143 offset:37888
	ds_read_b128 v[190:193], v143 offset:38912
	ds_read_b128 v[194:197], v143 offset:39936
	s_mov_b32 m0, s52
	s_nop 0
	global_load_lds_dwordx4 v130, s[28:29]
	s_mov_b32 m0, s53
	s_nop 0
	global_load_lds_dwordx4 v132, s[28:29]
	s_add_u32 s22, s28, 0x160000
	s_addc_u32 s23, s29, 0
	s_mov_b32 m0, s54
	s_nop 0
	global_load_lds_dwordx4 v130, s[22:23]
	s_mov_b32 m0, s55
	s_nop 0
	global_load_lds_dwordx4 v132, s[22:23]
	s_add_i32 s28, 0, 0x1c000
	v_add_u32_e32 v1, s28, v141
	ds_read_b128 v[198:201], v1
	ds_read_b128 v[202:205], v1 offset:1024
	ds_read_b128 v[206:209], v1 offset:2048
	ds_read_b128 v[210:213], v1 offset:3072
	s_waitcnt lgkmcnt(0)
	s_barrier
	v_mfma_f32_16x16x32_bf16 v[126:129], v[144:147], v[160:163], v[126:129]
	v_mfma_f32_16x16x32_bf16 v[126:129], v[148:151], v[164:167], v[126:129]
	v_mfma_f32_16x16x32_bf16 v[110:113], v[144:147], v[168:171], v[110:113]
	v_mfma_f32_16x16x32_bf16 v[110:113], v[148:151], v[172:175], v[110:113]
	v_mfma_f32_16x16x32_bf16 v[94:97], v[144:147], v[182:185], v[94:97]
	v_mfma_f32_16x16x32_bf16 v[94:97], v[148:151], v[186:189], v[94:97]
	v_mfma_f32_16x16x32_bf16 v[78:81], v[144:147], v[190:193], v[78:81]
	v_mfma_f32_16x16x32_bf16 v[78:81], v[148:151], v[194:197], v[78:81]
	v_mfma_f32_16x16x32_bf16 v[122:125], v[152:155], v[160:163], v[122:125]
	v_mfma_f32_16x16x32_bf16 v[122:125], v[156:159], v[164:167], v[122:125]
	v_mfma_f32_16x16x32_bf16 v[106:109], v[152:155], v[168:171], v[106:109]
	v_mfma_f32_16x16x32_bf16 v[106:109], v[156:159], v[172:175], v[106:109]
	v_mfma_f32_16x16x32_bf16 v[90:93], v[152:155], v[182:185], v[90:93]
	v_mfma_f32_16x16x32_bf16 v[90:93], v[156:159], v[186:189], v[90:93]
	v_mfma_f32_16x16x32_bf16 v[74:77], v[152:155], v[190:193], v[74:77]
	v_mfma_f32_16x16x32_bf16 v[74:77], v[156:159], v[194:197], v[74:77]
	v_mfma_f32_16x16x32_bf16 v[118:121], v[198:201], v[160:163], v[118:121]
	v_mfma_f32_16x16x32_bf16 v[118:121], v[202:205], v[164:167], v[118:121]
	v_mfma_f32_16x16x32_bf16 v[102:105], v[198:201], v[168:171], v[102:105]
	v_mfma_f32_16x16x32_bf16 v[102:105], v[202:205], v[172:175], v[102:105]
	v_mfma_f32_16x16x32_bf16 v[86:89], v[198:201], v[182:185], v[86:89]
	v_mfma_f32_16x16x32_bf16 v[86:89], v[202:205], v[186:189], v[86:89]
	v_mfma_f32_16x16x32_bf16 v[70:73], v[198:201], v[190:193], v[70:73]
	v_mfma_f32_16x16x32_bf16 v[70:73], v[202:205], v[194:197], v[70:73]
	v_mfma_f32_16x16x32_bf16 v[114:117], v[206:209], v[160:163], v[114:117]
	v_mfma_f32_16x16x32_bf16 v[114:117], v[210:213], v[164:167], v[114:117]
	v_mfma_f32_16x16x32_bf16 v[98:101], v[206:209], v[168:171], v[98:101]
	v_mfma_f32_16x16x32_bf16 v[98:101], v[210:213], v[172:175], v[98:101]
	v_mfma_f32_16x16x32_bf16 v[82:85], v[206:209], v[182:185], v[82:85]
	v_mfma_f32_16x16x32_bf16 v[82:85], v[210:213], v[186:189], v[82:85]
	v_mfma_f32_16x16x32_bf16 v[66:69], v[206:209], v[190:193], v[66:69]
	v_mfma_f32_16x16x32_bf16 v[66:69], v[210:213], v[194:197], v[66:69]
	s_barrier
	ds_read_b128 v[160:163], v143 offset:49152
	ds_read_b128 v[164:167], v143 offset:50176
	ds_read_b128 v[168:171], v143 offset:51200
	ds_read_b128 v[172:175], v143 offset:52224
	ds_read_b128 v[182:185], v143 offset:53248
	ds_read_b128 v[186:189], v143 offset:54272
	ds_read_b128 v[190:193], v143 offset:55296
	ds_read_b128 v[194:197], v143 offset:56320
	s_add_u32 s98, s26, 0x80
	s_addc_u32 s99, s27, 0
	s_add_i32 s22, s35, s50
	s_mov_b32 m0, s22
	s_nop 0
	global_load_lds_dwordx4 v178, s[98:99]
	s_add_i32 m0, s22, 0x2000
	s_nop 0
	global_load_lds_dwordx4 v134, s[98:99]
	s_add_u32 s22, s26, 0x160080
	s_addc_u32 s23, s27, 0
	s_add_i32 s26, s28, s50
	s_mov_b32 m0, s26
	s_nop 0
	global_load_lds_dwordx4 v178, s[22:23]
	s_add_i32 m0, s26, 0x2000
	s_nop 0
	global_load_lds_dwordx4 v134, s[22:23]
	s_waitcnt vmcnt(4)
	s_waitcnt lgkmcnt(0)
	s_barrier
	v_mfma_f32_16x16x32_bf16 v[62:65], v[144:147], v[160:163], v[62:65]
	v_mfma_f32_16x16x32_bf16 v[62:65], v[148:151], v[164:167], v[62:65]
	v_mfma_f32_16x16x32_bf16 v[46:49], v[144:147], v[168:171], v[46:49]
	v_mfma_f32_16x16x32_bf16 v[46:49], v[148:151], v[172:175], v[46:49]
	v_mfma_f32_16x16x32_bf16 v[30:33], v[144:147], v[182:185], v[30:33]
	v_mfma_f32_16x16x32_bf16 v[30:33], v[148:151], v[186:189], v[30:33]
	v_mfma_f32_16x16x32_bf16 v[14:17], v[144:147], v[190:193], v[14:17]
	v_mfma_f32_16x16x32_bf16 v[14:17], v[148:151], v[194:197], v[14:17]
	v_mfma_f32_16x16x32_bf16 v[58:61], v[152:155], v[160:163], v[58:61]
	v_mfma_f32_16x16x32_bf16 v[58:61], v[156:159], v[164:167], v[58:61]
	v_mfma_f32_16x16x32_bf16 v[42:45], v[152:155], v[168:171], v[42:45]
	v_mfma_f32_16x16x32_bf16 v[42:45], v[156:159], v[172:175], v[42:45]
	v_mfma_f32_16x16x32_bf16 v[26:29], v[152:155], v[182:185], v[26:29]
	v_mfma_f32_16x16x32_bf16 v[26:29], v[156:159], v[186:189], v[26:29]
	v_mfma_f32_16x16x32_bf16 v[10:13], v[152:155], v[190:193], v[10:13]
	v_mfma_f32_16x16x32_bf16 v[10:13], v[156:159], v[194:197], v[10:13]
	v_mfma_f32_16x16x32_bf16 v[54:57], v[198:201], v[160:163], v[54:57]
	v_mfma_f32_16x16x32_bf16 v[54:57], v[202:205], v[164:167], v[54:57]
	v_mfma_f32_16x16x32_bf16 v[38:41], v[198:201], v[168:171], v[38:41]
	v_mfma_f32_16x16x32_bf16 v[38:41], v[202:205], v[172:175], v[38:41]
	v_mfma_f32_16x16x32_bf16 v[22:25], v[198:201], v[182:185], v[22:25]
	v_mfma_f32_16x16x32_bf16 v[22:25], v[202:205], v[186:189], v[22:25]
	v_mfma_f32_16x16x32_bf16 v[6:9], v[198:201], v[190:193], v[6:9]
	v_mfma_f32_16x16x32_bf16 v[6:9], v[202:205], v[194:197], v[6:9]
	v_mfma_f32_16x16x32_bf16 v[50:53], v[206:209], v[160:163], v[50:53]
	v_mfma_f32_16x16x32_bf16 v[50:53], v[210:213], v[164:167], v[50:53]
	v_mfma_f32_16x16x32_bf16 v[34:37], v[206:209], v[168:171], v[34:37]
	v_mfma_f32_16x16x32_bf16 v[34:37], v[210:213], v[172:175], v[34:37]
	v_mfma_f32_16x16x32_bf16 v[18:21], v[206:209], v[182:185], v[18:21]
	v_mfma_f32_16x16x32_bf16 v[18:21], v[210:213], v[186:189], v[18:21]
	v_mfma_f32_16x16x32_bf16 v[2:5], v[206:209], v[190:193], v[2:5]
	v_mfma_f32_16x16x32_bf16 v[2:5], v[210:213], v[194:197], v[2:5]
	s_add_u32 s70, s70, 0x100
	s_addc_u32 s71, s71, 0
	s_cmp_ge_i32 s72, s68
	s_mov_b64 s[22:23], s[24:25]
	s_mov_b32 s26, s72
	s_barrier
	s_cbranch_scc0 .LBB0_1238
	v_readlane_b32 s76, v255, 26
	v_readlane_b32 s77, v255, 27
	s_branch .LBB0_1241
